# SwiGLU-type epilogues: 4 v_mov + v_pk_mul_f32 swizzle replaced by 2 v_mul_f32 (32 sites, bit-identical products)
# baseline (speedup 1.0000x reference)
; #define PG8_STAGE(bufoff, gbase, voff) do { _Pragma("unroll") for (int _i = 0; _i < 2; ++_i) \
;         __builtin_amdgcn_global_load_lds((const unsigned*)((const char*)(gbase) + (voff)[_i]), (PG8_LAS unsigned*)(lds + (bufoff) + ldsw + _i * 8192), 16, 0, 0); } while (0)
; #define PG8_LDA(dst, b, h) do { _Pragma("unroll") for (int m = 0; m < 4; ++m) _Pragma("unroll") for (int k = 0; k < 2; ++k) dst[m][k] = *(const PG8_LAS bf16x8*)(lds + PG8_SA(b, h) + aoff + m * 2048 + k * 1024); } while (0)
; #define PG8_LDB(dst, b, h) do { _Pragma("unroll") for (int n = 0; n < 2; ++n) _Pragma("unroll") for (int k = 0; k < 2; ++k) dst[n][k] = *(const PG8_LAS bf16x8*)(lds + PG8_SB(b, h) + boff + n * 2048 + k * 1024); } while (0)
; #define PG8_MMA(ai, bj, At, Bt) do { __builtin_amdgcn_s_setprio(1); _Pragma("unroll") for (int m = 0; m < 4; ++m) _Pragma("unroll") for (int n = 0; n < 2; ++n) _Pragma("unroll") for (int k = 0; k < 2; ++k) \
;         acc[ai][bj][m][n] = __builtin_amdgcn_mfma_f32_16x16x32_bf16(Bt[n][k], At[m][k], acc[ai][bj][m][n], 0, 0, 0); __builtin_amdgcn_s_setprio(0); } while (0)
; #define PG8_WAIT_V(n) asm volatile("s_waitcnt vmcnt(" #n ")" ::: "memory")
; template <class Epi, class Sched>
; __device__ __forceinline__ void gemm_phase(PG8_LAS unsigned char* lds, const Gemm g, const Sched& S, const Epi& E) {
;     ...
;         for (int t = 0; t < nt; t += 2) {
;             const bool last = (t == nt - 2);
;             const char* a1 = cA + (size_t)(t + 1) * kstep;
;             const char* a2 = last ? nA : cA + (size_t)(t + 2) * kstep; const char* b2 = last ? nB : cB + (size_t)(t + 2) * kstep;
;             const char* a3 = a2 + kstep; const char* b3 = b2 + kstep;
;             if (last && has_next) S.a_ready(nxt);
;             PG8_LDB(B0, 0, 0); PG8_SCHED; PG8_LDA(At, 0, 0); PG8_STAGE(PG8_SA(1, 1), a1 + hstep, voffA);
;             PG8_WAIT_L(8); PG8_BAR; PG8_WAIT_L(0); PG8_MMA(0, 0, At, B0); PG8_BAR; PG8_SCHED;
;             PG8_LDB(B1, 0, 1); PG8_STAGE(PG8_SB(0, 0), b2, voffB);
;             PG8_BAR; PG8_WAIT_L(0); PG8_MMA(0, 1, At, B1); PG8_BAR;
;             PG8_LDA(At, 0, 1); PG8_STAGE(PG8_SA(0, 0), a2, voffA);
;             PG8_BAR; PG8_WAIT_L(0); PG8_MMA(1, 0, At, B0); PG8_BAR; PG8_SCHED;
;             PG8_STAGE(PG8_SB(0, 1), b2 + hstep, voffB);
;             PG8_WAIT_V(6); PG8_BAR; PG8_MMA(1, 1, At, B1); PG8_BAR;
.LBB0_195:
	ds_read_b128 v[144:147], v151
	ds_read_b128 v[156:159], v151 offset:1024
	ds_read_b128 v[160:163], v151 offset:2048
	ds_read_b128 v[166:169], v151 offset:3072
	s_add_u32 s30, s28, 0xfffc0080
	s_addc_u32 s31, s29, -1
	s_cmp_eq_u32 s58, 12
	s_cselect_b32 s35, s17, s31
	s_cselect_b32 s34, s54, s30
	s_cselect_b32 s31, s15, s57
	s_cselect_b32 s30, s55, s56
	s_add_i32 m0, s27, 0xc000
	ds_read_b128 v[170:173], v153
	ds_read_b128 v[182:185], v153 offset:1024
	ds_read_b128 v[190:193], v153 offset:2048
	ds_read_b128 v[194:197], v153 offset:3072
	ds_read_b128 v[198:201], v153 offset:4096
	ds_read_b128 v[202:205], v153 offset:5120
	ds_read_b128 v[206:209], v153 offset:6144
	ds_read_b128 v[210:213], v153 offset:7168
	global_load_lds_dwordx4 v136, s[28:29]
	s_nop 1
	s_add_i32 m0, s27, 0xe000
	s_nop 0
	global_load_lds_dwordx4 v138, s[28:29]
	s_waitcnt lgkmcnt(8)
	ds_read_b128 v[214:217], v154
	ds_read_b128 v[218:221], v154 offset:1024
	ds_read_b128 v[222:225], v154 offset:2048
	ds_read_b128 v[226:229], v154 offset:3072
	s_waitcnt vmcnt(8) lgkmcnt(0)
	s_barrier
	v_mfma_f32_16x16x32_bf16 v[124:127], v[144:147], v[170:173], v[124:127]
	v_mfma_f32_16x16x32_bf16 v[120:123], v[160:163], v[170:173], v[120:123]
	v_mfma_f32_16x16x32_bf16 v[108:111], v[144:147], v[190:193], v[108:111]
	v_mfma_f32_16x16x32_bf16 v[104:107], v[160:163], v[190:193], v[104:107]
	v_mfma_f32_16x16x32_bf16 v[92:95], v[144:147], v[198:201], v[92:95]
	v_mfma_f32_16x16x32_bf16 v[88:91], v[160:163], v[198:201], v[88:91]
	v_mfma_f32_16x16x32_bf16 v[76:79], v[144:147], v[206:209], v[76:79]
	v_mfma_f32_16x16x32_bf16 v[72:75], v[160:163], v[206:209], v[72:75]
	v_mfma_f32_16x16x32_bf16 v[124:127], v[156:159], v[182:185], v[124:127]
	v_mfma_f32_16x16x32_bf16 v[120:123], v[166:169], v[182:185], v[120:123]
	v_mfma_f32_16x16x32_bf16 v[108:111], v[156:159], v[194:197], v[108:111]
	v_mfma_f32_16x16x32_bf16 v[104:107], v[166:169], v[194:197], v[104:107]
	v_mfma_f32_16x16x32_bf16 v[92:95], v[156:159], v[202:205], v[92:95]
	v_mfma_f32_16x16x32_bf16 v[88:91], v[166:169], v[202:205], v[88:91]
	v_mfma_f32_16x16x32_bf16 v[76:79], v[156:159], v[210:213], v[76:79]
	v_mfma_f32_16x16x32_bf16 v[72:75], v[166:169], v[210:213], v[72:75]
	v_mfma_f32_16x16x32_bf16 v[116:119], v[214:217], v[170:173], v[116:119]
	v_mfma_f32_16x16x32_bf16 v[112:115], v[222:225], v[170:173], v[112:115]
	v_mfma_f32_16x16x32_bf16 v[100:103], v[214:217], v[190:193], v[100:103]
	v_mfma_f32_16x16x32_bf16 v[96:99], v[222:225], v[190:193], v[96:99]
	v_mfma_f32_16x16x32_bf16 v[84:87], v[214:217], v[198:201], v[84:87]
	v_mfma_f32_16x16x32_bf16 v[80:83], v[222:225], v[198:201], v[80:83]
	v_mfma_f32_16x16x32_bf16 v[68:71], v[214:217], v[206:209], v[68:71]
	v_mfma_f32_16x16x32_bf16 v[64:67], v[222:225], v[206:209], v[64:67]
	v_mfma_f32_16x16x32_bf16 v[116:119], v[218:221], v[182:185], v[116:119]
	v_mfma_f32_16x16x32_bf16 v[112:115], v[226:229], v[182:185], v[112:115]
	v_mfma_f32_16x16x32_bf16 v[100:103], v[218:221], v[194:197], v[100:103]
	v_mfma_f32_16x16x32_bf16 v[96:99], v[226:229], v[194:197], v[96:99]
	v_mfma_f32_16x16x32_bf16 v[84:87], v[218:221], v[202:205], v[84:87]
	v_mfma_f32_16x16x32_bf16 v[80:83], v[226:229], v[202:205], v[80:83]
	v_mfma_f32_16x16x32_bf16 v[68:71], v[218:221], v[210:213], v[68:71]
	v_mfma_f32_16x16x32_bf16 v[64:67], v[226:229], v[210:213], v[64:67]
	s_barrier
	ds_read_b128 v[170:173], v153 offset:16384
	ds_read_b128 v[182:185], v153 offset:17408
	ds_read_b128 v[190:193], v153 offset:18432
	ds_read_b128 v[194:197], v153 offset:19456
	ds_read_b128 v[198:201], v153 offset:20480
	ds_read_b128 v[202:205], v153 offset:21504
	ds_read_b128 v[206:209], v153 offset:22528
	ds_read_b128 v[210:213], v153 offset:23552
	s_add_i32 s59, s50, s40
	s_add_u32 s98, s30, s10
	s_addc_u32 s99, s31, s11
	s_mov_b32 m0, s59
	s_nop 0
	global_load_lds_dwordx4 v132, s[30:31]
	s_nop 1
	s_add_i32 m0, s59, 0x2000
	s_nop 0
	global_load_lds_dwordx4 v128, s[30:31]
	s_nop 1
	s_mov_b32 m0, s27
	s_add_u32 s100, s34, s10
	s_addc_u32 s101, s35, s11
	global_load_lds_dwordx4 v134, s[34:35]
	s_nop 1
	s_mov_b32 m0, s43
	s_nop 0
	global_load_lds_dwordx4 v130, s[34:35]
	s_add_u32 s60, s30, 0x40000
	s_addc_u32 s61, s31, 0
	s_add_i32 s59, s51, s40
	s_mov_b32 m0, s59
	s_nop 0
	global_load_lds_dwordx4 v132, s[60:61]
	s_nop 1
	s_add_i32 m0, s59, 0x2000
	s_nop 0
	global_load_lds_dwordx4 v128, s[60:61]
	s_waitcnt vmcnt(8) lgkmcnt(0)
	s_barrier
	v_mfma_f32_16x16x32_bf16 v[60:63], v[144:147], v[170:173], v[60:63]
	v_mfma_f32_16x16x32_bf16 v[56:59], v[160:163], v[170:173], v[56:59]
	v_mfma_f32_16x16x32_bf16 v[44:47], v[144:147], v[190:193], v[44:47]
	v_mfma_f32_16x16x32_bf16 v[40:43], v[160:163], v[190:193], v[40:43]
	v_mfma_f32_16x16x32_bf16 v[28:31], v[144:147], v[198:201], v[28:31]
	v_mfma_f32_16x16x32_bf16 v[24:27], v[160:163], v[198:201], v[24:27]
	v_mfma_f32_16x16x32_bf16 v[12:15], v[144:147], v[206:209], v[12:15]
	v_mfma_f32_16x16x32_bf16 v[8:11], v[160:163], v[206:209], v[8:11]
	v_mfma_f32_16x16x32_bf16 v[60:63], v[156:159], v[182:185], v[60:63]
	v_mfma_f32_16x16x32_bf16 v[56:59], v[166:169], v[182:185], v[56:59]
	v_mfma_f32_16x16x32_bf16 v[44:47], v[156:159], v[194:197], v[44:47]
	v_mfma_f32_16x16x32_bf16 v[40:43], v[166:169], v[194:197], v[40:43]
	v_mfma_f32_16x16x32_bf16 v[28:31], v[156:159], v[202:205], v[28:31]
	v_mfma_f32_16x16x32_bf16 v[24:27], v[166:169], v[202:205], v[24:27]
	v_mfma_f32_16x16x32_bf16 v[12:15], v[156:159], v[210:213], v[12:15]
	v_mfma_f32_16x16x32_bf16 v[8:11], v[166:169], v[210:213], v[8:11]
	v_mfma_f32_16x16x32_bf16 v[52:55], v[214:217], v[170:173], v[52:55]
	v_mfma_f32_16x16x32_bf16 v[48:51], v[222:225], v[170:173], v[48:51]
	v_mfma_f32_16x16x32_bf16 v[36:39], v[214:217], v[190:193], v[36:39]
	v_mfma_f32_16x16x32_bf16 v[32:35], v[222:225], v[190:193], v[32:35]
	v_mfma_f32_16x16x32_bf16 v[20:23], v[214:217], v[198:201], v[20:23]
	v_mfma_f32_16x16x32_bf16 v[16:19], v[222:225], v[198:201], v[16:19]
	v_mfma_f32_16x16x32_bf16 v[4:7], v[214:217], v[206:209], v[4:7]
	v_mfma_f32_16x16x32_bf16 v[0:3], v[222:225], v[206:209], v[0:3]
	v_mfma_f32_16x16x32_bf16 v[52:55], v[218:221], v[182:185], v[52:55]
	v_mfma_f32_16x16x32_bf16 v[48:51], v[226:229], v[182:185], v[48:51]
	v_mfma_f32_16x16x32_bf16 v[36:39], v[218:221], v[194:197], v[36:39]
	v_mfma_f32_16x16x32_bf16 v[32:35], v[226:229], v[194:197], v[32:35]
	v_mfma_f32_16x16x32_bf16 v[20:23], v[218:221], v[202:205], v[20:23]
	v_mfma_f32_16x16x32_bf16 v[16:19], v[226:229], v[202:205], v[16:19]
	v_mfma_f32_16x16x32_bf16 v[4:7], v[218:221], v[210:213], v[4:7]
	v_mfma_f32_16x16x32_bf16 v[0:3], v[226:229], v[210:213], v[0:3]
	s_barrier
; #define PG8_STAGE(bufoff, gbase, voff) do { _Pragma("unroll") for (int _i = 0; _i < 2; ++_i) \
;         __builtin_amdgcn_global_load_lds((const unsigned*)((const char*)(gbase) + (voff)[_i]), (PG8_LAS unsigned*)(lds + (bufoff) + ldsw + _i * 8192), 16, 0, 0); } while (0)
; #define PG8_LDA(dst, b, h) do { _Pragma("unroll") for (int m = 0; m < 4; ++m) _Pragma("unroll") for (int k = 0; k < 2; ++k) dst[m][k] = *(const PG8_LAS bf16x8*)(lds + PG8_SA(b, h) + aoff + m * 2048 + k * 1024); } while (0)
; #define PG8_LDB(dst, b, h) do { _Pragma("unroll") for (int n = 0; n < 2; ++n) _Pragma("unroll") for (int k = 0; k < 2; ++k) dst[n][k] = *(const PG8_LAS bf16x8*)(lds + PG8_SB(b, h) + boff + n * 2048 + k * 1024); } while (0)
; #define PG8_MMA(ai, bj, At, Bt) do { __builtin_amdgcn_s_setprio(1); _Pragma("unroll") for (int m = 0; m < 4; ++m) _Pragma("unroll") for (int n = 0; n < 2; ++n) _Pragma("unroll") for (int k = 0; k < 2; ++k) \
;         acc[ai][bj][m][n] = __builtin_amdgcn_mfma_f32_16x16x32_bf16(Bt[n][k], At[m][k], acc[ai][bj][m][n], 0, 0, 0); __builtin_amdgcn_s_setprio(0); } while (0)
; #define PG8_WAIT_V(n) asm volatile("s_waitcnt vmcnt(" #n ")" ::: "memory")
; #define PG8_WAIT_L(n) asm volatile("s_waitcnt lgkmcnt(" #n ")" ::: "memory")
; #define PG8_BAR __builtin_amdgcn_s_barrier()
; #define PG8_SCHED __builtin_amdgcn_sched_barrier(0)
; template <class Epi, class Sched>
; __device__ __forceinline__ void gemm_phase(PG8_LAS unsigned char* lds, const Gemm g, const Sched& S, const Epi& E) {
;     ...
;             PG8_LDB(B0, 1, 0); PG8_SCHED; PG8_LDA(At, 1, 0); PG8_STAGE(PG8_SA(0, 1), a2 + hstep, voffA);
;             PG8_WAIT_L(8); PG8_BAR; PG8_WAIT_L(0); PG8_MMA(0, 0, At, B0); PG8_BAR; PG8_SCHED;
;             PG8_LDB(B1, 1, 1); PG8_STAGE(PG8_SB(1, 0), b3, voffB);
;             PG8_BAR; PG8_WAIT_L(0); PG8_MMA(0, 1, At, B1); PG8_BAR;
;             PG8_LDA(At, 1, 1); PG8_STAGE(PG8_SA(1, 0), a3, voffA);
;             PG8_BAR; PG8_WAIT_L(0); PG8_MMA(1, 0, At, B0); PG8_BAR; PG8_SCHED;
;             PG8_STAGE(PG8_SB(1, 1), b3 + hstep, voffB);
;             PG8_WAIT_V(6); PG8_BAR; PG8_MMA(1, 1, At, B1); PG8_BAR;
;         }
	s_add_i32 s59, 0, 0x18000
	v_add_u32_e32 v155, s59, v149
	ds_read_b128 v[144:147], v155
	ds_read_b128 v[156:159], v155 offset:1024
	ds_read_b128 v[160:163], v155 offset:2048
	ds_read_b128 v[166:169], v155 offset:3072
	s_add_u32 s34, s34, 0x40000
	s_addc_u32 s35, s35, 0
	s_mov_b32 m0, s44
	ds_read_b128 v[170:173], v153 offset:32768
	ds_read_b128 v[182:185], v153 offset:33792
	ds_read_b128 v[190:193], v153 offset:34816
	ds_read_b128 v[194:197], v153 offset:35840
	ds_read_b128 v[198:201], v153 offset:36864
	ds_read_b128 v[202:205], v153 offset:37888
	ds_read_b128 v[206:209], v153 offset:38912
	ds_read_b128 v[210:213], v153 offset:39936
	global_load_lds_dwordx4 v134, s[34:35]
	s_nop 1
	s_mov_b32 m0, s45
	s_nop 0
	global_load_lds_dwordx4 v130, s[34:35]
	s_add_i32 s34, 0, 0x1c000
	v_add_u32_e32 v155, s34, v149
	s_waitcnt lgkmcnt(8)
	ds_read_b128 v[214:217], v155
	ds_read_b128 v[218:221], v155 offset:1024
	ds_read_b128 v[222:225], v155 offset:2048
	ds_read_b128 v[226:229], v155 offset:3072
	s_waitcnt vmcnt(8) lgkmcnt(0)
	s_barrier
	v_mfma_f32_16x16x32_bf16 v[124:127], v[144:147], v[170:173], v[124:127]
	v_mfma_f32_16x16x32_bf16 v[120:123], v[160:163], v[170:173], v[120:123]
	v_mfma_f32_16x16x32_bf16 v[108:111], v[144:147], v[190:193], v[108:111]
	v_mfma_f32_16x16x32_bf16 v[104:107], v[160:163], v[190:193], v[104:107]
	v_mfma_f32_16x16x32_bf16 v[92:95], v[144:147], v[198:201], v[92:95]
	v_mfma_f32_16x16x32_bf16 v[88:91], v[160:163], v[198:201], v[88:91]
	v_mfma_f32_16x16x32_bf16 v[76:79], v[144:147], v[206:209], v[76:79]
	v_mfma_f32_16x16x32_bf16 v[72:75], v[160:163], v[206:209], v[72:75]
	v_mfma_f32_16x16x32_bf16 v[124:127], v[156:159], v[182:185], v[124:127]
	v_mfma_f32_16x16x32_bf16 v[120:123], v[166:169], v[182:185], v[120:123]
	v_mfma_f32_16x16x32_bf16 v[108:111], v[156:159], v[194:197], v[108:111]
	v_mfma_f32_16x16x32_bf16 v[104:107], v[166:169], v[194:197], v[104:107]
	v_mfma_f32_16x16x32_bf16 v[92:95], v[156:159], v[202:205], v[92:95]
	v_mfma_f32_16x16x32_bf16 v[88:91], v[166:169], v[202:205], v[88:91]
	v_mfma_f32_16x16x32_bf16 v[76:79], v[156:159], v[210:213], v[76:79]
	v_mfma_f32_16x16x32_bf16 v[72:75], v[166:169], v[210:213], v[72:75]
	v_mfma_f32_16x16x32_bf16 v[116:119], v[214:217], v[170:173], v[116:119]
	v_mfma_f32_16x16x32_bf16 v[112:115], v[222:225], v[170:173], v[112:115]
	v_mfma_f32_16x16x32_bf16 v[100:103], v[214:217], v[190:193], v[100:103]
	v_mfma_f32_16x16x32_bf16 v[96:99], v[222:225], v[190:193], v[96:99]
	v_mfma_f32_16x16x32_bf16 v[84:87], v[214:217], v[198:201], v[84:87]
	v_mfma_f32_16x16x32_bf16 v[80:83], v[222:225], v[198:201], v[80:83]
	v_mfma_f32_16x16x32_bf16 v[68:71], v[214:217], v[206:209], v[68:71]
	v_mfma_f32_16x16x32_bf16 v[64:67], v[222:225], v[206:209], v[64:67]
	v_mfma_f32_16x16x32_bf16 v[116:119], v[218:221], v[182:185], v[116:119]
	v_mfma_f32_16x16x32_bf16 v[112:115], v[226:229], v[182:185], v[112:115]
	v_mfma_f32_16x16x32_bf16 v[100:103], v[218:221], v[194:197], v[100:103]
	v_mfma_f32_16x16x32_bf16 v[96:99], v[226:229], v[194:197], v[96:99]
	v_mfma_f32_16x16x32_bf16 v[84:87], v[218:221], v[202:205], v[84:87]
	v_mfma_f32_16x16x32_bf16 v[80:83], v[226:229], v[202:205], v[80:83]
	v_mfma_f32_16x16x32_bf16 v[68:71], v[218:221], v[210:213], v[68:71]
	v_mfma_f32_16x16x32_bf16 v[64:67], v[226:229], v[210:213], v[64:67]
	s_barrier
	ds_read_b128 v[170:173], v153 offset:49152
	ds_read_b128 v[182:185], v153 offset:50176
	ds_read_b128 v[190:193], v153 offset:51200
	ds_read_b128 v[194:197], v153 offset:52224
	ds_read_b128 v[198:201], v153 offset:53248
	ds_read_b128 v[202:205], v153 offset:54272
	ds_read_b128 v[206:209], v153 offset:55296
	ds_read_b128 v[210:213], v153 offset:56320
	s_add_i32 s35, s59, s40
	s_mov_b32 m0, s35
	s_nop 0
	global_load_lds_dwordx4 v132, s[98:99]
	s_nop 1
	s_add_i32 m0, s35, 0x2000
	s_nop 0
	global_load_lds_dwordx4 v128, s[98:99]
	s_nop 1
	s_mov_b32 m0, s47
	s_nop 0
	global_load_lds_dwordx4 v134, s[100:101]
	s_nop 1
	s_mov_b32 m0, s48
	s_nop 0
	global_load_lds_dwordx4 v130, s[100:101]
	s_add_u32 s30, s30, 0x40080
	s_addc_u32 s31, s31, 0
	s_add_i32 s34, s34, s40
	s_mov_b32 m0, s34
	s_nop 0
	global_load_lds_dwordx4 v132, s[30:31]
	s_nop 1
	s_add_i32 m0, s34, 0x2000
	s_nop 0
	global_load_lds_dwordx4 v128, s[30:31]
	s_waitcnt vmcnt(8) lgkmcnt(0)
	s_barrier
	v_mfma_f32_16x16x32_bf16 v[60:63], v[144:147], v[170:173], v[60:63]
	v_mfma_f32_16x16x32_bf16 v[56:59], v[160:163], v[170:173], v[56:59]
	v_mfma_f32_16x16x32_bf16 v[44:47], v[144:147], v[190:193], v[44:47]
	v_mfma_f32_16x16x32_bf16 v[40:43], v[160:163], v[190:193], v[40:43]
	v_mfma_f32_16x16x32_bf16 v[28:31], v[144:147], v[198:201], v[28:31]
	v_mfma_f32_16x16x32_bf16 v[24:27], v[160:163], v[198:201], v[24:27]
	v_mfma_f32_16x16x32_bf16 v[12:15], v[144:147], v[206:209], v[12:15]
	v_mfma_f32_16x16x32_bf16 v[8:11], v[160:163], v[206:209], v[8:11]
	v_mfma_f32_16x16x32_bf16 v[60:63], v[156:159], v[182:185], v[60:63]
	v_mfma_f32_16x16x32_bf16 v[56:59], v[166:169], v[182:185], v[56:59]
	v_mfma_f32_16x16x32_bf16 v[44:47], v[156:159], v[194:197], v[44:47]
	v_mfma_f32_16x16x32_bf16 v[40:43], v[166:169], v[194:197], v[40:43]
	v_mfma_f32_16x16x32_bf16 v[28:31], v[156:159], v[202:205], v[28:31]
	v_mfma_f32_16x16x32_bf16 v[24:27], v[166:169], v[202:205], v[24:27]
	v_mfma_f32_16x16x32_bf16 v[12:15], v[156:159], v[210:213], v[12:15]
	v_mfma_f32_16x16x32_bf16 v[8:11], v[166:169], v[210:213], v[8:11]
	v_mfma_f32_16x16x32_bf16 v[52:55], v[214:217], v[170:173], v[52:55]
	v_mfma_f32_16x16x32_bf16 v[48:51], v[222:225], v[170:173], v[48:51]
	v_mfma_f32_16x16x32_bf16 v[36:39], v[214:217], v[190:193], v[36:39]
	v_mfma_f32_16x16x32_bf16 v[32:35], v[222:225], v[190:193], v[32:35]
	v_mfma_f32_16x16x32_bf16 v[20:23], v[214:217], v[198:201], v[20:23]
	v_mfma_f32_16x16x32_bf16 v[16:19], v[222:225], v[198:201], v[16:19]
	v_mfma_f32_16x16x32_bf16 v[4:7], v[214:217], v[206:209], v[4:7]
	v_mfma_f32_16x16x32_bf16 v[0:3], v[222:225], v[206:209], v[0:3]
	v_mfma_f32_16x16x32_bf16 v[52:55], v[218:221], v[182:185], v[52:55]
	v_mfma_f32_16x16x32_bf16 v[48:51], v[226:229], v[182:185], v[48:51]
	v_mfma_f32_16x16x32_bf16 v[36:39], v[218:221], v[194:197], v[36:39]
	v_mfma_f32_16x16x32_bf16 v[32:35], v[226:229], v[194:197], v[32:35]
	v_mfma_f32_16x16x32_bf16 v[20:23], v[218:221], v[202:205], v[20:23]
	v_mfma_f32_16x16x32_bf16 v[16:19], v[226:229], v[202:205], v[16:19]
	v_mfma_f32_16x16x32_bf16 v[4:7], v[218:221], v[210:213], v[4:7]
	v_mfma_f32_16x16x32_bf16 v[0:3], v[226:229], v[210:213], v[0:3]
	s_barrier
; __device__ __forceinline__ unsigned cvt_pk_bf16(float lo, float hi) { unsigned r; asm volatile("v_cvt_pk_bf16_f32 %0, %1, %2" : "=v"(r) : "v"(lo), "v"(hi)); return r; }
; __device__ __forceinline__ f32x4 sigmoid4(f32x4 x) {
;     f32x4 d;
; #pragma unroll
;     for (int j = 0; j < 4; ++j) d[j] = 1.0f + __expf(-fmaxf(x[j], -20.0f));
;     const float p01 = d[0] * d[1], p23 = d[2] * d[3], r = __builtin_amdgcn_rcpf(p01 * p23), r01 = r * p23, r23 = r * p01;
;     return (f32x4){r01 * d[1], r01 * d[0], r23 * d[3], r23 * d[2]};
; }
;     __device__ __forceinline__ void operator()(const f32x4 (&acc)[2][2][4][2], const Unit& u, int wr, int wc, int fr, int fq) const {
;         const int row0 = u.pm * BM + wr * 64 + fr, col0 = u.pn * HALF + wc * 32 + 8 * fq;
; #pragma unroll
;         for (int ai = 0; ai < 2; ++ai)
; #pragma unroll
;             for (int m = 0; m < 4; ++m) { bf16_t* rowp = O + (size_t)(row0 + ai * HALF + m * 16) * ldc + col0;
;                 f32x4 v0, v1;
; #pragma unroll
;                 for (int j = 0; j < 1; ++j) { v0 = acc[ai][0][m][0] * sigmoid4(acc[ai][0][m][0]) * acc[ai][1][m][0]; v1 = acc[ai][0][m][1] * sigmoid4(acc[ai][0][m][1]) * acc[ai][1][m][1]; }
;                 u32x4 w; w.x = cvt_pk_bf16(v0[0], v0[1]); w.y = cvt_pk_bf16(v0[2], v0[3]); w.z = cvt_pk_bf16(v1[0], v1[1]); w.w = cvt_pk_bf16(v1[2], v1[3]);
;                 *(u32x4*)rowp = w; }
	s_add_i32 s58, s58, 2
	s_add_u32 s28, s28, 0x100
	s_addc_u32 s29, s29, 0
	s_add_u32 s56, s56, 0x100
	s_addc_u32 s57, s57, 0
	s_cmp_gt_u32 s58, 13
	s_cbranch_scc0 .LBB0_195
	v_max_f32_e32 v144, 0xc1a00000, v124
	v_mul_f32_e32 v144, 0xbfb8aa3b, v144
	v_exp_f32_e32 v157, v144
	v_max_f32_e32 v144, 0xc1a00000, v125
	v_mul_f32_e32 v144, 0xbfb8aa3b, v144
	v_exp_f32_e32 v156, v144
	v_max_f32_e32 v144, 0xc1a00000, v126
	v_mul_f32_e32 v144, 0xbfb8aa3b, v144
	v_exp_f32_e32 v159, v144
	v_max_f32_e32 v144, 0xc1a00000, v127
	v_mul_f32_e32 v144, 0xbfb8aa3b, v144
	v_exp_f32_e32 v158, v144
	v_pk_add_f32 v[156:157], v[156:157], 1.0 op_sel_hi:[1,0]
	v_lshl_or_b32 v146, s53, 7, v150
	v_pk_add_f32 v[158:159], v[158:159], 1.0 op_sel_hi:[1,0]
	v_mul_f32_e32 v160, v157, v156
	v_mul_f32_e32 v161, v159, v158
	v_lshl_add_u32 v155, s26, 8, v148
	v_mul_f32_e32 v162, v160, v161
	v_rcp_f32_e32 v166, v162
	v_ashrrev_i32_e32 v147, 31, v146
	v_mov_b64_e32 v[144:145], s[4:5]
	v_mad_i64_i32 v[162:163], s[28:29], v155, s52, v[144:145]
	v_mul_f32_e32 v160, v160, v166
	v_mul_f32_e32 v164, v161, v166
	v_pk_mul_f32 v[158:159], v[158:159], v[160:161] op_sel_hi:[1,0]
	v_max_f32_e32 v160, 0xc1a00000, v120
	v_max_f32_e32 v166, 0xc1a00000, v122
	v_mul_f32_e32 v160, 0xbfb8aa3b, v160
	v_mul_f32_e32 v166, 0xbfb8aa3b, v166
	v_exp_f32_e32 v161, v160
	v_exp_f32_e32 v167, v166
	v_max_f32_e32 v160, 0xc1a00000, v121
	v_max_f32_e32 v166, 0xc1a00000, v123
	v_mul_f32_e32 v160, 0xbfb8aa3b, v160
	v_mul_f32_e32 v166, 0xbfb8aa3b, v166
	v_exp_f32_e32 v160, v160
	v_exp_f32_e32 v166, v166
	v_pk_mul_f32 v[156:157], v[156:157], v[164:165] op_sel_hi:[1,0]
	v_pk_mul_f32 v[126:127], v[126:127], v[158:159]
	v_pk_mul_f32 v[124:125], v[124:125], v[156:157]
	v_pk_add_f32 v[156:157], v[160:161], 1.0 op_sel_hi:[1,0]
	v_pk_add_f32 v[160:161], v[166:167], 1.0 op_sel_hi:[1,0]
	v_mov_b32_e32 v166, v157
	v_mov_b32_e32 v167, v161
	v_mov_b32_e32 v168, v156
	v_mov_b32_e32 v169, v160
	v_pk_mul_f32 v[166:167], v[166:167], v[168:169]
	v_pk_mul_f32 v[118:119], v[126:127], v[118:119]
	v_mul_f32_e32 v164, v166, v167
	v_rcp_f32_e32 v164, v164
	v_pk_mul_f32 v[116:117], v[124:125], v[116:117]
	v_lshlrev_b64 v[146:147], 1, v[146:147]
	v_lshl_add_u64 v[162:163], v[162:163], 0, v[146:147]
	v_mul_f32_e32 v124, v167, v164
	v_mul_f32_e32 v126, v166, v164
	v_pk_mul_f32 v[126:127], v[160:161], v[126:127] op_sel_hi:[1,0]
	v_pk_mul_f32 v[124:125], v[156:157], v[124:125] op_sel_hi:[1,0]
	v_pk_mul_f32 v[122:123], v[122:123], v[126:127]
	v_pk_mul_f32 v[120:121], v[120:121], v[124:125]
	v_pk_mul_f32 v[122:123], v[122:123], v[114:115]
	v_pk_mul_f32 v[114:115], v[120:121], v[112:113]
	v_cvt_pk_bf16_f32 v112, v116, v117
	v_cvt_pk_bf16_f32 v113, v118, v119
	v_max_f32_e32 v116, 0xc1a00000, v108
	v_max_f32_e32 v118, 0xc1a00000, v110
	v_mul_f32_e32 v116, 0xbfb8aa3b, v116
	v_mul_f32_e32 v118, 0xbfb8aa3b, v118
	v_exp_f32_e32 v117, v116
	v_exp_f32_e32 v119, v118
	v_max_f32_e32 v116, 0xc1a00000, v109
	v_max_f32_e32 v118, 0xc1a00000, v111
	v_mul_f32_e32 v116, 0xbfb8aa3b, v116
	v_mul_f32_e32 v118, 0xbfb8aa3b, v118
	v_exp_f32_e32 v116, v116
	v_exp_f32_e32 v118, v118
	v_cvt_pk_bf16_f32 v114, v114, v115
	v_cvt_pk_bf16_f32 v115, v122, v123
	global_store_dwordx4 v[162:163], v[112:115], off
	v_or_b32_e32 v120, 16, v155
	s_and_b64 vcc, exec, s[2:3]
	v_pk_add_f32 v[112:113], v[116:117], 1.0 op_sel_hi:[1,0]
	v_pk_add_f32 v[114:115], v[118:119], 1.0 op_sel_hi:[1,0]
	v_mul_f32_e32 v116, v113, v112
	v_mul_f32_e32 v117, v115, v114
	s_mov_b32 s53, s14
	v_mul_f32_e32 v118, v116, v117
	v_rcp_f32_e32 v121, v118
	v_mad_i64_i32 v[118:119], s[28:29], v120, s52, v[144:145]
	v_lshl_add_u64 v[118:119], v[118:119], 0, v[146:147]
	v_mul_f32_e32 v116, v116, v121
	v_mul_f32_e32 v120, v117, v121
	v_pk_mul_f32 v[114:115], v[114:115], v[116:117] op_sel_hi:[1,0]
	v_max_f32_e32 v116, 0xc1a00000, v104
	v_max_f32_e32 v121, 0xc1a00000, v106
	v_mul_f32_e32 v116, 0xbfb8aa3b, v116
	v_mul_f32_e32 v121, 0xbfb8aa3b, v121
	v_exp_f32_e32 v117, v116
	v_exp_f32_e32 v123, v121
	v_max_f32_e32 v116, 0xc1a00000, v105
	v_max_f32_e32 v121, 0xc1a00000, v107
	v_mul_f32_e32 v116, 0xbfb8aa3b, v116
	v_mul_f32_e32 v121, 0xbfb8aa3b, v121
	v_exp_f32_e32 v116, v116
	v_exp_f32_e32 v122, v121
	v_pk_mul_f32 v[112:113], v[112:113], v[120:121] op_sel_hi:[1,0]
	v_pk_mul_f32 v[110:111], v[110:111], v[114:115]
	v_pk_mul_f32 v[108:109], v[108:109], v[112:113]
	v_pk_add_f32 v[112:113], v[116:117], 1.0 op_sel_hi:[1,0]
	v_pk_add_f32 v[116:117], v[122:123], 1.0 op_sel_hi:[1,0]
	v_mov_b32_e32 v120, v113
	v_mov_b32_e32 v121, v117
	v_mov_b32_e32 v122, v112
	v_mov_b32_e32 v123, v116
	v_pk_mul_f32 v[120:121], v[120:121], v[122:123]
	v_pk_mul_f32 v[102:103], v[110:111], v[102:103]
	v_mul_f32_e32 v122, v120, v121
	v_rcp_f32_e32 v122, v122
	v_pk_mul_f32 v[100:101], v[108:109], v[100:101]
	s_mov_b32 s26, s16
	s_mov_b64 s[30:31], s[24:25]
	v_mul_f32_e32 v108, v121, v122
	v_mul_f32_e32 v110, v120, v122
	v_pk_mul_f32 v[110:111], v[116:117], v[110:111] op_sel_hi:[1,0]
	v_pk_mul_f32 v[108:109], v[112:113], v[108:109] op_sel_hi:[1,0]
	v_pk_mul_f32 v[106:107], v[106:107], v[110:111]
	v_pk_mul_f32 v[104:105], v[104:105], v[108:109]
	v_pk_mul_f32 v[106:107], v[106:107], v[98:99]
	v_pk_mul_f32 v[98:99], v[104:105], v[96:97]
	v_cvt_pk_bf16_f32 v96, v100, v101
	v_cvt_pk_bf16_f32 v97, v102, v103
	v_max_f32_e32 v100, 0xc1a00000, v92
	v_max_f32_e32 v102, 0xc1a00000, v94
	v_mul_f32_e32 v100, 0xbfb8aa3b, v100
	v_mul_f32_e32 v102, 0xbfb8aa3b, v102
	v_exp_f32_e32 v101, v100
	v_exp_f32_e32 v103, v102
	v_max_f32_e32 v100, 0xc1a00000, v93
	v_max_f32_e32 v102, 0xc1a00000, v95
	v_mul_f32_e32 v100, 0xbfb8aa3b, v100
	v_mul_f32_e32 v102, 0xbfb8aa3b, v102
; __device__ __forceinline__ unsigned cvt_pk_bf16(float lo, float hi) { unsigned r; asm volatile("v_cvt_pk_bf16_f32 %0, %1, %2" : "=v"(r) : "v"(lo), "v"(hi)); return r; }
; __device__ __forceinline__ f32x4 sigmoid4(f32x4 x) {
;     f32x4 d;
; #pragma unroll
;     for (int j = 0; j < 4; ++j) d[j] = 1.0f + __expf(-fmaxf(x[j], -20.0f));
;     const float p01 = d[0] * d[1], p23 = d[2] * d[3], r = __builtin_amdgcn_rcpf(p01 * p23), r01 = r * p23, r23 = r * p01;
;     return (f32x4){r01 * d[1], r01 * d[0], r23 * d[3], r23 * d[2]};
; }
;     __device__ __forceinline__ void operator()(const f32x4 (&acc)[2][2][4][2], const Unit& u, int wr, int wc, int fr, int fq) const {
;         const int row0 = u.pm * BM + wr * 64 + fr, col0 = u.pn * HALF + wc * 32 + 8 * fq;
; #pragma unroll
;         for (int ai = 0; ai < 2; ++ai)
; #pragma unroll
;             for (int m = 0; m < 4; ++m) { bf16_t* rowp = O + (size_t)(row0 + ai * HALF + m * 16) * ldc + col0;
;                 f32x4 v0, v1;
; #pragma unroll
;                 for (int j = 0; j < 1; ++j) { v0 = acc[ai][0][m][0] * sigmoid4(acc[ai][0][m][0]) * acc[ai][1][m][0]; v1 = acc[ai][0][m][1] * sigmoid4(acc[ai][0][m][1]) * acc[ai][1][m][1]; }
;                 u32x4 w; w.x = cvt_pk_bf16(v0[0], v0[1]); w.y = cvt_pk_bf16(v0[2], v0[3]); w.z = cvt_pk_bf16(v1[0], v1[1]); w.w = cvt_pk_bf16(v1[2], v1[3]);
;                 *(u32x4*)rowp = w; }
	v_exp_f32_e32 v100, v100
	v_exp_f32_e32 v102, v102
	v_cvt_pk_bf16_f32 v98, v98, v99
	v_cvt_pk_bf16_f32 v99, v106, v107
	global_store_dwordx4 v[118:119], v[96:99], off
	v_or_b32_e32 v104, 32, v155
	s_nop 0
	v_pk_add_f32 v[96:97], v[100:101], 1.0 op_sel_hi:[1,0]
	v_pk_add_f32 v[98:99], v[102:103], 1.0 op_sel_hi:[1,0]
	v_mul_f32_e32 v100, v97, v96
	v_mul_f32_e32 v101, v99, v98
	s_nop 0
	v_mul_f32_e32 v102, v100, v101
	v_rcp_f32_e32 v105, v102
	v_mad_i64_i32 v[102:103], s[28:29], v104, s52, v[144:145]
	v_lshl_add_u64 v[102:103], v[102:103], 0, v[146:147]
	v_mul_f32_e32 v100, v100, v105
	v_mul_f32_e32 v104, v101, v105
	v_pk_mul_f32 v[98:99], v[98:99], v[100:101] op_sel_hi:[1,0]
	v_max_f32_e32 v100, 0xc1a00000, v88
	v_max_f32_e32 v105, 0xc1a00000, v90
	v_mul_f32_e32 v100, 0xbfb8aa3b, v100
	v_mul_f32_e32 v105, 0xbfb8aa3b, v105
	v_exp_f32_e32 v101, v100
	v_exp_f32_e32 v107, v105
	v_max_f32_e32 v100, 0xc1a00000, v89
	v_max_f32_e32 v105, 0xc1a00000, v91
	v_mul_f32_e32 v100, 0xbfb8aa3b, v100
	v_mul_f32_e32 v105, 0xbfb8aa3b, v105
	v_exp_f32_e32 v100, v100
	v_exp_f32_e32 v106, v105
	v_pk_mul_f32 v[96:97], v[96:97], v[104:105] op_sel_hi:[1,0]
	v_pk_mul_f32 v[94:95], v[94:95], v[98:99]
	v_pk_mul_f32 v[92:93], v[92:93], v[96:97]
	v_pk_add_f32 v[96:97], v[100:101], 1.0 op_sel_hi:[1,0]
	v_pk_add_f32 v[100:101], v[106:107], 1.0 op_sel_hi:[1,0]
	v_mov_b32_e32 v104, v97
	v_mov_b32_e32 v105, v101
	v_mov_b32_e32 v106, v96
	v_mov_b32_e32 v107, v100
	v_pk_mul_f32 v[104:105], v[104:105], v[106:107]
	v_pk_mul_f32 v[86:87], v[94:95], v[86:87]
	v_mul_f32_e32 v106, v104, v105
	v_rcp_f32_e32 v106, v106
	v_pk_mul_f32 v[84:85], v[92:93], v[84:85]
	v_mul_f32_e32 v92, v105, v106
	v_mul_f32_e32 v94, v104, v106
	v_pk_mul_f32 v[94:95], v[100:101], v[94:95] op_sel_hi:[1,0]
	v_pk_mul_f32 v[92:93], v[96:97], v[92:93] op_sel_hi:[1,0]
	v_pk_mul_f32 v[90:91], v[90:91], v[94:95]
	v_pk_mul_f32 v[88:89], v[88:89], v[92:93]
	v_pk_mul_f32 v[90:91], v[90:91], v[82:83]
	v_pk_mul_f32 v[82:83], v[88:89], v[80:81]
	v_cvt_pk_bf16_f32 v80, v84, v85
	v_cvt_pk_bf16_f32 v81, v86, v87
	v_max_f32_e32 v84, 0xc1a00000, v76
	v_max_f32_e32 v86, 0xc1a00000, v78
	v_mul_f32_e32 v84, 0xbfb8aa3b, v84
	v_mul_f32_e32 v86, 0xbfb8aa3b, v86
	v_exp_f32_e32 v85, v84
	v_exp_f32_e32 v87, v86
	v_max_f32_e32 v84, 0xc1a00000, v77
	v_max_f32_e32 v86, 0xc1a00000, v79
	v_mul_f32_e32 v84, 0xbfb8aa3b, v84
	v_mul_f32_e32 v86, 0xbfb8aa3b, v86
	v_exp_f32_e32 v84, v84
	v_exp_f32_e32 v86, v86
	v_cvt_pk_bf16_f32 v82, v82, v83
	v_cvt_pk_bf16_f32 v83, v90, v91
	global_store_dwordx4 v[102:103], v[80:83], off
	v_or_b32_e32 v88, 48, v155
	s_nop 0
	v_pk_add_f32 v[80:81], v[84:85], 1.0 op_sel_hi:[1,0]
	v_pk_add_f32 v[82:83], v[86:87], 1.0 op_sel_hi:[1,0]
	v_mul_f32_e32 v84, v81, v80
	v_mul_f32_e32 v85, v83, v82
	s_nop 0
	v_mul_f32_e32 v86, v84, v85
	v_rcp_f32_e32 v89, v86
	v_mad_i64_i32 v[86:87], s[28:29], v88, s52, v[144:145]
	v_lshl_add_u64 v[86:87], v[86:87], 0, v[146:147]
	v_mul_f32_e32 v84, v84, v89
	v_mul_f32_e32 v88, v85, v89
	v_pk_mul_f32 v[82:83], v[82:83], v[84:85] op_sel_hi:[1,0]
	v_max_f32_e32 v84, 0xc1a00000, v72
	v_max_f32_e32 v89, 0xc1a00000, v74
	v_mul_f32_e32 v84, 0xbfb8aa3b, v84
	v_mul_f32_e32 v89, 0xbfb8aa3b, v89
	v_exp_f32_e32 v85, v84
	v_exp_f32_e32 v91, v89
	v_max_f32_e32 v84, 0xc1a00000, v73
	v_max_f32_e32 v89, 0xc1a00000, v75
	v_mul_f32_e32 v84, 0xbfb8aa3b, v84
	v_mul_f32_e32 v89, 0xbfb8aa3b, v89
	v_exp_f32_e32 v84, v84
	v_exp_f32_e32 v90, v89
	v_pk_mul_f32 v[80:81], v[80:81], v[88:89] op_sel_hi:[1,0]
	v_pk_mul_f32 v[78:79], v[78:79], v[82:83]
	v_pk_mul_f32 v[76:77], v[76:77], v[80:81]
	v_pk_add_f32 v[80:81], v[84:85], 1.0 op_sel_hi:[1,0]
	v_pk_add_f32 v[84:85], v[90:91], 1.0 op_sel_hi:[1,0]
	v_mov_b32_e32 v88, v81
	v_mov_b32_e32 v89, v85
	v_mov_b32_e32 v90, v80
	v_mov_b32_e32 v91, v84
	v_pk_mul_f32 v[88:89], v[88:89], v[90:91]
	v_pk_mul_f32 v[70:71], v[78:79], v[70:71]
	v_mul_f32_e32 v90, v88, v89
	v_rcp_f32_e32 v90, v90
	v_pk_mul_f32 v[68:69], v[76:77], v[68:69]
	v_mul_f32_e32 v76, v89, v90
	v_mul_f32_e32 v78, v88, v90
	v_pk_mul_f32 v[78:79], v[84:85], v[78:79] op_sel_hi:[1,0]
	v_pk_mul_f32 v[76:77], v[80:81], v[76:77] op_sel_hi:[1,0]
	v_pk_mul_f32 v[74:75], v[74:75], v[78:79]
	v_pk_mul_f32 v[72:73], v[72:73], v[76:77]
	v_pk_mul_f32 v[74:75], v[74:75], v[66:67]
	v_pk_mul_f32 v[66:67], v[72:73], v[64:65]
	v_cvt_pk_bf16_f32 v64, v68, v69
	v_cvt_pk_bf16_f32 v65, v70, v71
	v_max_f32_e32 v68, 0xc1a00000, v60
	v_max_f32_e32 v70, 0xc1a00000, v62
	v_mul_f32_e32 v68, 0xbfb8aa3b, v68
	v_mul_f32_e32 v70, 0xbfb8aa3b, v70
	v_exp_f32_e32 v69, v68
	v_exp_f32_e32 v71, v70
	v_max_f32_e32 v68, 0xc1a00000, v61
	v_max_f32_e32 v70, 0xc1a00000, v63
	v_mul_f32_e32 v68, 0xbfb8aa3b, v68
	v_mul_f32_e32 v70, 0xbfb8aa3b, v70
	v_exp_f32_e32 v68, v68
	v_exp_f32_e32 v70, v70
	v_cvt_pk_bf16_f32 v66, v66, v67
	v_cvt_pk_bf16_f32 v67, v74, v75
	global_store_dwordx4 v[86:87], v[64:67], off
	v_add_u32_e32 v72, 0x80, v155
	s_nop 0
	v_pk_add_f32 v[64:65], v[68:69], 1.0 op_sel_hi:[1,0]
	v_pk_add_f32 v[66:67], v[70:71], 1.0 op_sel_hi:[1,0]
	v_mul_f32_e32 v68, v65, v64
	v_mul_f32_e32 v69, v67, v66
	s_nop 0
	v_mul_f32_e32 v70, v68, v69
	v_rcp_f32_e32 v73, v70
	v_mad_i64_i32 v[70:71], s[28:29], v72, s52, v[144:145]
	v_lshl_add_u64 v[70:71], v[70:71], 0, v[146:147]
	v_mul_f32_e32 v68, v68, v73
	v_mul_f32_e32 v72, v69, v73
	v_pk_mul_f32 v[66:67], v[66:67], v[68:69] op_sel_hi:[1,0]
	v_max_f32_e32 v68, 0xc1a00000, v56
	v_max_f32_e32 v73, 0xc1a00000, v58
	v_mul_f32_e32 v68, 0xbfb8aa3b, v68
	v_mul_f32_e32 v73, 0xbfb8aa3b, v73
	v_exp_f32_e32 v69, v68
	v_exp_f32_e32 v75, v73
	v_max_f32_e32 v68, 0xc1a00000, v57
	v_max_f32_e32 v73, 0xc1a00000, v59
; __device__ __forceinline__ unsigned cvt_pk_bf16(float lo, float hi) { unsigned r; asm volatile("v_cvt_pk_bf16_f32 %0, %1, %2" : "=v"(r) : "v"(lo), "v"(hi)); return r; }
; __device__ __forceinline__ f32x4 sigmoid4(f32x4 x) {
;     f32x4 d;
; #pragma unroll
;     for (int j = 0; j < 4; ++j) d[j] = 1.0f + __expf(-fmaxf(x[j], -20.0f));
;     const float p01 = d[0] * d[1], p23 = d[2] * d[3], r = __builtin_amdgcn_rcpf(p01 * p23), r01 = r * p23, r23 = r * p01;
;     return (f32x4){r01 * d[1], r01 * d[0], r23 * d[3], r23 * d[2]};
; }
;     __device__ __forceinline__ void operator()(const f32x4 (&acc)[2][2][4][2], const Unit& u, int wr, int wc, int fr, int fq) const {
;         const int row0 = u.pm * BM + wr * 64 + fr, col0 = u.pn * HALF + wc * 32 + 8 * fq;
; #pragma unroll
;         for (int ai = 0; ai < 2; ++ai)
; #pragma unroll
;             for (int m = 0; m < 4; ++m) { bf16_t* rowp = O + (size_t)(row0 + ai * HALF + m * 16) * ldc + col0;
;                 f32x4 v0, v1;
; #pragma unroll
;                 for (int j = 0; j < 1; ++j) { v0 = acc[ai][0][m][0] * sigmoid4(acc[ai][0][m][0]) * acc[ai][1][m][0]; v1 = acc[ai][0][m][1] * sigmoid4(acc[ai][0][m][1]) * acc[ai][1][m][1]; }
;                 u32x4 w; w.x = cvt_pk_bf16(v0[0], v0[1]); w.y = cvt_pk_bf16(v0[2], v0[3]); w.z = cvt_pk_bf16(v1[0], v1[1]); w.w = cvt_pk_bf16(v1[2], v1[3]);
;                 *(u32x4*)rowp = w; }
	v_mul_f32_e32 v68, 0xbfb8aa3b, v68
	v_mul_f32_e32 v73, 0xbfb8aa3b, v73
	v_exp_f32_e32 v68, v68
	v_exp_f32_e32 v74, v73
	v_pk_mul_f32 v[64:65], v[64:65], v[72:73] op_sel_hi:[1,0]
	v_pk_mul_f32 v[62:63], v[62:63], v[66:67]
	v_pk_mul_f32 v[60:61], v[60:61], v[64:65]
	v_pk_add_f32 v[64:65], v[68:69], 1.0 op_sel_hi:[1,0]
	v_pk_add_f32 v[68:69], v[74:75], 1.0 op_sel_hi:[1,0]
	v_mov_b32_e32 v72, v65
	v_mov_b32_e32 v73, v69
	v_mov_b32_e32 v74, v64
	v_mov_b32_e32 v75, v68
	v_pk_mul_f32 v[72:73], v[72:73], v[74:75]
	v_pk_mul_f32 v[54:55], v[62:63], v[54:55]
	v_mul_f32_e32 v74, v72, v73
	v_rcp_f32_e32 v74, v74
	v_pk_mul_f32 v[52:53], v[60:61], v[52:53]
	v_mul_f32_e32 v60, v73, v74
	v_mul_f32_e32 v62, v72, v74
	v_pk_mul_f32 v[62:63], v[68:69], v[62:63] op_sel_hi:[1,0]
	v_pk_mul_f32 v[60:61], v[64:65], v[60:61] op_sel_hi:[1,0]
	v_pk_mul_f32 v[58:59], v[58:59], v[62:63]
	v_pk_mul_f32 v[56:57], v[56:57], v[60:61]
	v_pk_mul_f32 v[58:59], v[58:59], v[50:51]
	v_pk_mul_f32 v[50:51], v[56:57], v[48:49]
	v_cvt_pk_bf16_f32 v48, v52, v53
	v_cvt_pk_bf16_f32 v49, v54, v55
	v_max_f32_e32 v52, 0xc1a00000, v44
	v_max_f32_e32 v54, 0xc1a00000, v46
	v_mul_f32_e32 v52, 0xbfb8aa3b, v52
	v_mul_f32_e32 v54, 0xbfb8aa3b, v54
	v_exp_f32_e32 v53, v52
	v_exp_f32_e32 v55, v54
	v_max_f32_e32 v52, 0xc1a00000, v45
	v_max_f32_e32 v54, 0xc1a00000, v47
	v_mul_f32_e32 v52, 0xbfb8aa3b, v52
	v_mul_f32_e32 v54, 0xbfb8aa3b, v54
	v_exp_f32_e32 v52, v52
	v_exp_f32_e32 v54, v54
	v_cvt_pk_bf16_f32 v50, v50, v51
	v_cvt_pk_bf16_f32 v51, v58, v59
	global_store_dwordx4 v[70:71], v[48:51], off
	v_add_u32_e32 v56, 0x90, v155
	s_nop 0
	v_pk_add_f32 v[48:49], v[52:53], 1.0 op_sel_hi:[1,0]
	v_pk_add_f32 v[50:51], v[54:55], 1.0 op_sel_hi:[1,0]
	v_mul_f32_e32 v52, v49, v48
	v_mul_f32_e32 v53, v51, v50
	s_nop 0
	v_mul_f32_e32 v54, v52, v53
	v_rcp_f32_e32 v57, v54
	v_mad_i64_i32 v[54:55], s[28:29], v56, s52, v[144:145]
	v_lshl_add_u64 v[54:55], v[54:55], 0, v[146:147]
	v_mul_f32_e32 v52, v52, v57
	v_mul_f32_e32 v56, v53, v57
	v_pk_mul_f32 v[50:51], v[50:51], v[52:53] op_sel_hi:[1,0]
	v_max_f32_e32 v52, 0xc1a00000, v40
	v_max_f32_e32 v57, 0xc1a00000, v42
	v_mul_f32_e32 v52, 0xbfb8aa3b, v52
	v_mul_f32_e32 v57, 0xbfb8aa3b, v57
	v_exp_f32_e32 v53, v52
	v_exp_f32_e32 v59, v57
	v_max_f32_e32 v52, 0xc1a00000, v41
	v_max_f32_e32 v57, 0xc1a00000, v43
	v_mul_f32_e32 v52, 0xbfb8aa3b, v52
	v_mul_f32_e32 v57, 0xbfb8aa3b, v57
	v_exp_f32_e32 v52, v52
	v_exp_f32_e32 v58, v57
	v_pk_mul_f32 v[48:49], v[48:49], v[56:57] op_sel_hi:[1,0]
	v_pk_mul_f32 v[46:47], v[46:47], v[50:51]
	v_pk_mul_f32 v[44:45], v[44:45], v[48:49]
	v_pk_add_f32 v[48:49], v[52:53], 1.0 op_sel_hi:[1,0]
	v_pk_add_f32 v[52:53], v[58:59], 1.0 op_sel_hi:[1,0]
	v_mov_b32_e32 v56, v49
	v_mov_b32_e32 v57, v53
	v_mov_b32_e32 v58, v48
	v_mov_b32_e32 v59, v52
	v_pk_mul_f32 v[56:57], v[56:57], v[58:59]
	v_pk_mul_f32 v[38:39], v[46:47], v[38:39]
	v_mul_f32_e32 v58, v56, v57
	v_rcp_f32_e32 v58, v58
	v_pk_mul_f32 v[36:37], v[44:45], v[36:37]
	v_mul_f32_e32 v44, v57, v58
	v_mul_f32_e32 v46, v56, v58
	v_pk_mul_f32 v[46:47], v[52:53], v[46:47] op_sel_hi:[1,0]
	v_pk_mul_f32 v[44:45], v[48:49], v[44:45] op_sel_hi:[1,0]
	v_pk_mul_f32 v[42:43], v[42:43], v[46:47]
	v_pk_mul_f32 v[40:41], v[40:41], v[44:45]
	v_pk_mul_f32 v[42:43], v[42:43], v[34:35]
	v_pk_mul_f32 v[34:35], v[40:41], v[32:33]
	v_cvt_pk_bf16_f32 v32, v36, v37
	v_cvt_pk_bf16_f32 v33, v38, v39
	v_max_f32_e32 v36, 0xc1a00000, v28
	v_max_f32_e32 v38, 0xc1a00000, v30
	v_mul_f32_e32 v36, 0xbfb8aa3b, v36
	v_mul_f32_e32 v38, 0xbfb8aa3b, v38
	v_exp_f32_e32 v37, v36
	v_exp_f32_e32 v39, v38
	v_max_f32_e32 v36, 0xc1a00000, v29
	v_max_f32_e32 v38, 0xc1a00000, v31
	v_mul_f32_e32 v36, 0xbfb8aa3b, v36
	v_mul_f32_e32 v38, 0xbfb8aa3b, v38
	v_exp_f32_e32 v36, v36
	v_exp_f32_e32 v38, v38
	v_cvt_pk_bf16_f32 v34, v34, v35
	v_cvt_pk_bf16_f32 v35, v42, v43
	global_store_dwordx4 v[54:55], v[32:35], off
	v_add_u32_e32 v40, 0xa0, v155
	s_nop 0
	v_pk_add_f32 v[32:33], v[36:37], 1.0 op_sel_hi:[1,0]
	v_pk_add_f32 v[34:35], v[38:39], 1.0 op_sel_hi:[1,0]
	v_mul_f32_e32 v36, v33, v32
	v_mul_f32_e32 v37, v35, v34
	s_nop 0
	v_mul_f32_e32 v38, v36, v37
; __device__ __forceinline__ unsigned cvt_pk_bf16(float lo, float hi) { unsigned r; asm volatile("v_cvt_pk_bf16_f32 %0, %1, %2" : "=v"(r) : "v"(lo), "v"(hi)); return r; }
; __device__ __forceinline__ f32x4 sigmoid4(f32x4 x) {
;     f32x4 d;
; #pragma unroll
;     for (int j = 0; j < 4; ++j) d[j] = 1.0f + __expf(-fmaxf(x[j], -20.0f));
;     const float p01 = d[0] * d[1], p23 = d[2] * d[3], r = __builtin_amdgcn_rcpf(p01 * p23), r01 = r * p23, r23 = r * p01;
;     return (f32x4){r01 * d[1], r01 * d[0], r23 * d[3], r23 * d[2]};
; }
;     __device__ __forceinline__ void operator()(const f32x4 (&acc)[2][2][4][2], const Unit& u, int wr, int wc, int fr, int fq) const {
;         const int row0 = u.pm * BM + wr * 64 + fr, col0 = u.pn * HALF + wc * 32 + 8 * fq;
; #pragma unroll
;         for (int ai = 0; ai < 2; ++ai)
; #pragma unroll
;             for (int m = 0; m < 4; ++m) { bf16_t* rowp = O + (size_t)(row0 + ai * HALF + m * 16) * ldc + col0;
;                 f32x4 v0, v1;
; #pragma unroll
;                 for (int j = 0; j < 1; ++j) { v0 = acc[ai][0][m][0] * sigmoid4(acc[ai][0][m][0]) * acc[ai][1][m][0]; v1 = acc[ai][0][m][1] * sigmoid4(acc[ai][0][m][1]) * acc[ai][1][m][1]; }
;                 u32x4 w; w.x = cvt_pk_bf16(v0[0], v0[1]); w.y = cvt_pk_bf16(v0[2], v0[3]); w.z = cvt_pk_bf16(v1[0], v1[1]); w.w = cvt_pk_bf16(v1[2], v1[3]);
;                 *(u32x4*)rowp = w; }
	v_rcp_f32_e32 v41, v38
	v_mad_i64_i32 v[38:39], s[28:29], v40, s52, v[144:145]
	v_lshl_add_u64 v[38:39], v[38:39], 0, v[146:147]
	v_mul_f32_e32 v36, v36, v41
	v_mul_f32_e32 v40, v37, v41
	v_pk_mul_f32 v[34:35], v[34:35], v[36:37] op_sel_hi:[1,0]
	v_max_f32_e32 v36, 0xc1a00000, v24
	v_max_f32_e32 v41, 0xc1a00000, v26
	v_mul_f32_e32 v36, 0xbfb8aa3b, v36
	v_mul_f32_e32 v41, 0xbfb8aa3b, v41
	v_exp_f32_e32 v37, v36
	v_exp_f32_e32 v43, v41
	v_max_f32_e32 v36, 0xc1a00000, v25
	v_max_f32_e32 v41, 0xc1a00000, v27
	v_mul_f32_e32 v36, 0xbfb8aa3b, v36
	v_mul_f32_e32 v41, 0xbfb8aa3b, v41
	v_exp_f32_e32 v36, v36
	v_exp_f32_e32 v42, v41
	v_pk_mul_f32 v[32:33], v[32:33], v[40:41] op_sel_hi:[1,0]
	v_pk_mul_f32 v[30:31], v[30:31], v[34:35]
	v_pk_mul_f32 v[28:29], v[28:29], v[32:33]
	v_pk_add_f32 v[32:33], v[36:37], 1.0 op_sel_hi:[1,0]
	v_pk_add_f32 v[36:37], v[42:43], 1.0 op_sel_hi:[1,0]
	v_mov_b32_e32 v40, v33
	v_mov_b32_e32 v41, v37
	v_mov_b32_e32 v42, v32
	v_mov_b32_e32 v43, v36
	v_pk_mul_f32 v[40:41], v[40:41], v[42:43]
	v_pk_mul_f32 v[22:23], v[30:31], v[22:23]
	v_mul_f32_e32 v42, v40, v41
	v_rcp_f32_e32 v42, v42
	v_pk_mul_f32 v[20:21], v[28:29], v[20:21]
	v_mul_f32_e32 v28, v41, v42
	v_mul_f32_e32 v30, v40, v42
	v_pk_mul_f32 v[30:31], v[36:37], v[30:31] op_sel_hi:[1,0]
	v_pk_mul_f32 v[28:29], v[32:33], v[28:29] op_sel_hi:[1,0]
	v_pk_mul_f32 v[26:27], v[26:27], v[30:31]
	v_pk_mul_f32 v[24:25], v[24:25], v[28:29]
	v_pk_mul_f32 v[26:27], v[26:27], v[18:19]
	v_pk_mul_f32 v[18:19], v[24:25], v[16:17]
	v_cvt_pk_bf16_f32 v16, v20, v21
	v_cvt_pk_bf16_f32 v17, v22, v23
	v_max_f32_e32 v20, 0xc1a00000, v12
	v_max_f32_e32 v22, 0xc1a00000, v14
	v_mul_f32_e32 v20, 0xbfb8aa3b, v20
	v_mul_f32_e32 v22, 0xbfb8aa3b, v22
	v_exp_f32_e32 v21, v20
	v_exp_f32_e32 v23, v22
	v_max_f32_e32 v20, 0xc1a00000, v13
	v_max_f32_e32 v22, 0xc1a00000, v15
	v_mul_f32_e32 v20, 0xbfb8aa3b, v20
	v_mul_f32_e32 v22, 0xbfb8aa3b, v22
	v_exp_f32_e32 v20, v20
	v_exp_f32_e32 v22, v22
	v_cvt_pk_bf16_f32 v18, v18, v19
	v_cvt_pk_bf16_f32 v19, v26, v27
	global_store_dwordx4 v[38:39], v[16:19], off
	v_add_u32_e32 v24, 0xb0, v155
	s_nop 0
	v_pk_add_f32 v[16:17], v[20:21], 1.0 op_sel_hi:[1,0]
	v_pk_add_f32 v[18:19], v[22:23], 1.0 op_sel_hi:[1,0]
	v_mul_f32_e32 v20, v17, v16
	v_mul_f32_e32 v21, v19, v18
	s_nop 0
	v_mul_f32_e32 v22, v20, v21
	v_rcp_f32_e32 v25, v22
	v_mad_i64_i32 v[22:23], s[28:29], v24, s52, v[144:145]
	v_lshl_add_u64 v[22:23], v[22:23], 0, v[146:147]
	v_mul_f32_e32 v20, v20, v25
	v_mul_f32_e32 v24, v21, v25
	v_pk_mul_f32 v[18:19], v[18:19], v[20:21] op_sel_hi:[1,0]
	v_max_f32_e32 v20, 0xc1a00000, v8
	v_max_f32_e32 v25, 0xc1a00000, v10
	v_mul_f32_e32 v20, 0xbfb8aa3b, v20
	v_mul_f32_e32 v25, 0xbfb8aa3b, v25
	v_exp_f32_e32 v21, v20
	v_exp_f32_e32 v27, v25
	v_max_f32_e32 v20, 0xc1a00000, v9
	v_max_f32_e32 v25, 0xc1a00000, v11
	v_mul_f32_e32 v20, 0xbfb8aa3b, v20
	v_mul_f32_e32 v25, 0xbfb8aa3b, v25
	v_exp_f32_e32 v20, v20
	v_exp_f32_e32 v26, v25
	v_pk_mul_f32 v[16:17], v[16:17], v[24:25] op_sel_hi:[1,0]
	v_pk_mul_f32 v[14:15], v[14:15], v[18:19]
	v_pk_mul_f32 v[12:13], v[12:13], v[16:17]
	v_pk_add_f32 v[16:17], v[20:21], 1.0 op_sel_hi:[1,0]
	v_pk_add_f32 v[20:21], v[26:27], 1.0 op_sel_hi:[1,0]
	v_mov_b32_e32 v24, v17
	v_mov_b32_e32 v25, v21
	v_mov_b32_e32 v26, v16
	v_mov_b32_e32 v27, v20
	v_pk_mul_f32 v[24:25], v[24:25], v[26:27]
	v_pk_mul_f32 v[6:7], v[14:15], v[6:7]
	v_mul_f32_e32 v26, v24, v25
	v_rcp_f32_e32 v26, v26
	v_pk_mul_f32 v[4:5], v[12:13], v[4:5]
	s_mov_b64 s[28:29], s[18:19]
	v_mul_f32_e32 v12, v25, v26
	v_mul_f32_e32 v14, v24, v26
	v_pk_mul_f32 v[14:15], v[20:21], v[14:15] op_sel_hi:[1,0]
	v_pk_mul_f32 v[12:13], v[16:17], v[12:13] op_sel_hi:[1,0]
	v_pk_mul_f32 v[10:11], v[10:11], v[14:15]
	v_pk_mul_f32 v[8:9], v[8:9], v[12:13]
	v_pk_mul_f32 v[10:11], v[10:11], v[2:3]
	v_pk_mul_f32 v[2:3], v[8:9], v[0:1]
	v_cvt_pk_bf16_f32 v0, v4, v5
	v_cvt_pk_bf16_f32 v1, v6, v7
	s_nop 0
	v_cvt_pk_bf16_f32 v2, v2, v3
	v_cvt_pk_bf16_f32 v3, v10, v11
	global_store_dwordx4 v[22:23], v[0:3], off
	s_cbranch_vccz .LBB0_192
	s_waitcnt vmcnt(0)
	s_cmpk_gt_u32 s37, 0xff
	s_cbranch_scc1 .LBB0_199
	s_barrier

; __device__ __forceinline__ f32x4 sigmoid4(f32x4 x) {
;     f32x4 d;
; #pragma unroll
;     for (int j = 0; j < 4; ++j) d[j] = 1.0f + __expf(-fmaxf(x[j], -20.0f));
;     const float p01 = d[0] * d[1], p23 = d[2] * d[3], r = __builtin_amdgcn_rcpf(p01 * p23), r01 = r * p23, r23 = r * p01;
;     return (f32x4){r01 * d[1], r01 * d[0], r23 * d[3], r23 * d[2]};
; }
;     __device__ __forceinline__ void operator()(const f32x4 (&acc)[2][2][4][2], const Unit& u, int wr, int wc, int fr, int fq) const {
;     ...
;                 for (int bj = 0; bj < 2; ++bj) { f32x4 v0 = acc[ai][bj][m][0] + bv[bj][0], v1 = acc[ai][bj][m][1] + bv[bj][1];
;                     if (act == 1) {
; #pragma unroll
;                         for (int j = 0; j < 1; ++j) { v0 = v0 * sigmoid4(v0); v1 = v1 * sigmoid4(v1); } }
.LBB0_434:
	s_andn2_b64 vcc, exec, s[0:1]
	s_cbranch_vccnz .LBB0_436
	v_max_f32_e32 v144, 0xc1a00000, v140
	v_max_f32_e32 v146, 0xc1a00000, v142
	v_mul_f32_e32 v144, 0xbfb8aa3b, v144
	v_mul_f32_e32 v146, 0xbfb8aa3b, v146
	v_exp_f32_e32 v145, v144
	v_exp_f32_e32 v147, v146
	v_max_f32_e32 v144, 0xc1a00000, v141
	v_max_f32_e32 v146, 0xc1a00000, v143
	v_mul_f32_e32 v144, 0xbfb8aa3b, v144
	v_mul_f32_e32 v146, 0xbfb8aa3b, v146
	v_exp_f32_e32 v144, v144
	v_exp_f32_e32 v146, v146
	v_pk_add_f32 v[144:145], v[144:145], 1.0 op_sel_hi:[1,0]
	v_pk_add_f32 v[146:147], v[146:147], 1.0 op_sel_hi:[1,0]
	v_mul_f32_e32 v148, v145, v144
	v_mul_f32_e32 v149, v147, v146
	s_nop 0
	v_mul_f32_e32 v150, v148, v149
	v_rcp_f32_e32 v151, v150
	s_nop 0
	v_mul_f32_e32 v150, v149, v151
	v_max_f32_e32 v149, 0xc1a00000, v136
	v_mul_f32_e32 v149, 0xbfb8aa3b, v149
	v_exp_f32_e32 v175, v149
	v_max_f32_e32 v149, 0xc1a00000, v137
	v_mul_f32_e32 v149, 0xbfb8aa3b, v149
	v_exp_f32_e32 v174, v149
	v_max_f32_e32 v149, 0xc1a00000, v138
	v_mul_f32_e32 v149, 0xbfb8aa3b, v149
	v_exp_f32_e32 v183, v149
	v_max_f32_e32 v149, 0xc1a00000, v139
	v_mul_f32_e32 v149, 0xbfb8aa3b, v149
	v_exp_f32_e32 v182, v149
	v_mul_f32_e32 v148, v148, v151
	v_pk_mul_f32 v[144:145], v[144:145], v[150:151] op_sel_hi:[1,0]
	v_pk_add_f32 v[150:151], v[174:175], 1.0 op_sel_hi:[1,0]
	v_pk_add_f32 v[174:175], v[182:183], 1.0 op_sel_hi:[1,0]
	v_mov_b32_e32 v182, v151
	v_mov_b32_e32 v183, v175
	v_mov_b32_e32 v184, v150
	v_mov_b32_e32 v185, v174
	v_pk_mul_f32 v[182:183], v[182:183], v[184:185]
	v_pk_mul_f32 v[144:145], v[140:141], v[144:145]
	v_mul_f32_e32 v149, v182, v183
	v_rcp_f32_e32 v149, v149
	s_nop 0
	v_pk_mul_f32 v[146:147], v[146:147], v[148:149] op_sel_hi:[1,0]
	s_nop 0
	v_pk_mul_f32 v[146:147], v[142:143], v[146:147]
	v_mul_f32_e32 v140, v183, v149
	v_mul_f32_e32 v142, v182, v149
	v_pk_mul_f32 v[140:141], v[150:151], v[140:141] op_sel_hi:[1,0]
	v_pk_mul_f32 v[142:143], v[174:175], v[142:143] op_sel_hi:[1,0]
	v_pk_mul_f32 v[148:149], v[136:137], v[140:141]
	v_pk_mul_f32 v[150:151], v[138:139], v[142:143]

; __device__ __forceinline__ f32x4 sigmoid4(f32x4 x) {
;     f32x4 d;
; #pragma unroll
;     for (int j = 0; j < 4; ++j) d[j] = 1.0f + __expf(-fmaxf(x[j], -20.0f));
;     const float p01 = d[0] * d[1], p23 = d[2] * d[3], r = __builtin_amdgcn_rcpf(p01 * p23), r01 = r * p23, r23 = r * p01;
;     return (f32x4){r01 * d[1], r01 * d[0], r23 * d[3], r23 * d[2]};
; }
;     __device__ __forceinline__ void operator()(const f32x4 (&acc)[2][2][4][2], const Unit& u, int wr, int wc, int fr, int fq) const {
;     ...
;                 for (int bj = 0; bj < 2; ++bj) { f32x4 v0 = acc[ai][bj][m][0] + bv[bj][0], v1 = acc[ai][bj][m][1] + bv[bj][1];
;                     if (act == 1) {
; #pragma unroll
;                         for (int j = 0; j < 1; ++j) { v0 = v0 * sigmoid4(v0); v1 = v1 * sigmoid4(v1); } }
.LBB0_440:
	s_andn2_b64 vcc, exec, s[0:1]
	s_cbranch_vccnz .LBB0_442
	v_max_f32_e32 v136, 0xc1a00000, v132
	v_max_f32_e32 v138, 0xc1a00000, v134
	v_mul_f32_e32 v136, 0xbfb8aa3b, v136
	v_mul_f32_e32 v138, 0xbfb8aa3b, v138
	v_exp_f32_e32 v137, v136
	v_exp_f32_e32 v139, v138
	v_max_f32_e32 v136, 0xc1a00000, v133
	v_max_f32_e32 v138, 0xc1a00000, v135
	v_mul_f32_e32 v136, 0xbfb8aa3b, v136
	v_mul_f32_e32 v138, 0xbfb8aa3b, v138
	v_exp_f32_e32 v136, v136
	v_exp_f32_e32 v138, v138
	v_pk_add_f32 v[136:137], v[136:137], 1.0 op_sel_hi:[1,0]
	v_pk_add_f32 v[138:139], v[138:139], 1.0 op_sel_hi:[1,0]
	v_mul_f32_e32 v140, v137, v136
	v_mul_f32_e32 v141, v139, v138
	s_nop 0
	v_mul_f32_e32 v142, v140, v141
	v_rcp_f32_e32 v143, v142
	s_nop 0
	v_mul_f32_e32 v142, v141, v143
	v_max_f32_e32 v141, 0xc1a00000, v128
	v_mul_f32_e32 v141, 0xbfb8aa3b, v141
	v_exp_f32_e32 v145, v141
	v_max_f32_e32 v141, 0xc1a00000, v129
	v_mul_f32_e32 v141, 0xbfb8aa3b, v141
	v_exp_f32_e32 v144, v141
	v_max_f32_e32 v141, 0xc1a00000, v130
	v_mul_f32_e32 v141, 0xbfb8aa3b, v141
	v_exp_f32_e32 v147, v141
	v_max_f32_e32 v141, 0xc1a00000, v131
	v_mul_f32_e32 v141, 0xbfb8aa3b, v141
	v_exp_f32_e32 v146, v141
	v_mul_f32_e32 v140, v140, v143
	v_pk_mul_f32 v[136:137], v[136:137], v[142:143] op_sel_hi:[1,0]
	v_pk_add_f32 v[142:143], v[144:145], 1.0 op_sel_hi:[1,0]
	v_pk_add_f32 v[144:145], v[146:147], 1.0 op_sel_hi:[1,0]
	v_mov_b32_e32 v146, v143
	v_mov_b32_e32 v147, v145
	v_mov_b32_e32 v148, v142
	v_mov_b32_e32 v149, v144
	v_pk_mul_f32 v[146:147], v[146:147], v[148:149]
	v_pk_mul_f32 v[136:137], v[132:133], v[136:137]
	v_mul_f32_e32 v141, v146, v147
	v_rcp_f32_e32 v141, v141
	s_nop 0
	v_pk_mul_f32 v[138:139], v[138:139], v[140:141] op_sel_hi:[1,0]
	s_nop 0
	v_pk_mul_f32 v[138:139], v[134:135], v[138:139]
	v_mul_f32_e32 v132, v147, v141
	v_mul_f32_e32 v134, v146, v141
	v_pk_mul_f32 v[132:133], v[142:143], v[132:133] op_sel_hi:[1,0]
	v_pk_mul_f32 v[134:135], v[144:145], v[134:135] op_sel_hi:[1,0]
	v_pk_mul_f32 v[140:141], v[128:129], v[132:133]
	v_pk_mul_f32 v[142:143], v[130:131], v[134:135]

; __device__ __forceinline__ f32x4 sigmoid4(f32x4 x) {
;     f32x4 d;
; #pragma unroll
;     for (int j = 0; j < 4; ++j) d[j] = 1.0f + __expf(-fmaxf(x[j], -20.0f));
;     const float p01 = d[0] * d[1], p23 = d[2] * d[3], r = __builtin_amdgcn_rcpf(p01 * p23), r01 = r * p23, r23 = r * p01;
;     return (f32x4){r01 * d[1], r01 * d[0], r23 * d[3], r23 * d[2]};
; }
;     __device__ __forceinline__ void operator()(const f32x4 (&acc)[2][2][4][2], const Unit& u, int wr, int wc, int fr, int fq) const {
;     ...
;                 for (int bj = 0; bj < 2; ++bj) { f32x4 v0 = acc[ai][bj][m][0] + bv[bj][0], v1 = acc[ai][bj][m][1] + bv[bj][1];
;                     if (act == 1) {
; #pragma unroll
;                         for (int j = 0; j < 1; ++j) { v0 = v0 * sigmoid4(v0); v1 = v1 * sigmoid4(v1); } }
.LBB0_446:
	s_andn2_b64 vcc, exec, s[0:1]
	s_cbranch_vccnz .LBB0_448
	v_max_f32_e32 v128, 0xc1a00000, v124
	v_max_f32_e32 v130, 0xc1a00000, v126
	v_mul_f32_e32 v128, 0xbfb8aa3b, v128
	v_mul_f32_e32 v130, 0xbfb8aa3b, v130
	v_exp_f32_e32 v129, v128
	v_exp_f32_e32 v131, v130
	v_max_f32_e32 v128, 0xc1a00000, v125
	v_max_f32_e32 v130, 0xc1a00000, v127
	v_mul_f32_e32 v128, 0xbfb8aa3b, v128
	v_mul_f32_e32 v130, 0xbfb8aa3b, v130
	v_exp_f32_e32 v128, v128
	v_exp_f32_e32 v130, v130
	v_pk_add_f32 v[128:129], v[128:129], 1.0 op_sel_hi:[1,0]
	v_pk_add_f32 v[130:131], v[130:131], 1.0 op_sel_hi:[1,0]
	v_mul_f32_e32 v132, v129, v128
	v_mul_f32_e32 v133, v131, v130
	s_nop 0
	v_mul_f32_e32 v134, v132, v133
	v_rcp_f32_e32 v135, v134
	s_nop 0
	v_mul_f32_e32 v134, v133, v135
	v_max_f32_e32 v133, 0xc1a00000, v120
	v_mul_f32_e32 v133, 0xbfb8aa3b, v133
	v_exp_f32_e32 v137, v133
	v_max_f32_e32 v133, 0xc1a00000, v121
	v_mul_f32_e32 v133, 0xbfb8aa3b, v133
	v_exp_f32_e32 v136, v133
	v_max_f32_e32 v133, 0xc1a00000, v122
	v_mul_f32_e32 v133, 0xbfb8aa3b, v133
	v_exp_f32_e32 v139, v133
	v_max_f32_e32 v133, 0xc1a00000, v123
	v_mul_f32_e32 v133, 0xbfb8aa3b, v133
	v_exp_f32_e32 v138, v133
	v_mul_f32_e32 v132, v132, v135
	v_pk_mul_f32 v[128:129], v[128:129], v[134:135] op_sel_hi:[1,0]
	v_pk_add_f32 v[134:135], v[136:137], 1.0 op_sel_hi:[1,0]
	v_pk_add_f32 v[136:137], v[138:139], 1.0 op_sel_hi:[1,0]
	v_mov_b32_e32 v138, v135
	v_mov_b32_e32 v139, v137
	v_mov_b32_e32 v140, v134
	v_mov_b32_e32 v141, v136
	v_pk_mul_f32 v[138:139], v[138:139], v[140:141]
	v_pk_mul_f32 v[128:129], v[124:125], v[128:129]
	v_mul_f32_e32 v133, v138, v139
	v_rcp_f32_e32 v133, v133
	s_nop 0
	v_pk_mul_f32 v[130:131], v[130:131], v[132:133] op_sel_hi:[1,0]
	s_nop 0
	v_pk_mul_f32 v[130:131], v[126:127], v[130:131]
	v_mul_f32_e32 v124, v139, v133
	v_mul_f32_e32 v126, v138, v133
	v_pk_mul_f32 v[124:125], v[134:135], v[124:125] op_sel_hi:[1,0]
	v_pk_mul_f32 v[126:127], v[136:137], v[126:127] op_sel_hi:[1,0]
	v_pk_mul_f32 v[132:133], v[120:121], v[124:125]
	v_pk_mul_f32 v[134:135], v[122:123], v[126:127]

; __device__ __forceinline__ f32x4 sigmoid4(f32x4 x) {
;     f32x4 d;
; #pragma unroll
;     for (int j = 0; j < 4; ++j) d[j] = 1.0f + __expf(-fmaxf(x[j], -20.0f));
;     const float p01 = d[0] * d[1], p23 = d[2] * d[3], r = __builtin_amdgcn_rcpf(p01 * p23), r01 = r * p23, r23 = r * p01;
;     return (f32x4){r01 * d[1], r01 * d[0], r23 * d[3], r23 * d[2]};
; }
;     __device__ __forceinline__ void operator()(const f32x4 (&acc)[2][2][4][2], const Unit& u, int wr, int wc, int fr, int fq) const {
;     ...
;                 for (int bj = 0; bj < 2; ++bj) { f32x4 v0 = acc[ai][bj][m][0] + bv[bj][0], v1 = acc[ai][bj][m][1] + bv[bj][1];
;                     if (act == 1) {
; #pragma unroll
;                         for (int j = 0; j < 1; ++j) { v0 = v0 * sigmoid4(v0); v1 = v1 * sigmoid4(v1); } }
.LBB0_452:
	s_andn2_b64 vcc, exec, s[0:1]
	s_cbranch_vccnz .LBB0_454
	v_max_f32_e32 v120, 0xc1a00000, v116
	v_max_f32_e32 v122, 0xc1a00000, v118
	v_mul_f32_e32 v120, 0xbfb8aa3b, v120
	v_mul_f32_e32 v122, 0xbfb8aa3b, v122
	v_exp_f32_e32 v121, v120
	v_exp_f32_e32 v123, v122
	v_max_f32_e32 v120, 0xc1a00000, v117
	v_max_f32_e32 v122, 0xc1a00000, v119
	v_mul_f32_e32 v120, 0xbfb8aa3b, v120
	v_mul_f32_e32 v122, 0xbfb8aa3b, v122
	v_exp_f32_e32 v120, v120
	v_exp_f32_e32 v122, v122
	v_pk_add_f32 v[120:121], v[120:121], 1.0 op_sel_hi:[1,0]
	v_pk_add_f32 v[122:123], v[122:123], 1.0 op_sel_hi:[1,0]
	v_mul_f32_e32 v124, v121, v120
	v_mul_f32_e32 v125, v123, v122
	s_nop 0
	v_mul_f32_e32 v126, v124, v125
	v_rcp_f32_e32 v127, v126
	s_nop 0
	v_mul_f32_e32 v126, v125, v127
	v_max_f32_e32 v125, 0xc1a00000, v112
	v_mul_f32_e32 v125, 0xbfb8aa3b, v125
	v_exp_f32_e32 v129, v125
	v_max_f32_e32 v125, 0xc1a00000, v113
	v_mul_f32_e32 v125, 0xbfb8aa3b, v125
	v_exp_f32_e32 v128, v125
	v_max_f32_e32 v125, 0xc1a00000, v114
	v_mul_f32_e32 v125, 0xbfb8aa3b, v125
	v_exp_f32_e32 v131, v125
	v_max_f32_e32 v125, 0xc1a00000, v115
	v_mul_f32_e32 v125, 0xbfb8aa3b, v125
	v_exp_f32_e32 v130, v125
	v_mul_f32_e32 v124, v124, v127
	v_pk_mul_f32 v[120:121], v[120:121], v[126:127] op_sel_hi:[1,0]
	v_pk_add_f32 v[126:127], v[128:129], 1.0 op_sel_hi:[1,0]
	v_pk_add_f32 v[128:129], v[130:131], 1.0 op_sel_hi:[1,0]
	v_mov_b32_e32 v130, v127
	v_mov_b32_e32 v131, v129
	v_mov_b32_e32 v132, v126
	v_mov_b32_e32 v133, v128
	v_pk_mul_f32 v[130:131], v[130:131], v[132:133]
	v_pk_mul_f32 v[120:121], v[116:117], v[120:121]
	v_mul_f32_e32 v125, v130, v131
	v_rcp_f32_e32 v125, v125
	s_nop 0
	v_pk_mul_f32 v[122:123], v[122:123], v[124:125] op_sel_hi:[1,0]
	s_nop 0
	v_pk_mul_f32 v[122:123], v[118:119], v[122:123]
	v_mul_f32_e32 v116, v131, v125
	v_mul_f32_e32 v118, v130, v125
	v_pk_mul_f32 v[116:117], v[126:127], v[116:117] op_sel_hi:[1,0]
	v_pk_mul_f32 v[118:119], v[128:129], v[118:119] op_sel_hi:[1,0]
	v_pk_mul_f32 v[124:125], v[112:113], v[116:117]
	v_pk_mul_f32 v[126:127], v[114:115], v[118:119]

; __device__ __forceinline__ f32x4 sigmoid4(f32x4 x) {
;     f32x4 d;
; #pragma unroll
;     for (int j = 0; j < 4; ++j) d[j] = 1.0f + __expf(-fmaxf(x[j], -20.0f));
;     const float p01 = d[0] * d[1], p23 = d[2] * d[3], r = __builtin_amdgcn_rcpf(p01 * p23), r01 = r * p23, r23 = r * p01;
;     return (f32x4){r01 * d[1], r01 * d[0], r23 * d[3], r23 * d[2]};
; }
;     __device__ __forceinline__ void operator()(const f32x4 (&acc)[2][2][4][2], const Unit& u, int wr, int wc, int fr, int fq) const {
;     ...
;                 for (int bj = 0; bj < 2; ++bj) { f32x4 v0 = acc[ai][bj][m][0] + bv[bj][0], v1 = acc[ai][bj][m][1] + bv[bj][1];
;                     if (act == 1) {
; #pragma unroll
;                         for (int j = 0; j < 1; ++j) { v0 = v0 * sigmoid4(v0); v1 = v1 * sigmoid4(v1); } }
.LBB0_458:
	s_andn2_b64 vcc, exec, s[0:1]
	s_cbranch_vccnz .LBB0_460
	v_max_f32_e32 v112, 0xc1a00000, v108
	v_max_f32_e32 v114, 0xc1a00000, v110
	v_mul_f32_e32 v112, 0xbfb8aa3b, v112
	v_mul_f32_e32 v114, 0xbfb8aa3b, v114
	v_exp_f32_e32 v113, v112
	v_exp_f32_e32 v115, v114
	v_max_f32_e32 v112, 0xc1a00000, v109
	v_max_f32_e32 v114, 0xc1a00000, v111
	v_mul_f32_e32 v112, 0xbfb8aa3b, v112
	v_mul_f32_e32 v114, 0xbfb8aa3b, v114
	v_exp_f32_e32 v112, v112
	v_exp_f32_e32 v114, v114
	v_pk_add_f32 v[112:113], v[112:113], 1.0 op_sel_hi:[1,0]
	v_pk_add_f32 v[114:115], v[114:115], 1.0 op_sel_hi:[1,0]
	v_mul_f32_e32 v116, v113, v112
	v_mul_f32_e32 v117, v115, v114
	s_nop 0
	v_mul_f32_e32 v118, v116, v117
	v_rcp_f32_e32 v119, v118
	s_nop 0
	v_mul_f32_e32 v118, v117, v119
	v_max_f32_e32 v117, 0xc1a00000, v104
	v_mul_f32_e32 v117, 0xbfb8aa3b, v117
	v_exp_f32_e32 v121, v117
	v_max_f32_e32 v117, 0xc1a00000, v105
	v_mul_f32_e32 v117, 0xbfb8aa3b, v117
	v_exp_f32_e32 v120, v117
	v_max_f32_e32 v117, 0xc1a00000, v106
	v_mul_f32_e32 v117, 0xbfb8aa3b, v117
	v_exp_f32_e32 v123, v117
	v_max_f32_e32 v117, 0xc1a00000, v107
	v_mul_f32_e32 v117, 0xbfb8aa3b, v117
	v_exp_f32_e32 v122, v117
	v_mul_f32_e32 v116, v116, v119
	v_pk_mul_f32 v[112:113], v[112:113], v[118:119] op_sel_hi:[1,0]
	v_pk_add_f32 v[118:119], v[120:121], 1.0 op_sel_hi:[1,0]
	v_pk_add_f32 v[120:121], v[122:123], 1.0 op_sel_hi:[1,0]
	v_mov_b32_e32 v122, v119
	v_mov_b32_e32 v123, v121
	v_mov_b32_e32 v124, v118
	v_mov_b32_e32 v125, v120
	v_pk_mul_f32 v[122:123], v[122:123], v[124:125]
	v_pk_mul_f32 v[112:113], v[108:109], v[112:113]
	v_mul_f32_e32 v117, v122, v123
	v_rcp_f32_e32 v117, v117
	s_nop 0
	v_pk_mul_f32 v[114:115], v[114:115], v[116:117] op_sel_hi:[1,0]
	s_nop 0
	v_pk_mul_f32 v[114:115], v[110:111], v[114:115]
	v_mul_f32_e32 v108, v123, v117
	v_mul_f32_e32 v110, v122, v117
	v_pk_mul_f32 v[108:109], v[118:119], v[108:109] op_sel_hi:[1,0]
	v_pk_mul_f32 v[110:111], v[120:121], v[110:111] op_sel_hi:[1,0]
	v_pk_mul_f32 v[116:117], v[104:105], v[108:109]
	v_pk_mul_f32 v[118:119], v[106:107], v[110:111]

; __device__ __forceinline__ f32x4 sigmoid4(f32x4 x) {
;     f32x4 d;
; #pragma unroll
;     for (int j = 0; j < 4; ++j) d[j] = 1.0f + __expf(-fmaxf(x[j], -20.0f));
;     const float p01 = d[0] * d[1], p23 = d[2] * d[3], r = __builtin_amdgcn_rcpf(p01 * p23), r01 = r * p23, r23 = r * p01;
;     return (f32x4){r01 * d[1], r01 * d[0], r23 * d[3], r23 * d[2]};
; }
;     __device__ __forceinline__ void operator()(const f32x4 (&acc)[2][2][4][2], const Unit& u, int wr, int wc, int fr, int fq) const {
;     ...
;                 for (int bj = 0; bj < 2; ++bj) { f32x4 v0 = acc[ai][bj][m][0] + bv[bj][0], v1 = acc[ai][bj][m][1] + bv[bj][1];
;                     if (act == 1) {
; #pragma unroll
;                         for (int j = 0; j < 1; ++j) { v0 = v0 * sigmoid4(v0); v1 = v1 * sigmoid4(v1); } }
.LBB0_464:
	s_andn2_b64 vcc, exec, s[0:1]
	s_cbranch_vccnz .LBB0_466
	v_max_f32_e32 v104, 0xc1a00000, v100
	v_max_f32_e32 v106, 0xc1a00000, v102
	v_mul_f32_e32 v104, 0xbfb8aa3b, v104
	v_mul_f32_e32 v106, 0xbfb8aa3b, v106
	v_exp_f32_e32 v105, v104
	v_exp_f32_e32 v107, v106
	v_max_f32_e32 v104, 0xc1a00000, v101
	v_max_f32_e32 v106, 0xc1a00000, v103
	v_mul_f32_e32 v104, 0xbfb8aa3b, v104
	v_mul_f32_e32 v106, 0xbfb8aa3b, v106
	v_exp_f32_e32 v104, v104
	v_exp_f32_e32 v106, v106
	v_pk_add_f32 v[104:105], v[104:105], 1.0 op_sel_hi:[1,0]
	v_pk_add_f32 v[106:107], v[106:107], 1.0 op_sel_hi:[1,0]
	v_mul_f32_e32 v108, v105, v104
	v_mul_f32_e32 v109, v107, v106
	s_nop 0
	v_mul_f32_e32 v110, v108, v109
	v_rcp_f32_e32 v111, v110
	s_nop 0
	v_mul_f32_e32 v110, v109, v111
	v_max_f32_e32 v109, 0xc1a00000, v96
	v_mul_f32_e32 v109, 0xbfb8aa3b, v109
	v_exp_f32_e32 v113, v109
	v_max_f32_e32 v109, 0xc1a00000, v97
	v_mul_f32_e32 v109, 0xbfb8aa3b, v109
	v_exp_f32_e32 v112, v109
	v_max_f32_e32 v109, 0xc1a00000, v98
	v_mul_f32_e32 v109, 0xbfb8aa3b, v109
	v_exp_f32_e32 v115, v109
	v_max_f32_e32 v109, 0xc1a00000, v99
	v_mul_f32_e32 v109, 0xbfb8aa3b, v109
	v_exp_f32_e32 v114, v109
	v_mul_f32_e32 v108, v108, v111
	v_pk_mul_f32 v[104:105], v[104:105], v[110:111] op_sel_hi:[1,0]
	v_pk_add_f32 v[110:111], v[112:113], 1.0 op_sel_hi:[1,0]
	v_pk_add_f32 v[112:113], v[114:115], 1.0 op_sel_hi:[1,0]
	v_mov_b32_e32 v114, v111
	v_mov_b32_e32 v115, v113
	v_mov_b32_e32 v116, v110
	v_mov_b32_e32 v117, v112
	v_pk_mul_f32 v[114:115], v[114:115], v[116:117]
	v_pk_mul_f32 v[104:105], v[100:101], v[104:105]
	v_mul_f32_e32 v109, v114, v115
	v_rcp_f32_e32 v109, v109
	s_nop 0
	v_pk_mul_f32 v[106:107], v[106:107], v[108:109] op_sel_hi:[1,0]
	s_nop 0
	v_pk_mul_f32 v[106:107], v[102:103], v[106:107]
	v_mul_f32_e32 v100, v115, v109
	v_mul_f32_e32 v102, v114, v109
	v_pk_mul_f32 v[100:101], v[110:111], v[100:101] op_sel_hi:[1,0]
	v_pk_mul_f32 v[102:103], v[112:113], v[102:103] op_sel_hi:[1,0]
	v_pk_mul_f32 v[108:109], v[96:97], v[100:101]
	v_pk_mul_f32 v[110:111], v[98:99], v[102:103]

; __device__ __forceinline__ f32x4 sigmoid4(f32x4 x) {
;     f32x4 d;
; #pragma unroll
;     for (int j = 0; j < 4; ++j) d[j] = 1.0f + __expf(-fmaxf(x[j], -20.0f));
;     const float p01 = d[0] * d[1], p23 = d[2] * d[3], r = __builtin_amdgcn_rcpf(p01 * p23), r01 = r * p23, r23 = r * p01;
;     return (f32x4){r01 * d[1], r01 * d[0], r23 * d[3], r23 * d[2]};
; }
;     __device__ __forceinline__ void operator()(const f32x4 (&acc)[2][2][4][2], const Unit& u, int wr, int wc, int fr, int fq) const {
;     ...
;                 for (int bj = 0; bj < 2; ++bj) { f32x4 v0 = acc[ai][bj][m][0] + bv[bj][0], v1 = acc[ai][bj][m][1] + bv[bj][1];
;                     if (act == 1) {
; #pragma unroll
;                         for (int j = 0; j < 1; ++j) { v0 = v0 * sigmoid4(v0); v1 = v1 * sigmoid4(v1); } }
.LBB0_470:
	s_andn2_b64 vcc, exec, s[0:1]
	s_cbranch_vccnz .LBB0_472
	v_max_f32_e32 v96, 0xc1a00000, v92
	v_max_f32_e32 v98, 0xc1a00000, v94
	v_mul_f32_e32 v96, 0xbfb8aa3b, v96
	v_mul_f32_e32 v98, 0xbfb8aa3b, v98
	v_exp_f32_e32 v97, v96
	v_exp_f32_e32 v99, v98
	v_max_f32_e32 v96, 0xc1a00000, v93
	v_max_f32_e32 v98, 0xc1a00000, v95
	v_mul_f32_e32 v96, 0xbfb8aa3b, v96
	v_mul_f32_e32 v98, 0xbfb8aa3b, v98
	v_exp_f32_e32 v96, v96
	v_exp_f32_e32 v98, v98
	v_pk_add_f32 v[96:97], v[96:97], 1.0 op_sel_hi:[1,0]
	v_pk_add_f32 v[98:99], v[98:99], 1.0 op_sel_hi:[1,0]
	v_mul_f32_e32 v100, v97, v96
	v_mul_f32_e32 v101, v99, v98
	s_nop 0
	v_mul_f32_e32 v102, v100, v101
	v_rcp_f32_e32 v103, v102
	s_nop 0
	v_mul_f32_e32 v102, v101, v103
	v_max_f32_e32 v101, 0xc1a00000, v88
	v_mul_f32_e32 v101, 0xbfb8aa3b, v101
	v_exp_f32_e32 v105, v101
	v_max_f32_e32 v101, 0xc1a00000, v89
	v_mul_f32_e32 v101, 0xbfb8aa3b, v101
	v_exp_f32_e32 v104, v101
	v_max_f32_e32 v101, 0xc1a00000, v90
	v_mul_f32_e32 v101, 0xbfb8aa3b, v101
	v_exp_f32_e32 v107, v101
	v_max_f32_e32 v101, 0xc1a00000, v91
	v_mul_f32_e32 v101, 0xbfb8aa3b, v101
	v_exp_f32_e32 v106, v101
	v_mul_f32_e32 v100, v100, v103
	v_pk_mul_f32 v[96:97], v[96:97], v[102:103] op_sel_hi:[1,0]
	v_pk_add_f32 v[102:103], v[104:105], 1.0 op_sel_hi:[1,0]
	v_pk_add_f32 v[104:105], v[106:107], 1.0 op_sel_hi:[1,0]
	v_mov_b32_e32 v106, v103
	v_mov_b32_e32 v107, v105
	v_mov_b32_e32 v108, v102
	v_mov_b32_e32 v109, v104
	v_pk_mul_f32 v[106:107], v[106:107], v[108:109]
	v_pk_mul_f32 v[96:97], v[92:93], v[96:97]
	v_mul_f32_e32 v101, v106, v107
	v_rcp_f32_e32 v101, v101
	s_nop 0
	v_pk_mul_f32 v[98:99], v[98:99], v[100:101] op_sel_hi:[1,0]
	s_nop 0
	v_pk_mul_f32 v[98:99], v[94:95], v[98:99]
	v_mul_f32_e32 v92, v107, v101
	v_mul_f32_e32 v94, v106, v101
	v_pk_mul_f32 v[92:93], v[102:103], v[92:93] op_sel_hi:[1,0]
	v_pk_mul_f32 v[94:95], v[104:105], v[94:95] op_sel_hi:[1,0]
	v_pk_mul_f32 v[100:101], v[88:89], v[92:93]
	v_pk_mul_f32 v[102:103], v[90:91], v[94:95]

; __device__ __forceinline__ f32x4 sigmoid4(f32x4 x) {
;     f32x4 d;
; #pragma unroll
;     for (int j = 0; j < 4; ++j) d[j] = 1.0f + __expf(-fmaxf(x[j], -20.0f));
;     const float p01 = d[0] * d[1], p23 = d[2] * d[3], r = __builtin_amdgcn_rcpf(p01 * p23), r01 = r * p23, r23 = r * p01;
;     return (f32x4){r01 * d[1], r01 * d[0], r23 * d[3], r23 * d[2]};
; }
;     __device__ __forceinline__ void operator()(const f32x4 (&acc)[2][2][4][2], const Unit& u, int wr, int wc, int fr, int fq) const {
;     ...
;                 for (int bj = 0; bj < 2; ++bj) { f32x4 v0 = acc[ai][bj][m][0] + bv[bj][0], v1 = acc[ai][bj][m][1] + bv[bj][1];
;                     if (act == 1) {
; #pragma unroll
;                         for (int j = 0; j < 1; ++j) { v0 = v0 * sigmoid4(v0); v1 = v1 * sigmoid4(v1); } }
.LBB0_476:
	s_andn2_b64 vcc, exec, s[0:1]
	s_cbranch_vccnz .LBB0_478
	v_max_f32_e32 v88, 0xc1a00000, v84
	v_max_f32_e32 v90, 0xc1a00000, v86
	v_mul_f32_e32 v88, 0xbfb8aa3b, v88
	v_mul_f32_e32 v90, 0xbfb8aa3b, v90
	v_exp_f32_e32 v89, v88
	v_exp_f32_e32 v91, v90
	v_max_f32_e32 v88, 0xc1a00000, v85
	v_max_f32_e32 v90, 0xc1a00000, v87
	v_mul_f32_e32 v88, 0xbfb8aa3b, v88
	v_mul_f32_e32 v90, 0xbfb8aa3b, v90
	v_exp_f32_e32 v88, v88
	v_exp_f32_e32 v90, v90
	v_pk_add_f32 v[88:89], v[88:89], 1.0 op_sel_hi:[1,0]
	v_pk_add_f32 v[90:91], v[90:91], 1.0 op_sel_hi:[1,0]
	v_mul_f32_e32 v92, v89, v88
	v_mul_f32_e32 v93, v91, v90
	s_nop 0
	v_mul_f32_e32 v94, v92, v93
	v_rcp_f32_e32 v95, v94
	s_nop 0
	v_mul_f32_e32 v94, v93, v95
	v_max_f32_e32 v93, 0xc1a00000, v80
	v_mul_f32_e32 v93, 0xbfb8aa3b, v93
	v_exp_f32_e32 v97, v93
	v_max_f32_e32 v93, 0xc1a00000, v81
	v_mul_f32_e32 v93, 0xbfb8aa3b, v93
	v_exp_f32_e32 v96, v93
	v_max_f32_e32 v93, 0xc1a00000, v82
	v_mul_f32_e32 v93, 0xbfb8aa3b, v93
	v_exp_f32_e32 v99, v93
	v_max_f32_e32 v93, 0xc1a00000, v83
	v_mul_f32_e32 v93, 0xbfb8aa3b, v93
	v_exp_f32_e32 v98, v93
	v_mul_f32_e32 v92, v92, v95
	v_pk_mul_f32 v[88:89], v[88:89], v[94:95] op_sel_hi:[1,0]
	v_pk_add_f32 v[94:95], v[96:97], 1.0 op_sel_hi:[1,0]
	v_pk_add_f32 v[96:97], v[98:99], 1.0 op_sel_hi:[1,0]
	v_mov_b32_e32 v98, v95
	v_mov_b32_e32 v99, v97
	v_mov_b32_e32 v100, v94
	v_mov_b32_e32 v101, v96
	v_pk_mul_f32 v[98:99], v[98:99], v[100:101]
	v_pk_mul_f32 v[88:89], v[84:85], v[88:89]
	v_mul_f32_e32 v93, v98, v99
	v_rcp_f32_e32 v93, v93
	s_nop 0
	v_pk_mul_f32 v[90:91], v[90:91], v[92:93] op_sel_hi:[1,0]
	s_nop 0
	v_pk_mul_f32 v[90:91], v[86:87], v[90:91]
	v_mul_f32_e32 v84, v99, v93
	v_mul_f32_e32 v86, v98, v93
	v_pk_mul_f32 v[84:85], v[94:95], v[84:85] op_sel_hi:[1,0]
	v_pk_mul_f32 v[86:87], v[96:97], v[86:87] op_sel_hi:[1,0]
	v_pk_mul_f32 v[92:93], v[80:81], v[84:85]
	v_pk_mul_f32 v[94:95], v[82:83], v[86:87]

; __device__ __forceinline__ f32x4 sigmoid4(f32x4 x) {
;     f32x4 d;
; #pragma unroll
;     for (int j = 0; j < 4; ++j) d[j] = 1.0f + __expf(-fmaxf(x[j], -20.0f));
;     const float p01 = d[0] * d[1], p23 = d[2] * d[3], r = __builtin_amdgcn_rcpf(p01 * p23), r01 = r * p23, r23 = r * p01;
;     return (f32x4){r01 * d[1], r01 * d[0], r23 * d[3], r23 * d[2]};
; }
;     __device__ __forceinline__ void operator()(const f32x4 (&acc)[2][2][4][2], const Unit& u, int wr, int wc, int fr, int fq) const {
;     ...
;                 for (int bj = 0; bj < 2; ++bj) { f32x4 v0 = acc[ai][bj][m][0] + bv[bj][0], v1 = acc[ai][bj][m][1] + bv[bj][1];
;                     if (act == 1) {
; #pragma unroll
;                         for (int j = 0; j < 1; ++j) { v0 = v0 * sigmoid4(v0); v1 = v1 * sigmoid4(v1); } }
.LBB0_482:
	s_andn2_b64 vcc, exec, s[0:1]
	s_cbranch_vccnz .LBB0_484
	v_max_f32_e32 v80, 0xc1a00000, v76
	v_max_f32_e32 v82, 0xc1a00000, v78
	v_mul_f32_e32 v80, 0xbfb8aa3b, v80
	v_mul_f32_e32 v82, 0xbfb8aa3b, v82
	v_exp_f32_e32 v81, v80
	v_exp_f32_e32 v83, v82
	v_max_f32_e32 v80, 0xc1a00000, v77
	v_max_f32_e32 v82, 0xc1a00000, v79
	v_mul_f32_e32 v80, 0xbfb8aa3b, v80
	v_mul_f32_e32 v82, 0xbfb8aa3b, v82
	v_exp_f32_e32 v80, v80
	v_exp_f32_e32 v82, v82
	v_pk_add_f32 v[80:81], v[80:81], 1.0 op_sel_hi:[1,0]
	v_pk_add_f32 v[82:83], v[82:83], 1.0 op_sel_hi:[1,0]
	v_mul_f32_e32 v84, v81, v80
	v_mul_f32_e32 v85, v83, v82
	s_nop 0
	v_mul_f32_e32 v86, v84, v85
	v_rcp_f32_e32 v87, v86
	s_nop 0
	v_mul_f32_e32 v86, v85, v87
	v_max_f32_e32 v85, 0xc1a00000, v72
	v_mul_f32_e32 v85, 0xbfb8aa3b, v85
	v_exp_f32_e32 v89, v85
	v_max_f32_e32 v85, 0xc1a00000, v73
	v_mul_f32_e32 v85, 0xbfb8aa3b, v85
	v_exp_f32_e32 v88, v85
	v_max_f32_e32 v85, 0xc1a00000, v74
	v_mul_f32_e32 v85, 0xbfb8aa3b, v85
	v_exp_f32_e32 v91, v85
	v_max_f32_e32 v85, 0xc1a00000, v75
	v_mul_f32_e32 v85, 0xbfb8aa3b, v85
	v_exp_f32_e32 v90, v85
	v_mul_f32_e32 v84, v84, v87
	v_pk_mul_f32 v[80:81], v[80:81], v[86:87] op_sel_hi:[1,0]
	v_pk_add_f32 v[86:87], v[88:89], 1.0 op_sel_hi:[1,0]
	v_pk_add_f32 v[88:89], v[90:91], 1.0 op_sel_hi:[1,0]
	v_mov_b32_e32 v90, v87
	v_mov_b32_e32 v91, v89
	v_mov_b32_e32 v92, v86
	v_mov_b32_e32 v93, v88
	v_pk_mul_f32 v[90:91], v[90:91], v[92:93]
	v_pk_mul_f32 v[80:81], v[76:77], v[80:81]
	v_mul_f32_e32 v85, v90, v91
	v_rcp_f32_e32 v85, v85
	s_nop 0
	v_pk_mul_f32 v[82:83], v[82:83], v[84:85] op_sel_hi:[1,0]
	s_nop 0
	v_pk_mul_f32 v[82:83], v[78:79], v[82:83]
	v_mul_f32_e32 v76, v91, v85
	v_mul_f32_e32 v78, v90, v85
	v_pk_mul_f32 v[76:77], v[86:87], v[76:77] op_sel_hi:[1,0]
	v_pk_mul_f32 v[78:79], v[88:89], v[78:79] op_sel_hi:[1,0]
	v_pk_mul_f32 v[84:85], v[72:73], v[76:77]
	v_pk_mul_f32 v[86:87], v[74:75], v[78:79]

; __device__ __forceinline__ f32x4 sigmoid4(f32x4 x) {
;     f32x4 d;
; #pragma unroll
;     for (int j = 0; j < 4; ++j) d[j] = 1.0f + __expf(-fmaxf(x[j], -20.0f));
;     const float p01 = d[0] * d[1], p23 = d[2] * d[3], r = __builtin_amdgcn_rcpf(p01 * p23), r01 = r * p23, r23 = r * p01;
;     return (f32x4){r01 * d[1], r01 * d[0], r23 * d[3], r23 * d[2]};
; }
;     __device__ __forceinline__ void operator()(const f32x4 (&acc)[2][2][4][2], const Unit& u, int wr, int wc, int fr, int fq) const {
;     ...
;                 for (int bj = 0; bj < 2; ++bj) { f32x4 v0 = acc[ai][bj][m][0] + bv[bj][0], v1 = acc[ai][bj][m][1] + bv[bj][1];
;                     if (act == 1) {
; #pragma unroll
;                         for (int j = 0; j < 1; ++j) { v0 = v0 * sigmoid4(v0); v1 = v1 * sigmoid4(v1); } }
.LBB0_488:
	s_andn2_b64 vcc, exec, s[0:1]
	s_cbranch_vccnz .LBB0_490
	v_max_f32_e32 v72, 0xc1a00000, v68
	v_max_f32_e32 v74, 0xc1a00000, v70
	v_mul_f32_e32 v72, 0xbfb8aa3b, v72
	v_mul_f32_e32 v74, 0xbfb8aa3b, v74
	v_exp_f32_e32 v73, v72
	v_exp_f32_e32 v75, v74
	v_max_f32_e32 v72, 0xc1a00000, v69
	v_max_f32_e32 v74, 0xc1a00000, v71
	v_mul_f32_e32 v72, 0xbfb8aa3b, v72
	v_mul_f32_e32 v74, 0xbfb8aa3b, v74
	v_exp_f32_e32 v72, v72
	v_exp_f32_e32 v74, v74
	v_pk_add_f32 v[72:73], v[72:73], 1.0 op_sel_hi:[1,0]
	v_pk_add_f32 v[74:75], v[74:75], 1.0 op_sel_hi:[1,0]
	v_mul_f32_e32 v76, v73, v72
	v_mul_f32_e32 v77, v75, v74
	s_nop 0
	v_mul_f32_e32 v78, v76, v77
	v_rcp_f32_e32 v79, v78
	s_nop 0
	v_mul_f32_e32 v78, v77, v79
	v_max_f32_e32 v77, 0xc1a00000, v64
	v_mul_f32_e32 v77, 0xbfb8aa3b, v77
	v_exp_f32_e32 v81, v77
	v_max_f32_e32 v77, 0xc1a00000, v65
	v_mul_f32_e32 v77, 0xbfb8aa3b, v77
	v_exp_f32_e32 v80, v77
	v_max_f32_e32 v77, 0xc1a00000, v66
	v_mul_f32_e32 v77, 0xbfb8aa3b, v77
	v_exp_f32_e32 v83, v77
	v_max_f32_e32 v77, 0xc1a00000, v67
	v_mul_f32_e32 v77, 0xbfb8aa3b, v77
	v_exp_f32_e32 v82, v77
	v_mul_f32_e32 v76, v76, v79
	v_pk_mul_f32 v[72:73], v[72:73], v[78:79] op_sel_hi:[1,0]
	v_pk_add_f32 v[78:79], v[80:81], 1.0 op_sel_hi:[1,0]
	v_pk_add_f32 v[80:81], v[82:83], 1.0 op_sel_hi:[1,0]
	v_mov_b32_e32 v82, v79
	v_mov_b32_e32 v83, v81
	v_mov_b32_e32 v84, v78
	v_mov_b32_e32 v85, v80
	v_pk_mul_f32 v[82:83], v[82:83], v[84:85]
	v_pk_mul_f32 v[72:73], v[68:69], v[72:73]
	v_mul_f32_e32 v77, v82, v83
	v_rcp_f32_e32 v77, v77
	s_nop 0
	v_pk_mul_f32 v[74:75], v[74:75], v[76:77] op_sel_hi:[1,0]
	s_nop 0
	v_pk_mul_f32 v[74:75], v[70:71], v[74:75]
	v_mul_f32_e32 v68, v83, v77
	v_mul_f32_e32 v70, v82, v77
	v_pk_mul_f32 v[68:69], v[78:79], v[68:69] op_sel_hi:[1,0]
	v_pk_mul_f32 v[70:71], v[80:81], v[70:71] op_sel_hi:[1,0]
	v_pk_mul_f32 v[76:77], v[64:65], v[68:69]
	v_pk_mul_f32 v[78:79], v[66:67], v[70:71]

; __device__ __forceinline__ f32x4 sigmoid4(f32x4 x) {
;     f32x4 d;
; #pragma unroll
;     for (int j = 0; j < 4; ++j) d[j] = 1.0f + __expf(-fmaxf(x[j], -20.0f));
;     const float p01 = d[0] * d[1], p23 = d[2] * d[3], r = __builtin_amdgcn_rcpf(p01 * p23), r01 = r * p23, r23 = r * p01;
;     return (f32x4){r01 * d[1], r01 * d[0], r23 * d[3], r23 * d[2]};
; }
;     __device__ __forceinline__ void operator()(const f32x4 (&acc)[2][2][4][2], const Unit& u, int wr, int wc, int fr, int fq) const {
;     ...
;                 for (int bj = 0; bj < 2; ++bj) { f32x4 v0 = acc[ai][bj][m][0] + bv[bj][0], v1 = acc[ai][bj][m][1] + bv[bj][1];
;                     if (act == 1) {
; #pragma unroll
;                         for (int j = 0; j < 1; ++j) { v0 = v0 * sigmoid4(v0); v1 = v1 * sigmoid4(v1); } }
.LBB0_494:
	s_andn2_b64 vcc, exec, s[0:1]
	s_cbranch_vccnz .LBB0_496
	v_max_f32_e32 v64, 0xc1a00000, v60
	v_max_f32_e32 v66, 0xc1a00000, v62
	v_mul_f32_e32 v64, 0xbfb8aa3b, v64
	v_mul_f32_e32 v66, 0xbfb8aa3b, v66
	v_exp_f32_e32 v65, v64
	v_exp_f32_e32 v67, v66
	v_max_f32_e32 v64, 0xc1a00000, v61
	v_max_f32_e32 v66, 0xc1a00000, v63
	v_mul_f32_e32 v64, 0xbfb8aa3b, v64
	v_mul_f32_e32 v66, 0xbfb8aa3b, v66
	v_exp_f32_e32 v64, v64
	v_exp_f32_e32 v66, v66
	v_pk_add_f32 v[64:65], v[64:65], 1.0 op_sel_hi:[1,0]
	v_pk_add_f32 v[66:67], v[66:67], 1.0 op_sel_hi:[1,0]
	v_mul_f32_e32 v68, v65, v64
	v_mul_f32_e32 v69, v67, v66
	s_nop 0
	v_mul_f32_e32 v70, v68, v69
	v_rcp_f32_e32 v71, v70
	s_nop 0
	v_mul_f32_e32 v70, v69, v71
	v_max_f32_e32 v69, 0xc1a00000, v56
	v_mul_f32_e32 v69, 0xbfb8aa3b, v69
	v_exp_f32_e32 v73, v69
	v_max_f32_e32 v69, 0xc1a00000, v57
	v_mul_f32_e32 v69, 0xbfb8aa3b, v69
	v_exp_f32_e32 v72, v69
	v_max_f32_e32 v69, 0xc1a00000, v58
	v_mul_f32_e32 v69, 0xbfb8aa3b, v69
	v_exp_f32_e32 v75, v69
	v_max_f32_e32 v69, 0xc1a00000, v59
	v_mul_f32_e32 v69, 0xbfb8aa3b, v69
	v_exp_f32_e32 v74, v69
	v_mul_f32_e32 v68, v68, v71
	v_pk_mul_f32 v[64:65], v[64:65], v[70:71] op_sel_hi:[1,0]
	v_pk_add_f32 v[70:71], v[72:73], 1.0 op_sel_hi:[1,0]
	v_pk_add_f32 v[72:73], v[74:75], 1.0 op_sel_hi:[1,0]
	v_mov_b32_e32 v74, v71
	v_mov_b32_e32 v75, v73
	v_mov_b32_e32 v76, v70
	v_mov_b32_e32 v77, v72
	v_pk_mul_f32 v[74:75], v[74:75], v[76:77]
	v_pk_mul_f32 v[64:65], v[60:61], v[64:65]
	v_mul_f32_e32 v69, v74, v75
	v_rcp_f32_e32 v69, v69
	s_nop 0
	v_pk_mul_f32 v[66:67], v[66:67], v[68:69] op_sel_hi:[1,0]
	s_nop 0
	v_pk_mul_f32 v[66:67], v[62:63], v[66:67]
	v_mul_f32_e32 v60, v75, v69
	v_mul_f32_e32 v62, v74, v69
	v_pk_mul_f32 v[60:61], v[70:71], v[60:61] op_sel_hi:[1,0]
	v_pk_mul_f32 v[62:63], v[72:73], v[62:63] op_sel_hi:[1,0]
	v_pk_mul_f32 v[68:69], v[56:57], v[60:61]
	v_pk_mul_f32 v[70:71], v[58:59], v[62:63]

; __device__ __forceinline__ f32x4 sigmoid4(f32x4 x) {
;     f32x4 d;
; #pragma unroll
;     for (int j = 0; j < 4; ++j) d[j] = 1.0f + __expf(-fmaxf(x[j], -20.0f));
;     const float p01 = d[0] * d[1], p23 = d[2] * d[3], r = __builtin_amdgcn_rcpf(p01 * p23), r01 = r * p23, r23 = r * p01;
;     return (f32x4){r01 * d[1], r01 * d[0], r23 * d[3], r23 * d[2]};
; }
;     __device__ __forceinline__ void operator()(const f32x4 (&acc)[2][2][4][2], const Unit& u, int wr, int wc, int fr, int fq) const {
;     ...
;                 for (int bj = 0; bj < 2; ++bj) { f32x4 v0 = acc[ai][bj][m][0] + bv[bj][0], v1 = acc[ai][bj][m][1] + bv[bj][1];
;                     if (act == 1) {
; #pragma unroll
;                         for (int j = 0; j < 1; ++j) { v0 = v0 * sigmoid4(v0); v1 = v1 * sigmoid4(v1); } }
.LBB0_500:
	s_andn2_b64 vcc, exec, s[0:1]
	s_cbranch_vccnz .LBB0_502
	v_max_f32_e32 v56, 0xc1a00000, v52
	v_max_f32_e32 v58, 0xc1a00000, v54
	v_mul_f32_e32 v56, 0xbfb8aa3b, v56
	v_mul_f32_e32 v58, 0xbfb8aa3b, v58
	v_exp_f32_e32 v57, v56
	v_exp_f32_e32 v59, v58
	v_max_f32_e32 v56, 0xc1a00000, v53
	v_max_f32_e32 v58, 0xc1a00000, v55
	v_mul_f32_e32 v56, 0xbfb8aa3b, v56
	v_mul_f32_e32 v58, 0xbfb8aa3b, v58
	v_exp_f32_e32 v56, v56
	v_exp_f32_e32 v58, v58
	v_pk_add_f32 v[56:57], v[56:57], 1.0 op_sel_hi:[1,0]
	v_pk_add_f32 v[58:59], v[58:59], 1.0 op_sel_hi:[1,0]
	v_mul_f32_e32 v60, v57, v56
	v_mul_f32_e32 v61, v59, v58
	s_nop 0
	v_mul_f32_e32 v62, v60, v61
	v_rcp_f32_e32 v63, v62
	s_nop 0
	v_mul_f32_e32 v62, v61, v63
	v_max_f32_e32 v61, 0xc1a00000, v48
	v_mul_f32_e32 v61, 0xbfb8aa3b, v61
	v_exp_f32_e32 v65, v61
	v_max_f32_e32 v61, 0xc1a00000, v49
	v_mul_f32_e32 v61, 0xbfb8aa3b, v61
	v_exp_f32_e32 v64, v61
	v_max_f32_e32 v61, 0xc1a00000, v50
	v_mul_f32_e32 v61, 0xbfb8aa3b, v61
	v_exp_f32_e32 v67, v61
	v_max_f32_e32 v61, 0xc1a00000, v51
	v_mul_f32_e32 v61, 0xbfb8aa3b, v61
	v_exp_f32_e32 v66, v61
	v_mul_f32_e32 v60, v60, v63
	v_pk_mul_f32 v[56:57], v[56:57], v[62:63] op_sel_hi:[1,0]
	v_pk_add_f32 v[62:63], v[64:65], 1.0 op_sel_hi:[1,0]
	v_pk_add_f32 v[64:65], v[66:67], 1.0 op_sel_hi:[1,0]
	v_mov_b32_e32 v66, v63
	v_mov_b32_e32 v67, v65
	v_mov_b32_e32 v68, v62
	v_mov_b32_e32 v69, v64
	v_pk_mul_f32 v[66:67], v[66:67], v[68:69]
	v_pk_mul_f32 v[56:57], v[52:53], v[56:57]
	v_mul_f32_e32 v61, v66, v67
	v_rcp_f32_e32 v61, v61
	s_nop 0
	v_pk_mul_f32 v[58:59], v[58:59], v[60:61] op_sel_hi:[1,0]
	s_nop 0
	v_pk_mul_f32 v[58:59], v[54:55], v[58:59]
	v_mul_f32_e32 v52, v67, v61
	v_mul_f32_e32 v54, v66, v61
	v_pk_mul_f32 v[52:53], v[62:63], v[52:53] op_sel_hi:[1,0]
	v_pk_mul_f32 v[54:55], v[64:65], v[54:55] op_sel_hi:[1,0]
	v_pk_mul_f32 v[60:61], v[48:49], v[52:53]
	v_pk_mul_f32 v[62:63], v[50:51], v[54:55]

; __device__ __forceinline__ f32x4 sigmoid4(f32x4 x) {
;     f32x4 d;
; #pragma unroll
;     for (int j = 0; j < 4; ++j) d[j] = 1.0f + __expf(-fmaxf(x[j], -20.0f));
;     const float p01 = d[0] * d[1], p23 = d[2] * d[3], r = __builtin_amdgcn_rcpf(p01 * p23), r01 = r * p23, r23 = r * p01;
;     return (f32x4){r01 * d[1], r01 * d[0], r23 * d[3], r23 * d[2]};
; }
;     __device__ __forceinline__ void operator()(const f32x4 (&acc)[2][2][4][2], const Unit& u, int wr, int wc, int fr, int fq) const {
;     ...
;                 for (int bj = 0; bj < 2; ++bj) { f32x4 v0 = acc[ai][bj][m][0] + bv[bj][0], v1 = acc[ai][bj][m][1] + bv[bj][1];
;                     if (act == 1) {
; #pragma unroll
;                         for (int j = 0; j < 1; ++j) { v0 = v0 * sigmoid4(v0); v1 = v1 * sigmoid4(v1); } }
.LBB0_506:
	s_andn2_b64 vcc, exec, s[0:1]
	s_cbranch_vccnz .LBB0_508
	v_max_f32_e32 v48, 0xc1a00000, v36
	v_max_f32_e32 v50, 0xc1a00000, v38
	v_mul_f32_e32 v48, 0xbfb8aa3b, v48
	v_mul_f32_e32 v50, 0xbfb8aa3b, v50
	v_exp_f32_e32 v49, v48
	v_exp_f32_e32 v51, v50
	v_max_f32_e32 v48, 0xc1a00000, v37
	v_max_f32_e32 v50, 0xc1a00000, v39
	v_mul_f32_e32 v48, 0xbfb8aa3b, v48
	v_mul_f32_e32 v50, 0xbfb8aa3b, v50
	v_exp_f32_e32 v48, v48
	v_exp_f32_e32 v50, v50
	v_pk_add_f32 v[48:49], v[48:49], 1.0 op_sel_hi:[1,0]
	v_pk_add_f32 v[50:51], v[50:51], 1.0 op_sel_hi:[1,0]
	v_mul_f32_e32 v52, v49, v48
	v_mul_f32_e32 v53, v51, v50
	s_nop 0
	v_mul_f32_e32 v54, v52, v53
	v_rcp_f32_e32 v55, v54
	s_nop 0
	v_mul_f32_e32 v54, v53, v55
	v_max_f32_e32 v53, 0xc1a00000, v32
	v_mul_f32_e32 v53, 0xbfb8aa3b, v53
	v_exp_f32_e32 v57, v53
	v_max_f32_e32 v53, 0xc1a00000, v33
	v_mul_f32_e32 v53, 0xbfb8aa3b, v53
	v_exp_f32_e32 v56, v53
	v_max_f32_e32 v53, 0xc1a00000, v34
	v_mul_f32_e32 v53, 0xbfb8aa3b, v53
	v_exp_f32_e32 v59, v53
	v_max_f32_e32 v53, 0xc1a00000, v35
	v_mul_f32_e32 v53, 0xbfb8aa3b, v53
	v_exp_f32_e32 v58, v53
	v_mul_f32_e32 v52, v52, v55
	v_pk_mul_f32 v[48:49], v[48:49], v[54:55] op_sel_hi:[1,0]
	v_pk_add_f32 v[54:55], v[56:57], 1.0 op_sel_hi:[1,0]
	v_pk_add_f32 v[56:57], v[58:59], 1.0 op_sel_hi:[1,0]
	v_mov_b32_e32 v58, v55
	v_mov_b32_e32 v59, v57
	v_mov_b32_e32 v60, v54
	v_mov_b32_e32 v61, v56
	v_pk_mul_f32 v[58:59], v[58:59], v[60:61]
	v_pk_mul_f32 v[48:49], v[36:37], v[48:49]
	v_mul_f32_e32 v53, v58, v59
	v_rcp_f32_e32 v53, v53
	s_nop 0
	v_pk_mul_f32 v[50:51], v[50:51], v[52:53] op_sel_hi:[1,0]
	s_nop 0
	v_pk_mul_f32 v[50:51], v[38:39], v[50:51]
	v_mul_f32_e32 v36, v59, v53
	v_mul_f32_e32 v38, v58, v53
	v_pk_mul_f32 v[36:37], v[54:55], v[36:37] op_sel_hi:[1,0]
	v_pk_mul_f32 v[38:39], v[56:57], v[38:39] op_sel_hi:[1,0]
	v_pk_mul_f32 v[52:53], v[32:33], v[36:37]
	v_pk_mul_f32 v[54:55], v[34:35], v[38:39]

; __device__ __forceinline__ f32x4 sigmoid4(f32x4 x) {
;     f32x4 d;
; #pragma unroll
;     for (int j = 0; j < 4; ++j) d[j] = 1.0f + __expf(-fmaxf(x[j], -20.0f));
;     const float p01 = d[0] * d[1], p23 = d[2] * d[3], r = __builtin_amdgcn_rcpf(p01 * p23), r01 = r * p23, r23 = r * p01;
;     return (f32x4){r01 * d[1], r01 * d[0], r23 * d[3], r23 * d[2]};
; }
;     __device__ __forceinline__ void operator()(const f32x4 (&acc)[2][2][4][2], const Unit& u, int wr, int wc, int fr, int fq) const {
;     ...
;                 for (int bj = 0; bj < 2; ++bj) { f32x4 v0 = acc[ai][bj][m][0] + bv[bj][0], v1 = acc[ai][bj][m][1] + bv[bj][1];
;                     if (act == 1) {
; #pragma unroll
;                         for (int j = 0; j < 1; ++j) { v0 = v0 * sigmoid4(v0); v1 = v1 * sigmoid4(v1); } }
.LBB0_512:
	s_andn2_b64 vcc, exec, s[0:1]
	s_cbranch_vccnz .LBB0_514
	v_max_f32_e32 v32, 0xc1a00000, v20
	v_max_f32_e32 v34, 0xc1a00000, v22
	v_mul_f32_e32 v32, 0xbfb8aa3b, v32
	v_mul_f32_e32 v34, 0xbfb8aa3b, v34
	v_exp_f32_e32 v33, v32
	v_exp_f32_e32 v35, v34
	v_max_f32_e32 v32, 0xc1a00000, v21
	v_max_f32_e32 v34, 0xc1a00000, v23
	v_mul_f32_e32 v32, 0xbfb8aa3b, v32
	v_mul_f32_e32 v34, 0xbfb8aa3b, v34
	v_exp_f32_e32 v32, v32
	v_exp_f32_e32 v34, v34
	v_pk_add_f32 v[32:33], v[32:33], 1.0 op_sel_hi:[1,0]
	v_pk_add_f32 v[34:35], v[34:35], 1.0 op_sel_hi:[1,0]
	v_mul_f32_e32 v36, v33, v32
	v_mul_f32_e32 v37, v35, v34
	s_nop 0
	v_mul_f32_e32 v38, v36, v37
	v_rcp_f32_e32 v39, v38
	s_nop 0
	v_mul_f32_e32 v38, v37, v39
	v_max_f32_e32 v37, 0xc1a00000, v16
	v_mul_f32_e32 v37, 0xbfb8aa3b, v37
	v_exp_f32_e32 v49, v37
	v_max_f32_e32 v37, 0xc1a00000, v17
	v_mul_f32_e32 v37, 0xbfb8aa3b, v37
	v_exp_f32_e32 v48, v37
	v_max_f32_e32 v37, 0xc1a00000, v18
	v_mul_f32_e32 v37, 0xbfb8aa3b, v37
	v_exp_f32_e32 v51, v37
	v_max_f32_e32 v37, 0xc1a00000, v19
	v_mul_f32_e32 v37, 0xbfb8aa3b, v37
	v_exp_f32_e32 v50, v37
	v_mul_f32_e32 v36, v36, v39
	v_pk_mul_f32 v[32:33], v[32:33], v[38:39] op_sel_hi:[1,0]
	v_pk_add_f32 v[38:39], v[48:49], 1.0 op_sel_hi:[1,0]
	v_pk_add_f32 v[48:49], v[50:51], 1.0 op_sel_hi:[1,0]
	v_mov_b32_e32 v50, v39
	v_mov_b32_e32 v51, v49
	v_mov_b32_e32 v52, v38
	v_mov_b32_e32 v53, v48
	v_pk_mul_f32 v[50:51], v[50:51], v[52:53]
	v_pk_mul_f32 v[32:33], v[20:21], v[32:33]
	v_mul_f32_e32 v37, v50, v51
	v_rcp_f32_e32 v37, v37
	s_nop 0
	v_pk_mul_f32 v[34:35], v[34:35], v[36:37] op_sel_hi:[1,0]
	s_nop 0
	v_pk_mul_f32 v[34:35], v[22:23], v[34:35]
	v_mul_f32_e32 v20, v51, v37
	v_mul_f32_e32 v22, v50, v37
	v_pk_mul_f32 v[20:21], v[38:39], v[20:21] op_sel_hi:[1,0]
	v_pk_mul_f32 v[22:23], v[48:49], v[22:23] op_sel_hi:[1,0]
	v_pk_mul_f32 v[36:37], v[16:17], v[20:21]
	v_pk_mul_f32 v[38:39], v[18:19], v[22:23]

; __device__ __forceinline__ f32x4 sigmoid4(f32x4 x) {
;     f32x4 d;
; #pragma unroll
;     for (int j = 0; j < 4; ++j) d[j] = 1.0f + __expf(-fmaxf(x[j], -20.0f));
;     const float p01 = d[0] * d[1], p23 = d[2] * d[3], r = __builtin_amdgcn_rcpf(p01 * p23), r01 = r * p23, r23 = r * p01;
;     return (f32x4){r01 * d[1], r01 * d[0], r23 * d[3], r23 * d[2]};
; }
;     __device__ __forceinline__ void operator()(const f32x4 (&acc)[2][2][4][2], const Unit& u, int wr, int wc, int fr, int fq) const {
;     ...
;                 for (int bj = 0; bj < 2; ++bj) { f32x4 v0 = acc[ai][bj][m][0] + bv[bj][0], v1 = acc[ai][bj][m][1] + bv[bj][1];
;                     if (act == 1) {
; #pragma unroll
;                         for (int j = 0; j < 1; ++j) { v0 = v0 * sigmoid4(v0); v1 = v1 * sigmoid4(v1); } }
.LBB0_518:
	s_andn2_b64 vcc, exec, s[0:1]
	s_cbranch_vccnz .LBB0_520
	v_max_f32_e32 v16, 0xc1a00000, v12
	v_max_f32_e32 v18, 0xc1a00000, v14
	v_mul_f32_e32 v16, 0xbfb8aa3b, v16
	v_mul_f32_e32 v18, 0xbfb8aa3b, v18
	v_exp_f32_e32 v17, v16
	v_exp_f32_e32 v19, v18
	v_max_f32_e32 v16, 0xc1a00000, v13
	v_max_f32_e32 v18, 0xc1a00000, v15
	v_mul_f32_e32 v16, 0xbfb8aa3b, v16
	v_mul_f32_e32 v18, 0xbfb8aa3b, v18
	v_exp_f32_e32 v16, v16
	v_exp_f32_e32 v18, v18
	v_pk_add_f32 v[16:17], v[16:17], 1.0 op_sel_hi:[1,0]
	v_pk_add_f32 v[18:19], v[18:19], 1.0 op_sel_hi:[1,0]
	v_mul_f32_e32 v20, v17, v16
	v_mul_f32_e32 v21, v19, v18
	s_nop 0
	v_mul_f32_e32 v22, v20, v21
	v_rcp_f32_e32 v23, v22
	s_nop 0
	v_mul_f32_e32 v22, v21, v23
	v_max_f32_e32 v21, 0xc1a00000, v8
	v_mul_f32_e32 v21, 0xbfb8aa3b, v21
	v_exp_f32_e32 v33, v21
	v_max_f32_e32 v21, 0xc1a00000, v9
	v_mul_f32_e32 v21, 0xbfb8aa3b, v21
	v_exp_f32_e32 v32, v21
	v_max_f32_e32 v21, 0xc1a00000, v10
	v_mul_f32_e32 v21, 0xbfb8aa3b, v21
	v_exp_f32_e32 v35, v21
	v_max_f32_e32 v21, 0xc1a00000, v11
	v_mul_f32_e32 v21, 0xbfb8aa3b, v21
	v_exp_f32_e32 v34, v21
	v_mul_f32_e32 v20, v20, v23
	v_pk_mul_f32 v[16:17], v[16:17], v[22:23] op_sel_hi:[1,0]
	v_pk_add_f32 v[22:23], v[32:33], 1.0 op_sel_hi:[1,0]
	v_pk_add_f32 v[32:33], v[34:35], 1.0 op_sel_hi:[1,0]
	v_mov_b32_e32 v34, v23
	v_mov_b32_e32 v35, v33
	v_mov_b32_e32 v36, v22
	v_mov_b32_e32 v37, v32
	v_pk_mul_f32 v[34:35], v[34:35], v[36:37]
	v_pk_mul_f32 v[16:17], v[12:13], v[16:17]
	v_mul_f32_e32 v21, v34, v35
	v_rcp_f32_e32 v21, v21
	s_nop 0
	v_pk_mul_f32 v[18:19], v[18:19], v[20:21] op_sel_hi:[1,0]
	s_nop 0
	v_pk_mul_f32 v[18:19], v[14:15], v[18:19]
	v_mul_f32_e32 v12, v35, v21
	v_mul_f32_e32 v14, v34, v21
	v_pk_mul_f32 v[12:13], v[22:23], v[12:13] op_sel_hi:[1,0]
	v_pk_mul_f32 v[14:15], v[32:33], v[14:15] op_sel_hi:[1,0]
	v_pk_mul_f32 v[20:21], v[8:9], v[12:13]
	v_pk_mul_f32 v[22:23], v[10:11], v[14:15]

; __device__ __forceinline__ f32x4 sigmoid4(f32x4 x) {
;     f32x4 d;
; #pragma unroll
;     for (int j = 0; j < 4; ++j) d[j] = 1.0f + __expf(-fmaxf(x[j], -20.0f));
;     const float p01 = d[0] * d[1], p23 = d[2] * d[3], r = __builtin_amdgcn_rcpf(p01 * p23), r01 = r * p23, r23 = r * p01;
;     return (f32x4){r01 * d[1], r01 * d[0], r23 * d[3], r23 * d[2]};
; }
;     __device__ __forceinline__ void operator()(const f32x4 (&acc)[2][2][4][2], const Unit& u, int wr, int wc, int fr, int fq) const {
;     ...
;                 for (int bj = 0; bj < 2; ++bj) { f32x4 v0 = acc[ai][bj][m][0] + bv[bj][0], v1 = acc[ai][bj][m][1] + bv[bj][1];
;                     if (act == 1) {
; #pragma unroll
;                         for (int j = 0; j < 1; ++j) { v0 = v0 * sigmoid4(v0); v1 = v1 * sigmoid4(v1); } }
.LBB0_524:
	s_andn2_b64 vcc, exec, s[0:1]
	s_cbranch_vccnz .LBB0_408
	v_max_f32_e32 v8, 0xc1a00000, v4
	v_max_f32_e32 v10, 0xc1a00000, v6
	v_mul_f32_e32 v8, 0xbfb8aa3b, v8
	v_mul_f32_e32 v10, 0xbfb8aa3b, v10
	v_exp_f32_e32 v9, v8
	v_exp_f32_e32 v11, v10
	v_max_f32_e32 v8, 0xc1a00000, v5
	v_max_f32_e32 v10, 0xc1a00000, v7
	v_mul_f32_e32 v8, 0xbfb8aa3b, v8
	v_mul_f32_e32 v10, 0xbfb8aa3b, v10
	v_exp_f32_e32 v8, v8
	v_exp_f32_e32 v10, v10
	v_pk_add_f32 v[8:9], v[8:9], 1.0 op_sel_hi:[1,0]
	v_pk_add_f32 v[10:11], v[10:11], 1.0 op_sel_hi:[1,0]
	v_mul_f32_e32 v12, v9, v8
	v_mul_f32_e32 v13, v11, v10
	s_nop 0
	v_mul_f32_e32 v14, v12, v13
	v_rcp_f32_e32 v15, v14
	s_nop 0
	v_mul_f32_e32 v14, v13, v15
	v_max_f32_e32 v13, 0xc1a00000, v0
	v_mul_f32_e32 v13, 0xbfb8aa3b, v13
	v_exp_f32_e32 v17, v13
	v_max_f32_e32 v13, 0xc1a00000, v1
	v_mul_f32_e32 v13, 0xbfb8aa3b, v13
	v_exp_f32_e32 v16, v13
	v_max_f32_e32 v13, 0xc1a00000, v2
	v_mul_f32_e32 v13, 0xbfb8aa3b, v13
	v_exp_f32_e32 v19, v13
	v_max_f32_e32 v13, 0xc1a00000, v3
	v_mul_f32_e32 v13, 0xbfb8aa3b, v13
	v_exp_f32_e32 v18, v13
	v_mul_f32_e32 v12, v12, v15
	v_pk_mul_f32 v[8:9], v[8:9], v[14:15] op_sel_hi:[1,0]
	v_pk_add_f32 v[14:15], v[16:17], 1.0 op_sel_hi:[1,0]
	v_pk_add_f32 v[16:17], v[18:19], 1.0 op_sel_hi:[1,0]
	v_mov_b32_e32 v18, v15
	v_mov_b32_e32 v19, v17
	v_mov_b32_e32 v20, v14
	v_mov_b32_e32 v21, v16
	v_pk_mul_f32 v[18:19], v[18:19], v[20:21]
	v_pk_mul_f32 v[8:9], v[4:5], v[8:9]
	v_mul_f32_e32 v13, v18, v19
	v_rcp_f32_e32 v13, v13
	s_nop 0
	v_pk_mul_f32 v[10:11], v[10:11], v[12:13] op_sel_hi:[1,0]
	s_nop 0
	v_pk_mul_f32 v[10:11], v[6:7], v[10:11]
	v_mul_f32_e32 v4, v19, v13
	v_mul_f32_e32 v6, v18, v13
	v_pk_mul_f32 v[4:5], v[14:15], v[4:5] op_sel_hi:[1,0]
	v_pk_mul_f32 v[6:7], v[16:17], v[6:7] op_sel_hi:[1,0]
	v_pk_mul_f32 v[12:13], v[0:1], v[4:5]
	v_pk_mul_f32 v[14:15], v[2:3], v[6:7]
	s_branch .LBB0_408

; #define PG8_STAGE(bufoff, gbase, voff) do { _Pragma("unroll") for (int _i = 0; _i < 2; ++_i) \
;         __builtin_amdgcn_global_load_lds((const unsigned*)((const char*)(gbase) + (voff)[_i]), (PG8_LAS unsigned*)(lds + (bufoff) + ldsw + _i * 8192), 16, 0, 0); } while (0)
; #define PG8_LDA(dst, b, h) do { _Pragma("unroll") for (int m = 0; m < 4; ++m) _Pragma("unroll") for (int k = 0; k < 2; ++k) dst[m][k] = *(const PG8_LAS bf16x8*)(lds + PG8_SA(b, h) + aoff + m * 2048 + k * 1024); } while (0)
; #define PG8_WAIT_V(n) asm volatile("s_waitcnt vmcnt(" #n ")" ::: "memory")
; template <class Epi, class Sched>
; __device__ __forceinline__ void gemm_phase(PG8_LAS unsigned char* lds, const Gemm g, const Sched& S, const Epi& E) {
;     ...
;         for (int t = 0; t < nt; t += 2) {
;             const bool last = (t == nt - 2);
;             const char* a1 = cA + (size_t)(t + 1) * kstep;
;             const char* a2 = last ? nA : cA + (size_t)(t + 2) * kstep; const char* b2 = last ? nB : cB + (size_t)(t + 2) * kstep;
;             const char* a3 = a2 + kstep; const char* b3 = b2 + kstep;
;             if (last && has_next) S.a_ready(nxt);
;             PG8_LDB(B0, 0, 0); PG8_SCHED; PG8_LDA(At, 0, 0); PG8_STAGE(PG8_SA(1, 1), a1 + hstep, voffA);
;             PG8_WAIT_L(8); PG8_BAR; PG8_WAIT_L(0); PG8_MMA(0, 0, At, B0); PG8_BAR; PG8_SCHED;
;             PG8_LDB(B1, 0, 1); PG8_STAGE(PG8_SB(0, 0), b2, voffB);
;             PG8_BAR; PG8_WAIT_L(0); PG8_MMA(0, 1, At, B1); PG8_BAR;
;             PG8_LDA(At, 0, 1); PG8_STAGE(PG8_SA(0, 0), a2, voffA);
;             PG8_BAR; PG8_WAIT_L(0); PG8_MMA(1, 0, At, B0); PG8_BAR; PG8_SCHED;
;             PG8_STAGE(PG8_SB(0, 1), b2 + hstep, voffB);
;             PG8_WAIT_V(6); PG8_BAR; PG8_MMA(1, 1, At, B1); PG8_BAR;
;             PG8_LDB(B0, 1, 0); PG8_SCHED; PG8_LDA(At, 1, 0); PG8_STAGE(PG8_SA(0, 1), a2 + hstep, voffA);
;             PG8_WAIT_L(8); PG8_BAR; PG8_WAIT_L(0); PG8_MMA(0, 0, At, B0); PG8_BAR; PG8_SCHED;
;             PG8_LDB(B1, 1, 1); PG8_STAGE(PG8_SB(1, 0), b3, voffB);
;             PG8_BAR; PG8_WAIT_L(0); PG8_MMA(0, 1, At, B1); PG8_BAR;
;             PG8_LDA(At, 1, 1); PG8_STAGE(PG8_SA(1, 0), a3, voffA);
;             PG8_BAR; PG8_WAIT_L(0); PG8_MMA(1, 0, At, B0); PG8_BAR; PG8_SCHED;
;             PG8_STAGE(PG8_SB(1, 1), b3 + hstep, voffB);
;             PG8_WAIT_V(6); PG8_BAR; PG8_MMA(1, 1, At, B1); PG8_BAR;
.LBB0_1202:
	ds_read_b128 v[144:147], v151
	ds_read_b128 v[154:157], v151 offset:1024
	ds_read_b128 v[158:161], v151 offset:2048
	ds_read_b128 v[162:165], v151 offset:3072
	s_add_u32 s18, s16, 0xfffc0080
	s_addc_u32 s19, s17, -1
	s_cmp_eq_u32 s46, 12
	s_cselect_b32 s21, s9, s19
	s_cselect_b32 s20, s42, s18
	s_cselect_b32 s19, s7, s45
	s_cselect_b32 s18, s43, s44
	s_add_i32 m0, s15, 0xc000
	ds_read_b128 v[166:169], v152
	ds_read_b128 v[170:173], v152 offset:1024
	ds_read_b128 v[182:185], v152 offset:2048
	ds_read_b128 v[190:193], v152 offset:3072
	ds_read_b128 v[194:197], v152 offset:4096
	ds_read_b128 v[198:201], v152 offset:5120
	ds_read_b128 v[202:205], v152 offset:6144
	ds_read_b128 v[206:209], v152 offset:7168
	global_load_lds_dwordx4 v136, s[16:17]
	s_nop 1
	s_add_i32 m0, s15, 0xe000
	s_nop 0
	global_load_lds_dwordx4 v138, s[16:17]
	s_waitcnt lgkmcnt(8)
	ds_read_b128 v[210:213], v153
	ds_read_b128 v[214:217], v153 offset:1024
	ds_read_b128 v[218:221], v153 offset:2048
	ds_read_b128 v[222:225], v153 offset:3072
	s_waitcnt vmcnt(8) lgkmcnt(0)
	s_barrier
	v_mfma_f32_16x16x32_bf16 v[124:127], v[144:147], v[166:169], v[124:127]
	v_mfma_f32_16x16x32_bf16 v[120:123], v[158:161], v[166:169], v[120:123]
	v_mfma_f32_16x16x32_bf16 v[108:111], v[144:147], v[182:185], v[108:111]
	v_mfma_f32_16x16x32_bf16 v[104:107], v[158:161], v[182:185], v[104:107]
	v_mfma_f32_16x16x32_bf16 v[92:95], v[144:147], v[194:197], v[92:95]
	v_mfma_f32_16x16x32_bf16 v[88:91], v[158:161], v[194:197], v[88:91]
	v_mfma_f32_16x16x32_bf16 v[76:79], v[144:147], v[202:205], v[76:79]
	v_mfma_f32_16x16x32_bf16 v[72:75], v[158:161], v[202:205], v[72:75]
	v_mfma_f32_16x16x32_bf16 v[124:127], v[154:157], v[170:173], v[124:127]
	v_mfma_f32_16x16x32_bf16 v[120:123], v[162:165], v[170:173], v[120:123]
	v_mfma_f32_16x16x32_bf16 v[108:111], v[154:157], v[190:193], v[108:111]
	v_mfma_f32_16x16x32_bf16 v[104:107], v[162:165], v[190:193], v[104:107]
	v_mfma_f32_16x16x32_bf16 v[92:95], v[154:157], v[198:201], v[92:95]
	v_mfma_f32_16x16x32_bf16 v[88:91], v[162:165], v[198:201], v[88:91]
	v_mfma_f32_16x16x32_bf16 v[76:79], v[154:157], v[206:209], v[76:79]
	v_mfma_f32_16x16x32_bf16 v[72:75], v[162:165], v[206:209], v[72:75]
	v_mfma_f32_16x16x32_bf16 v[116:119], v[210:213], v[166:169], v[116:119]
	v_mfma_f32_16x16x32_bf16 v[112:115], v[218:221], v[166:169], v[112:115]
	v_mfma_f32_16x16x32_bf16 v[100:103], v[210:213], v[182:185], v[100:103]
	v_mfma_f32_16x16x32_bf16 v[96:99], v[218:221], v[182:185], v[96:99]
	v_mfma_f32_16x16x32_bf16 v[84:87], v[210:213], v[194:197], v[84:87]
	v_mfma_f32_16x16x32_bf16 v[80:83], v[218:221], v[194:197], v[80:83]
	v_mfma_f32_16x16x32_bf16 v[68:71], v[210:213], v[202:205], v[68:71]
	v_mfma_f32_16x16x32_bf16 v[64:67], v[218:221], v[202:205], v[64:67]
	v_mfma_f32_16x16x32_bf16 v[116:119], v[214:217], v[170:173], v[116:119]
	v_mfma_f32_16x16x32_bf16 v[112:115], v[222:225], v[170:173], v[112:115]
	v_mfma_f32_16x16x32_bf16 v[100:103], v[214:217], v[190:193], v[100:103]
	v_mfma_f32_16x16x32_bf16 v[96:99], v[222:225], v[190:193], v[96:99]
	v_mfma_f32_16x16x32_bf16 v[84:87], v[214:217], v[198:201], v[84:87]
	v_mfma_f32_16x16x32_bf16 v[80:83], v[222:225], v[198:201], v[80:83]
	v_mfma_f32_16x16x32_bf16 v[68:71], v[214:217], v[206:209], v[68:71]
	v_mfma_f32_16x16x32_bf16 v[64:67], v[222:225], v[206:209], v[64:67]
	s_barrier
	ds_read_b128 v[166:169], v152 offset:16384
	ds_read_b128 v[170:173], v152 offset:17408
	ds_read_b128 v[182:185], v152 offset:18432
	ds_read_b128 v[190:193], v152 offset:19456
	ds_read_b128 v[194:197], v152 offset:20480
	ds_read_b128 v[198:201], v152 offset:21504
	ds_read_b128 v[202:205], v152 offset:22528
	ds_read_b128 v[206:209], v152 offset:23552
	s_add_i32 s47, s38, s26
	s_add_u32 s98, s18, s4
	s_addc_u32 s99, s19, s5
	s_mov_b32 m0, s47
	s_nop 0
	global_load_lds_dwordx4 v132, s[18:19]
	s_nop 1
	s_add_i32 m0, s47, 0x2000
	s_nop 0
	global_load_lds_dwordx4 v128, s[18:19]
	s_nop 1
	s_mov_b32 m0, s15
	s_add_u32 s100, s20, s4
	s_addc_u32 s101, s21, s5
	global_load_lds_dwordx4 v134, s[20:21]
	s_nop 1
	s_mov_b32 m0, s29
	s_nop 0
	global_load_lds_dwordx4 v130, s[20:21]
	s_add_u32 s48, s18, 0x40000
	s_addc_u32 s49, s19, 0
	s_add_i32 s47, s39, s26
	s_mov_b32 m0, s47
	s_nop 0
	global_load_lds_dwordx4 v132, s[48:49]
	s_nop 1
	s_add_i32 m0, s47, 0x2000
	s_nop 0
	global_load_lds_dwordx4 v128, s[48:49]
	s_waitcnt vmcnt(8) lgkmcnt(0)
	s_barrier
	v_mfma_f32_16x16x32_bf16 v[60:63], v[144:147], v[166:169], v[60:63]
	v_mfma_f32_16x16x32_bf16 v[56:59], v[158:161], v[166:169], v[56:59]
	v_mfma_f32_16x16x32_bf16 v[44:47], v[144:147], v[182:185], v[44:47]
	v_mfma_f32_16x16x32_bf16 v[40:43], v[158:161], v[182:185], v[40:43]
	v_mfma_f32_16x16x32_bf16 v[28:31], v[144:147], v[194:197], v[28:31]
	v_mfma_f32_16x16x32_bf16 v[24:27], v[158:161], v[194:197], v[24:27]
	v_mfma_f32_16x16x32_bf16 v[12:15], v[144:147], v[202:205], v[12:15]
	v_mfma_f32_16x16x32_bf16 v[8:11], v[158:161], v[202:205], v[8:11]
	v_mfma_f32_16x16x32_bf16 v[60:63], v[154:157], v[170:173], v[60:63]
	v_mfma_f32_16x16x32_bf16 v[56:59], v[162:165], v[170:173], v[56:59]
	v_mfma_f32_16x16x32_bf16 v[44:47], v[154:157], v[190:193], v[44:47]
	v_mfma_f32_16x16x32_bf16 v[40:43], v[162:165], v[190:193], v[40:43]
	v_mfma_f32_16x16x32_bf16 v[28:31], v[154:157], v[198:201], v[28:31]
	v_mfma_f32_16x16x32_bf16 v[24:27], v[162:165], v[198:201], v[24:27]
	v_mfma_f32_16x16x32_bf16 v[12:15], v[154:157], v[206:209], v[12:15]
	v_mfma_f32_16x16x32_bf16 v[8:11], v[162:165], v[206:209], v[8:11]
	v_mfma_f32_16x16x32_bf16 v[52:55], v[210:213], v[166:169], v[52:55]
	v_mfma_f32_16x16x32_bf16 v[48:51], v[218:221], v[166:169], v[48:51]
	v_mfma_f32_16x16x32_bf16 v[36:39], v[210:213], v[182:185], v[36:39]
	v_mfma_f32_16x16x32_bf16 v[32:35], v[218:221], v[182:185], v[32:35]
	v_mfma_f32_16x16x32_bf16 v[20:23], v[210:213], v[194:197], v[20:23]
	v_mfma_f32_16x16x32_bf16 v[16:19], v[218:221], v[194:197], v[16:19]
	v_mfma_f32_16x16x32_bf16 v[4:7], v[210:213], v[202:205], v[4:7]
	v_mfma_f32_16x16x32_bf16 v[0:3], v[218:221], v[202:205], v[0:3]
	v_mfma_f32_16x16x32_bf16 v[52:55], v[214:217], v[170:173], v[52:55]
	v_mfma_f32_16x16x32_bf16 v[48:51], v[222:225], v[170:173], v[48:51]
	v_mfma_f32_16x16x32_bf16 v[36:39], v[214:217], v[190:193], v[36:39]
	v_mfma_f32_16x16x32_bf16 v[32:35], v[222:225], v[190:193], v[32:35]
	v_mfma_f32_16x16x32_bf16 v[20:23], v[214:217], v[198:201], v[20:23]
	v_mfma_f32_16x16x32_bf16 v[16:19], v[222:225], v[198:201], v[16:19]
	v_mfma_f32_16x16x32_bf16 v[4:7], v[214:217], v[206:209], v[4:7]
	v_mfma_f32_16x16x32_bf16 v[0:3], v[222:225], v[206:209], v[0:3]
	s_barrier
; #define PG8_STAGE(bufoff, gbase, voff) do { _Pragma("unroll") for (int _i = 0; _i < 2; ++_i) \
;         __builtin_amdgcn_global_load_lds((const unsigned*)((const char*)(gbase) + (voff)[_i]), (PG8_LAS unsigned*)(lds + (bufoff) + ldsw + _i * 8192), 16, 0, 0); } while (0)
; #define PG8_LDA(dst, b, h) do { _Pragma("unroll") for (int m = 0; m < 4; ++m) _Pragma("unroll") for (int k = 0; k < 2; ++k) dst[m][k] = *(const PG8_LAS bf16x8*)(lds + PG8_SA(b, h) + aoff + m * 2048 + k * 1024); } while (0)
; #define PG8_WAIT_V(n) asm volatile("s_waitcnt vmcnt(" #n ")" ::: "memory")
; template <class Epi, class Sched>
; __device__ __forceinline__ void gemm_phase(PG8_LAS unsigned char* lds, const Gemm g, const Sched& S, const Epi& E) {
;     ...
;         for (int t = 0; t < nt; t += 2) {
;             const bool last = (t == nt - 2);
;             const char* a1 = cA + (size_t)(t + 1) * kstep;
;             const char* a2 = last ? nA : cA + (size_t)(t + 2) * kstep; const char* b2 = last ? nB : cB + (size_t)(t + 2) * kstep;
;             const char* a3 = a2 + kstep; const char* b3 = b2 + kstep;
;             if (last && has_next) S.a_ready(nxt);
;             PG8_LDB(B0, 0, 0); PG8_SCHED; PG8_LDA(At, 0, 0); PG8_STAGE(PG8_SA(1, 1), a1 + hstep, voffA);
;             PG8_WAIT_L(8); PG8_BAR; PG8_WAIT_L(0); PG8_MMA(0, 0, At, B0); PG8_BAR; PG8_SCHED;
;             PG8_LDB(B1, 0, 1); PG8_STAGE(PG8_SB(0, 0), b2, voffB);
;             PG8_BAR; PG8_WAIT_L(0); PG8_MMA(0, 1, At, B1); PG8_BAR;
;             PG8_LDA(At, 0, 1); PG8_STAGE(PG8_SA(0, 0), a2, voffA);
;             PG8_BAR; PG8_WAIT_L(0); PG8_MMA(1, 0, At, B0); PG8_BAR; PG8_SCHED;
;             PG8_STAGE(PG8_SB(0, 1), b2 + hstep, voffB);
;             PG8_WAIT_V(6); PG8_BAR; PG8_MMA(1, 1, At, B1); PG8_BAR;
;             PG8_LDB(B0, 1, 0); PG8_SCHED; PG8_LDA(At, 1, 0); PG8_STAGE(PG8_SA(0, 1), a2 + hstep, voffA);
;             PG8_WAIT_L(8); PG8_BAR; PG8_WAIT_L(0); PG8_MMA(0, 0, At, B0); PG8_BAR; PG8_SCHED;
;             PG8_LDB(B1, 1, 1); PG8_STAGE(PG8_SB(1, 0), b3, voffB);
;             PG8_BAR; PG8_WAIT_L(0); PG8_MMA(0, 1, At, B1); PG8_BAR;
;             PG8_LDA(At, 1, 1); PG8_STAGE(PG8_SA(1, 0), a3, voffA);
;             PG8_BAR; PG8_WAIT_L(0); PG8_MMA(1, 0, At, B0); PG8_BAR; PG8_SCHED;
;             PG8_STAGE(PG8_SB(1, 1), b3 + hstep, voffB);
;             PG8_WAIT_V(6); PG8_BAR; PG8_MMA(1, 1, At, B1); PG8_BAR;
	s_add_i32 s47, 0, 0x18000
	v_add_u32_e32 v162, s47, v149
	ds_read_b128 v[144:147], v162
	ds_read_b128 v[154:157], v162 offset:1024
	ds_read_b128 v[158:161], v162 offset:2048
	ds_read_b128 v[162:165], v162 offset:3072
	s_add_u32 s20, s20, 0x40000
	s_addc_u32 s21, s21, 0
	s_mov_b32 m0, s30
	ds_read_b128 v[166:169], v152 offset:32768
	ds_read_b128 v[170:173], v152 offset:33792
	ds_read_b128 v[182:185], v152 offset:34816
	ds_read_b128 v[190:193], v152 offset:35840
	ds_read_b128 v[194:197], v152 offset:36864
	ds_read_b128 v[198:201], v152 offset:37888
	ds_read_b128 v[202:205], v152 offset:38912
	ds_read_b128 v[206:209], v152 offset:39936
	global_load_lds_dwordx4 v134, s[20:21]
	s_nop 1
	s_mov_b32 m0, s31
	s_nop 0
	global_load_lds_dwordx4 v130, s[20:21]
	s_add_i32 s20, 0, 0x1c000
	v_add_u32_e32 v179, s20, v149
	s_waitcnt lgkmcnt(8)
	ds_read_b128 v[210:213], v179
	ds_read_b128 v[214:217], v179 offset:1024
	ds_read_b128 v[218:221], v179 offset:2048
	ds_read_b128 v[222:225], v179 offset:3072
	s_waitcnt vmcnt(8) lgkmcnt(0)
	s_barrier
	v_mfma_f32_16x16x32_bf16 v[124:127], v[144:147], v[166:169], v[124:127]
	v_mfma_f32_16x16x32_bf16 v[120:123], v[158:161], v[166:169], v[120:123]
	v_mfma_f32_16x16x32_bf16 v[108:111], v[144:147], v[182:185], v[108:111]
	v_mfma_f32_16x16x32_bf16 v[104:107], v[158:161], v[182:185], v[104:107]
	v_mfma_f32_16x16x32_bf16 v[92:95], v[144:147], v[194:197], v[92:95]
	v_mfma_f32_16x16x32_bf16 v[88:91], v[158:161], v[194:197], v[88:91]
	v_mfma_f32_16x16x32_bf16 v[76:79], v[144:147], v[202:205], v[76:79]
	v_mfma_f32_16x16x32_bf16 v[72:75], v[158:161], v[202:205], v[72:75]
	v_mfma_f32_16x16x32_bf16 v[124:127], v[154:157], v[170:173], v[124:127]
	v_mfma_f32_16x16x32_bf16 v[120:123], v[162:165], v[170:173], v[120:123]
	v_mfma_f32_16x16x32_bf16 v[108:111], v[154:157], v[190:193], v[108:111]
	v_mfma_f32_16x16x32_bf16 v[104:107], v[162:165], v[190:193], v[104:107]
	v_mfma_f32_16x16x32_bf16 v[92:95], v[154:157], v[198:201], v[92:95]
	v_mfma_f32_16x16x32_bf16 v[88:91], v[162:165], v[198:201], v[88:91]
	v_mfma_f32_16x16x32_bf16 v[76:79], v[154:157], v[206:209], v[76:79]
	v_mfma_f32_16x16x32_bf16 v[72:75], v[162:165], v[206:209], v[72:75]
	v_mfma_f32_16x16x32_bf16 v[116:119], v[210:213], v[166:169], v[116:119]
	v_mfma_f32_16x16x32_bf16 v[112:115], v[218:221], v[166:169], v[112:115]
	v_mfma_f32_16x16x32_bf16 v[100:103], v[210:213], v[182:185], v[100:103]
	v_mfma_f32_16x16x32_bf16 v[96:99], v[218:221], v[182:185], v[96:99]
	v_mfma_f32_16x16x32_bf16 v[84:87], v[210:213], v[194:197], v[84:87]
	v_mfma_f32_16x16x32_bf16 v[80:83], v[218:221], v[194:197], v[80:83]
	v_mfma_f32_16x16x32_bf16 v[68:71], v[210:213], v[202:205], v[68:71]
	v_mfma_f32_16x16x32_bf16 v[64:67], v[218:221], v[202:205], v[64:67]
	v_mfma_f32_16x16x32_bf16 v[116:119], v[214:217], v[170:173], v[116:119]
	v_mfma_f32_16x16x32_bf16 v[112:115], v[222:225], v[170:173], v[112:115]
	v_mfma_f32_16x16x32_bf16 v[100:103], v[214:217], v[190:193], v[100:103]
	v_mfma_f32_16x16x32_bf16 v[96:99], v[222:225], v[190:193], v[96:99]
	v_mfma_f32_16x16x32_bf16 v[84:87], v[214:217], v[198:201], v[84:87]
	v_mfma_f32_16x16x32_bf16 v[80:83], v[222:225], v[198:201], v[80:83]
	v_mfma_f32_16x16x32_bf16 v[68:71], v[214:217], v[206:209], v[68:71]
	v_mfma_f32_16x16x32_bf16 v[64:67], v[222:225], v[206:209], v[64:67]
	s_barrier
	ds_read_b128 v[166:169], v152 offset:49152
	ds_read_b128 v[170:173], v152 offset:50176
	ds_read_b128 v[182:185], v152 offset:51200
	ds_read_b128 v[190:193], v152 offset:52224
	ds_read_b128 v[194:197], v152 offset:53248
	ds_read_b128 v[198:201], v152 offset:54272
	ds_read_b128 v[202:205], v152 offset:55296
	ds_read_b128 v[206:209], v152 offset:56320
	s_add_i32 s21, s47, s26
	s_mov_b32 m0, s21
	s_nop 0
	global_load_lds_dwordx4 v132, s[98:99]
	s_nop 1
	s_add_i32 m0, s21, 0x2000
	s_nop 0
	global_load_lds_dwordx4 v128, s[98:99]
	s_nop 1
	s_mov_b32 m0, s35
	s_nop 0
	global_load_lds_dwordx4 v134, s[100:101]
	s_nop 1
	s_mov_b32 m0, s36
	s_nop 0
	global_load_lds_dwordx4 v130, s[100:101]
	s_add_u32 s18, s18, 0x40080
	s_addc_u32 s19, s19, 0
	s_add_i32 s20, s20, s26
	s_mov_b32 m0, s20
	s_nop 0
	global_load_lds_dwordx4 v132, s[18:19]
	s_nop 1
	s_add_i32 m0, s20, 0x2000
	s_nop 0
	global_load_lds_dwordx4 v128, s[18:19]
	s_waitcnt vmcnt(8) lgkmcnt(0)
	s_barrier
	v_mfma_f32_16x16x32_bf16 v[60:63], v[144:147], v[166:169], v[60:63]
	v_mfma_f32_16x16x32_bf16 v[56:59], v[158:161], v[166:169], v[56:59]
	v_mfma_f32_16x16x32_bf16 v[44:47], v[144:147], v[182:185], v[44:47]
	v_mfma_f32_16x16x32_bf16 v[40:43], v[158:161], v[182:185], v[40:43]
	v_mfma_f32_16x16x32_bf16 v[28:31], v[144:147], v[194:197], v[28:31]
	v_mfma_f32_16x16x32_bf16 v[24:27], v[158:161], v[194:197], v[24:27]
	v_mfma_f32_16x16x32_bf16 v[12:15], v[144:147], v[202:205], v[12:15]
	v_mfma_f32_16x16x32_bf16 v[8:11], v[158:161], v[202:205], v[8:11]
	v_mfma_f32_16x16x32_bf16 v[60:63], v[154:157], v[170:173], v[60:63]
	v_mfma_f32_16x16x32_bf16 v[56:59], v[162:165], v[170:173], v[56:59]
	v_mfma_f32_16x16x32_bf16 v[44:47], v[154:157], v[190:193], v[44:47]
	v_mfma_f32_16x16x32_bf16 v[40:43], v[162:165], v[190:193], v[40:43]
	v_mfma_f32_16x16x32_bf16 v[28:31], v[154:157], v[198:201], v[28:31]
	v_mfma_f32_16x16x32_bf16 v[24:27], v[162:165], v[198:201], v[24:27]
	v_mfma_f32_16x16x32_bf16 v[12:15], v[154:157], v[206:209], v[12:15]
	v_mfma_f32_16x16x32_bf16 v[8:11], v[162:165], v[206:209], v[8:11]
	v_mfma_f32_16x16x32_bf16 v[52:55], v[210:213], v[166:169], v[52:55]
	v_mfma_f32_16x16x32_bf16 v[48:51], v[218:221], v[166:169], v[48:51]
	v_mfma_f32_16x16x32_bf16 v[36:39], v[210:213], v[182:185], v[36:39]
	v_mfma_f32_16x16x32_bf16 v[32:35], v[218:221], v[182:185], v[32:35]
	v_mfma_f32_16x16x32_bf16 v[20:23], v[210:213], v[194:197], v[20:23]
	v_mfma_f32_16x16x32_bf16 v[16:19], v[218:221], v[194:197], v[16:19]
	v_mfma_f32_16x16x32_bf16 v[4:7], v[210:213], v[202:205], v[4:7]
	v_mfma_f32_16x16x32_bf16 v[0:3], v[218:221], v[202:205], v[0:3]
	v_mfma_f32_16x16x32_bf16 v[52:55], v[214:217], v[170:173], v[52:55]
	v_mfma_f32_16x16x32_bf16 v[48:51], v[222:225], v[170:173], v[48:51]
	v_mfma_f32_16x16x32_bf16 v[36:39], v[214:217], v[190:193], v[36:39]
	v_mfma_f32_16x16x32_bf16 v[32:35], v[222:225], v[190:193], v[32:35]
	v_mfma_f32_16x16x32_bf16 v[20:23], v[214:217], v[198:201], v[20:23]
	v_mfma_f32_16x16x32_bf16 v[16:19], v[222:225], v[198:201], v[16:19]
	v_mfma_f32_16x16x32_bf16 v[4:7], v[214:217], v[206:209], v[4:7]
	v_mfma_f32_16x16x32_bf16 v[0:3], v[222:225], v[206:209], v[0:3]
	s_barrier
; __device__ __forceinline__ unsigned cvt_pk_bf16(float lo, float hi) { unsigned r; asm volatile("v_cvt_pk_bf16_f32 %0, %1, %2" : "=v"(r) : "v"(lo), "v"(hi)); return r; }
; __device__ __forceinline__ f32x4 sigmoid4(f32x4 x) {
;     f32x4 d;
; #pragma unroll
;     for (int j = 0; j < 4; ++j) d[j] = 1.0f + __expf(-fmaxf(x[j], -20.0f));
;     const float p01 = d[0] * d[1], p23 = d[2] * d[3], r = __builtin_amdgcn_rcpf(p01 * p23), r01 = r * p23, r23 = r * p01;
;     return (f32x4){r01 * d[1], r01 * d[0], r23 * d[3], r23 * d[2]};
; }
;     __device__ __forceinline__ void operator()(const f32x4 (&acc)[2][2][4][2], const Unit& u, int wr, int wc, int fr, int fq) const {
;         const int row0 = u.pm * BM + wr * 64 + fr, col0 = u.pn * HALF + wc * 32 + 8 * fq;
; #pragma unroll
;         for (int ai = 0; ai < 2; ++ai)
; #pragma unroll
;             for (int m = 0; m < 4; ++m) { bf16_t* rowp = O + (size_t)(row0 + ai * HALF + m * 16) * ldc + col0;
;                 f32x4 v0, v1;
; #pragma unroll
;                 for (int j = 0; j < 1; ++j) { v0 = acc[ai][0][m][0] * sigmoid4(acc[ai][0][m][0]) * acc[ai][1][m][0]; v1 = acc[ai][0][m][1] * sigmoid4(acc[ai][0][m][1]) * acc[ai][1][m][1]; }
;                 u32x4 w; w.x = cvt_pk_bf16(v0[0], v0[1]); w.y = cvt_pk_bf16(v0[2], v0[3]); w.z = cvt_pk_bf16(v1[0], v1[1]); w.w = cvt_pk_bf16(v1[2], v1[3]);
;                 *(u32x4*)rowp = w; }
	s_add_i32 s46, s46, 2
	s_add_u32 s16, s16, 0x100
	s_addc_u32 s17, s17, 0
	s_add_u32 s44, s44, 0x100
	s_addc_u32 s45, s45, 0
	s_cmp_gt_u32 s46, 13
	s_cbranch_scc0 .LBB0_1202
	v_max_f32_e32 v144, 0xc1a00000, v124
	v_mul_f32_e32 v144, 0xbfb8aa3b, v144
	v_exp_f32_e32 v157, v144
	v_max_f32_e32 v144, 0xc1a00000, v125
	v_mul_f32_e32 v144, 0xbfb8aa3b, v144
	v_exp_f32_e32 v156, v144
	v_max_f32_e32 v144, 0xc1a00000, v126
	v_mul_f32_e32 v144, 0xbfb8aa3b, v144
	v_exp_f32_e32 v159, v144
	v_max_f32_e32 v144, 0xc1a00000, v127
	v_mul_f32_e32 v144, 0xbfb8aa3b, v144
	v_exp_f32_e32 v158, v144
	v_pk_add_f32 v[156:157], v[156:157], 1.0 op_sel_hi:[1,0]
	v_lshl_or_b32 v146, s41, 7, v150
	v_pk_add_f32 v[158:159], v[158:159], 1.0 op_sel_hi:[1,0]
	v_mul_f32_e32 v160, v157, v156
	v_mul_f32_e32 v161, v159, v158
	v_lshl_add_u32 v154, s14, 8, v148
	v_mul_f32_e32 v155, v160, v161
	v_rcp_f32_e32 v155, v155
	v_ashrrev_i32_e32 v147, 31, v146
	v_mov_b64_e32 v[144:145], s[0:1]
	v_mad_i64_i32 v[162:163], s[16:17], v154, s40, v[144:145]
	v_mul_f32_e32 v164, v161, v155
	v_mul_f32_e32 v160, v160, v155
	v_max_f32_e32 v155, 0xc1a00000, v120
	v_mul_f32_e32 v155, 0xbfb8aa3b, v155
	v_pk_mul_f32 v[158:159], v[158:159], v[160:161] op_sel_hi:[1,0]
	v_exp_f32_e32 v161, v155
	v_max_f32_e32 v155, 0xc1a00000, v121
	v_mul_f32_e32 v155, 0xbfb8aa3b, v155
	v_exp_f32_e32 v160, v155
	v_max_f32_e32 v155, 0xc1a00000, v122
	v_mul_f32_e32 v155, 0xbfb8aa3b, v155
	v_exp_f32_e32 v167, v155
	v_max_f32_e32 v155, 0xc1a00000, v123
	v_mul_f32_e32 v155, 0xbfb8aa3b, v155
	v_exp_f32_e32 v166, v155
	v_pk_mul_f32 v[156:157], v[156:157], v[164:165] op_sel_hi:[1,0]
	v_pk_mul_f32 v[126:127], v[126:127], v[158:159]
	v_pk_mul_f32 v[124:125], v[124:125], v[156:157]
	v_pk_add_f32 v[156:157], v[160:161], 1.0 op_sel_hi:[1,0]
	v_pk_add_f32 v[160:161], v[166:167], 1.0 op_sel_hi:[1,0]
	v_mov_b32_e32 v164, v157
	v_mov_b32_e32 v165, v161
	v_mov_b32_e32 v166, v156
	v_mov_b32_e32 v167, v160
	v_pk_mul_f32 v[164:165], v[164:165], v[166:167]
	v_pk_mul_f32 v[118:119], v[126:127], v[118:119]
	v_mul_f32_e32 v155, v164, v165
	v_rcp_f32_e32 v155, v155
	v_pk_mul_f32 v[116:117], v[124:125], v[116:117]
	v_lshlrev_b64 v[146:147], 1, v[146:147]
	v_lshl_add_u64 v[162:163], v[162:163], 0, v[146:147]
	v_mul_f32_e32 v124, v165, v155
	v_mul_f32_e32 v126, v164, v155
	v_pk_mul_f32 v[126:127], v[160:161], v[126:127] op_sel_hi:[1,0]
	v_pk_mul_f32 v[124:125], v[156:157], v[124:125] op_sel_hi:[1,0]
	v_pk_mul_f32 v[122:123], v[122:123], v[126:127]
	v_pk_mul_f32 v[120:121], v[120:121], v[124:125]
	v_pk_mul_f32 v[122:123], v[122:123], v[114:115]
	v_pk_mul_f32 v[114:115], v[120:121], v[112:113]
	v_cvt_pk_bf16_f32 v112, v116, v117
	v_cvt_pk_bf16_f32 v113, v118, v119
	v_max_f32_e32 v116, 0xc1a00000, v108
	v_max_f32_e32 v118, 0xc1a00000, v110
	v_mul_f32_e32 v116, 0xbfb8aa3b, v116
	v_mul_f32_e32 v118, 0xbfb8aa3b, v118
	v_exp_f32_e32 v117, v116
	v_exp_f32_e32 v119, v118
	v_max_f32_e32 v116, 0xc1a00000, v109
	v_max_f32_e32 v118, 0xc1a00000, v111
	v_mul_f32_e32 v116, 0xbfb8aa3b, v116
	v_mul_f32_e32 v118, 0xbfb8aa3b, v118
	v_exp_f32_e32 v116, v116
	v_exp_f32_e32 v118, v118
	v_cvt_pk_bf16_f32 v114, v114, v115
	v_cvt_pk_bf16_f32 v115, v122, v123
	global_store_dwordx4 v[162:163], v[112:115], off
	v_or_b32_e32 v120, 16, v154
	s_and_b64 vcc, exec, s[2:3]
	v_pk_add_f32 v[112:113], v[116:117], 1.0 op_sel_hi:[1,0]
	v_pk_add_f32 v[114:115], v[118:119], 1.0 op_sel_hi:[1,0]
	v_mul_f32_e32 v116, v113, v112
	v_mul_f32_e32 v117, v115, v114
	s_mov_b32 s41, s6
	v_mul_f32_e32 v118, v116, v117
	v_rcp_f32_e32 v121, v118
	v_mad_i64_i32 v[118:119], s[16:17], v120, s40, v[144:145]
	v_lshl_add_u64 v[118:119], v[118:119], 0, v[146:147]
	v_mul_f32_e32 v116, v116, v121
	v_mul_f32_e32 v120, v117, v121
	v_pk_mul_f32 v[114:115], v[114:115], v[116:117] op_sel_hi:[1,0]
	v_max_f32_e32 v116, 0xc1a00000, v104
	v_max_f32_e32 v121, 0xc1a00000, v106
	v_mul_f32_e32 v116, 0xbfb8aa3b, v116
	v_mul_f32_e32 v121, 0xbfb8aa3b, v121
	v_exp_f32_e32 v117, v116
	v_exp_f32_e32 v123, v121
	v_max_f32_e32 v116, 0xc1a00000, v105
	v_max_f32_e32 v121, 0xc1a00000, v107
	v_mul_f32_e32 v116, 0xbfb8aa3b, v116
	v_mul_f32_e32 v121, 0xbfb8aa3b, v121
	v_exp_f32_e32 v116, v116
	v_exp_f32_e32 v122, v121
	v_pk_mul_f32 v[112:113], v[112:113], v[120:121] op_sel_hi:[1,0]
	v_pk_mul_f32 v[110:111], v[110:111], v[114:115]
	v_pk_mul_f32 v[108:109], v[108:109], v[112:113]
	v_pk_add_f32 v[112:113], v[116:117], 1.0 op_sel_hi:[1,0]
	v_pk_add_f32 v[116:117], v[122:123], 1.0 op_sel_hi:[1,0]
	v_mov_b32_e32 v120, v113
	v_mov_b32_e32 v121, v117
	v_mov_b32_e32 v122, v112
	v_mov_b32_e32 v123, v116
	v_pk_mul_f32 v[120:121], v[120:121], v[122:123]
	v_pk_mul_f32 v[102:103], v[110:111], v[102:103]
	v_mul_f32_e32 v122, v120, v121
	v_rcp_f32_e32 v122, v122
	v_pk_mul_f32 v[100:101], v[108:109], v[100:101]
	s_mov_b32 s14, s8
	s_mov_b64 s[18:19], s[12:13]
	v_mul_f32_e32 v108, v121, v122
	v_mul_f32_e32 v110, v120, v122
	v_pk_mul_f32 v[110:111], v[116:117], v[110:111] op_sel_hi:[1,0]
	v_pk_mul_f32 v[108:109], v[112:113], v[108:109] op_sel_hi:[1,0]
	v_pk_mul_f32 v[106:107], v[106:107], v[110:111]
	v_pk_mul_f32 v[104:105], v[104:105], v[108:109]
	v_pk_mul_f32 v[106:107], v[106:107], v[98:99]
	v_pk_mul_f32 v[98:99], v[104:105], v[96:97]
	v_cvt_pk_bf16_f32 v96, v100, v101
	v_cvt_pk_bf16_f32 v97, v102, v103
	v_max_f32_e32 v100, 0xc1a00000, v92
	v_max_f32_e32 v102, 0xc1a00000, v94
	v_mul_f32_e32 v100, 0xbfb8aa3b, v100
	v_mul_f32_e32 v102, 0xbfb8aa3b, v102
	v_exp_f32_e32 v101, v100
	v_exp_f32_e32 v103, v102
	v_max_f32_e32 v100, 0xc1a00000, v93
	v_max_f32_e32 v102, 0xc1a00000, v95
	v_mul_f32_e32 v100, 0xbfb8aa3b, v100
	v_mul_f32_e32 v102, 0xbfb8aa3b, v102
; __device__ __forceinline__ unsigned cvt_pk_bf16(float lo, float hi) { unsigned r; asm volatile("v_cvt_pk_bf16_f32 %0, %1, %2" : "=v"(r) : "v"(lo), "v"(hi)); return r; }
; __device__ __forceinline__ f32x4 sigmoid4(f32x4 x) {
;     f32x4 d;
; #pragma unroll
;     for (int j = 0; j < 4; ++j) d[j] = 1.0f + __expf(-fmaxf(x[j], -20.0f));
;     const float p01 = d[0] * d[1], p23 = d[2] * d[3], r = __builtin_amdgcn_rcpf(p01 * p23), r01 = r * p23, r23 = r * p01;
;     return (f32x4){r01 * d[1], r01 * d[0], r23 * d[3], r23 * d[2]};
; }
;     __device__ __forceinline__ void operator()(const f32x4 (&acc)[2][2][4][2], const Unit& u, int wr, int wc, int fr, int fq) const {
;         const int row0 = u.pm * BM + wr * 64 + fr, col0 = u.pn * HALF + wc * 32 + 8 * fq;
; #pragma unroll
;         for (int ai = 0; ai < 2; ++ai)
; #pragma unroll
;             for (int m = 0; m < 4; ++m) { bf16_t* rowp = O + (size_t)(row0 + ai * HALF + m * 16) * ldc + col0;
;                 f32x4 v0, v1;
; #pragma unroll
;                 for (int j = 0; j < 1; ++j) { v0 = acc[ai][0][m][0] * sigmoid4(acc[ai][0][m][0]) * acc[ai][1][m][0]; v1 = acc[ai][0][m][1] * sigmoid4(acc[ai][0][m][1]) * acc[ai][1][m][1]; }
;                 u32x4 w; w.x = cvt_pk_bf16(v0[0], v0[1]); w.y = cvt_pk_bf16(v0[2], v0[3]); w.z = cvt_pk_bf16(v1[0], v1[1]); w.w = cvt_pk_bf16(v1[2], v1[3]);
;                 *(u32x4*)rowp = w; }
	v_exp_f32_e32 v100, v100
	v_exp_f32_e32 v102, v102
	v_cvt_pk_bf16_f32 v98, v98, v99
	v_cvt_pk_bf16_f32 v99, v106, v107
	global_store_dwordx4 v[118:119], v[96:99], off
	v_or_b32_e32 v104, 32, v154
	s_nop 0
	v_pk_add_f32 v[96:97], v[100:101], 1.0 op_sel_hi:[1,0]
	v_pk_add_f32 v[98:99], v[102:103], 1.0 op_sel_hi:[1,0]
	v_mul_f32_e32 v100, v97, v96
	v_mul_f32_e32 v101, v99, v98
	s_nop 0
	v_mul_f32_e32 v102, v100, v101
	v_rcp_f32_e32 v105, v102
	v_mad_i64_i32 v[102:103], s[16:17], v104, s40, v[144:145]
	v_lshl_add_u64 v[102:103], v[102:103], 0, v[146:147]
	v_mul_f32_e32 v100, v100, v105
	v_mul_f32_e32 v104, v101, v105
	v_pk_mul_f32 v[98:99], v[98:99], v[100:101] op_sel_hi:[1,0]
	v_max_f32_e32 v100, 0xc1a00000, v88
	v_max_f32_e32 v105, 0xc1a00000, v90
	v_mul_f32_e32 v100, 0xbfb8aa3b, v100
	v_mul_f32_e32 v105, 0xbfb8aa3b, v105
	v_exp_f32_e32 v101, v100
	v_exp_f32_e32 v107, v105
	v_max_f32_e32 v100, 0xc1a00000, v89
	v_max_f32_e32 v105, 0xc1a00000, v91
	v_mul_f32_e32 v100, 0xbfb8aa3b, v100
	v_mul_f32_e32 v105, 0xbfb8aa3b, v105
	v_exp_f32_e32 v100, v100
	v_exp_f32_e32 v106, v105
	v_pk_mul_f32 v[96:97], v[96:97], v[104:105] op_sel_hi:[1,0]
	v_pk_mul_f32 v[94:95], v[94:95], v[98:99]
	v_pk_mul_f32 v[92:93], v[92:93], v[96:97]
	v_pk_add_f32 v[96:97], v[100:101], 1.0 op_sel_hi:[1,0]
	v_pk_add_f32 v[100:101], v[106:107], 1.0 op_sel_hi:[1,0]
	v_mov_b32_e32 v104, v97
	v_mov_b32_e32 v105, v101
	v_mov_b32_e32 v106, v96
	v_mov_b32_e32 v107, v100
	v_pk_mul_f32 v[104:105], v[104:105], v[106:107]
	v_pk_mul_f32 v[86:87], v[94:95], v[86:87]
	v_mul_f32_e32 v106, v104, v105
	v_rcp_f32_e32 v106, v106
	v_pk_mul_f32 v[84:85], v[92:93], v[84:85]
	v_mul_f32_e32 v92, v105, v106
	v_mul_f32_e32 v94, v104, v106
	v_pk_mul_f32 v[94:95], v[100:101], v[94:95] op_sel_hi:[1,0]
	v_pk_mul_f32 v[92:93], v[96:97], v[92:93] op_sel_hi:[1,0]
	v_pk_mul_f32 v[90:91], v[90:91], v[94:95]
	v_pk_mul_f32 v[88:89], v[88:89], v[92:93]
	v_pk_mul_f32 v[90:91], v[90:91], v[82:83]
	v_pk_mul_f32 v[82:83], v[88:89], v[80:81]
	v_cvt_pk_bf16_f32 v80, v84, v85
	v_cvt_pk_bf16_f32 v81, v86, v87
	v_max_f32_e32 v84, 0xc1a00000, v76
	v_max_f32_e32 v86, 0xc1a00000, v78
	v_mul_f32_e32 v84, 0xbfb8aa3b, v84
	v_mul_f32_e32 v86, 0xbfb8aa3b, v86
	v_exp_f32_e32 v85, v84
	v_exp_f32_e32 v87, v86
	v_max_f32_e32 v84, 0xc1a00000, v77
	v_max_f32_e32 v86, 0xc1a00000, v79
	v_mul_f32_e32 v84, 0xbfb8aa3b, v84
	v_mul_f32_e32 v86, 0xbfb8aa3b, v86
	v_exp_f32_e32 v84, v84
	v_exp_f32_e32 v86, v86
	v_cvt_pk_bf16_f32 v82, v82, v83
	v_cvt_pk_bf16_f32 v83, v90, v91
	global_store_dwordx4 v[102:103], v[80:83], off
	v_or_b32_e32 v88, 48, v154
	s_nop 0
	v_pk_add_f32 v[80:81], v[84:85], 1.0 op_sel_hi:[1,0]
	v_pk_add_f32 v[82:83], v[86:87], 1.0 op_sel_hi:[1,0]
	v_mul_f32_e32 v84, v81, v80
	v_mul_f32_e32 v85, v83, v82
	s_nop 0
	v_mul_f32_e32 v86, v84, v85
	v_rcp_f32_e32 v89, v86
	v_mad_i64_i32 v[86:87], s[16:17], v88, s40, v[144:145]
	v_lshl_add_u64 v[86:87], v[86:87], 0, v[146:147]
	v_mul_f32_e32 v84, v84, v89
	v_mul_f32_e32 v88, v85, v89
	v_pk_mul_f32 v[82:83], v[82:83], v[84:85] op_sel_hi:[1,0]
	v_max_f32_e32 v84, 0xc1a00000, v72
	v_max_f32_e32 v89, 0xc1a00000, v74
	v_mul_f32_e32 v84, 0xbfb8aa3b, v84
	v_mul_f32_e32 v89, 0xbfb8aa3b, v89
	v_exp_f32_e32 v85, v84
	v_exp_f32_e32 v91, v89
	v_max_f32_e32 v84, 0xc1a00000, v73
	v_max_f32_e32 v89, 0xc1a00000, v75
	v_mul_f32_e32 v84, 0xbfb8aa3b, v84
	v_mul_f32_e32 v89, 0xbfb8aa3b, v89
	v_exp_f32_e32 v84, v84
	v_exp_f32_e32 v90, v89
	v_pk_mul_f32 v[80:81], v[80:81], v[88:89] op_sel_hi:[1,0]
	v_pk_mul_f32 v[78:79], v[78:79], v[82:83]
	v_pk_mul_f32 v[76:77], v[76:77], v[80:81]
	v_pk_add_f32 v[80:81], v[84:85], 1.0 op_sel_hi:[1,0]
	v_pk_add_f32 v[84:85], v[90:91], 1.0 op_sel_hi:[1,0]
	v_mov_b32_e32 v88, v81
	v_mov_b32_e32 v89, v85
	v_mov_b32_e32 v90, v80
	v_mov_b32_e32 v91, v84
	v_pk_mul_f32 v[88:89], v[88:89], v[90:91]
	v_pk_mul_f32 v[70:71], v[78:79], v[70:71]
	v_mul_f32_e32 v90, v88, v89
	v_rcp_f32_e32 v90, v90
	v_pk_mul_f32 v[68:69], v[76:77], v[68:69]
	v_mul_f32_e32 v76, v89, v90
	v_mul_f32_e32 v78, v88, v90
	v_pk_mul_f32 v[78:79], v[84:85], v[78:79] op_sel_hi:[1,0]
	v_pk_mul_f32 v[76:77], v[80:81], v[76:77] op_sel_hi:[1,0]
	v_pk_mul_f32 v[74:75], v[74:75], v[78:79]
	v_pk_mul_f32 v[72:73], v[72:73], v[76:77]
	v_pk_mul_f32 v[74:75], v[74:75], v[66:67]
	v_pk_mul_f32 v[66:67], v[72:73], v[64:65]
	v_cvt_pk_bf16_f32 v64, v68, v69
	v_cvt_pk_bf16_f32 v65, v70, v71
	v_max_f32_e32 v68, 0xc1a00000, v60
	v_max_f32_e32 v70, 0xc1a00000, v62
	v_mul_f32_e32 v68, 0xbfb8aa3b, v68
	v_mul_f32_e32 v70, 0xbfb8aa3b, v70
	v_exp_f32_e32 v69, v68
	v_exp_f32_e32 v71, v70
	v_max_f32_e32 v68, 0xc1a00000, v61
	v_max_f32_e32 v70, 0xc1a00000, v63
	v_mul_f32_e32 v68, 0xbfb8aa3b, v68
	v_mul_f32_e32 v70, 0xbfb8aa3b, v70
	v_exp_f32_e32 v68, v68
	v_exp_f32_e32 v70, v70
	v_cvt_pk_bf16_f32 v66, v66, v67
	v_cvt_pk_bf16_f32 v67, v74, v75
	global_store_dwordx4 v[86:87], v[64:67], off
	v_add_u32_e32 v72, 0x80, v154
	s_nop 0
	v_pk_add_f32 v[64:65], v[68:69], 1.0 op_sel_hi:[1,0]
	v_pk_add_f32 v[66:67], v[70:71], 1.0 op_sel_hi:[1,0]
	v_mul_f32_e32 v68, v65, v64
	v_mul_f32_e32 v69, v67, v66
	s_nop 0
	v_mul_f32_e32 v70, v68, v69
	v_rcp_f32_e32 v73, v70
	v_mad_i64_i32 v[70:71], s[16:17], v72, s40, v[144:145]
	v_lshl_add_u64 v[70:71], v[70:71], 0, v[146:147]
	v_mul_f32_e32 v68, v68, v73
	v_mul_f32_e32 v72, v69, v73
	v_pk_mul_f32 v[66:67], v[66:67], v[68:69] op_sel_hi:[1,0]
	v_max_f32_e32 v68, 0xc1a00000, v56
	v_max_f32_e32 v73, 0xc1a00000, v58
	v_mul_f32_e32 v68, 0xbfb8aa3b, v68
	v_mul_f32_e32 v73, 0xbfb8aa3b, v73
	v_exp_f32_e32 v69, v68
	v_exp_f32_e32 v75, v73
	v_max_f32_e32 v68, 0xc1a00000, v57
	v_max_f32_e32 v73, 0xc1a00000, v59
; __device__ __forceinline__ unsigned cvt_pk_bf16(float lo, float hi) { unsigned r; asm volatile("v_cvt_pk_bf16_f32 %0, %1, %2" : "=v"(r) : "v"(lo), "v"(hi)); return r; }
; __device__ __forceinline__ f32x4 sigmoid4(f32x4 x) {
;     f32x4 d;
; #pragma unroll
;     for (int j = 0; j < 4; ++j) d[j] = 1.0f + __expf(-fmaxf(x[j], -20.0f));
;     const float p01 = d[0] * d[1], p23 = d[2] * d[3], r = __builtin_amdgcn_rcpf(p01 * p23), r01 = r * p23, r23 = r * p01;
;     return (f32x4){r01 * d[1], r01 * d[0], r23 * d[3], r23 * d[2]};
; }
;     __device__ __forceinline__ void operator()(const f32x4 (&acc)[2][2][4][2], const Unit& u, int wr, int wc, int fr, int fq) const {
;         const int row0 = u.pm * BM + wr * 64 + fr, col0 = u.pn * HALF + wc * 32 + 8 * fq;
; #pragma unroll
;         for (int ai = 0; ai < 2; ++ai)
; #pragma unroll
;             for (int m = 0; m < 4; ++m) { bf16_t* rowp = O + (size_t)(row0 + ai * HALF + m * 16) * ldc + col0;
;                 f32x4 v0, v1;
; #pragma unroll
;                 for (int j = 0; j < 1; ++j) { v0 = acc[ai][0][m][0] * sigmoid4(acc[ai][0][m][0]) * acc[ai][1][m][0]; v1 = acc[ai][0][m][1] * sigmoid4(acc[ai][0][m][1]) * acc[ai][1][m][1]; }
;                 u32x4 w; w.x = cvt_pk_bf16(v0[0], v0[1]); w.y = cvt_pk_bf16(v0[2], v0[3]); w.z = cvt_pk_bf16(v1[0], v1[1]); w.w = cvt_pk_bf16(v1[2], v1[3]);
;                 *(u32x4*)rowp = w; }
	v_mul_f32_e32 v68, 0xbfb8aa3b, v68
	v_mul_f32_e32 v73, 0xbfb8aa3b, v73
	v_exp_f32_e32 v68, v68
	v_exp_f32_e32 v74, v73
	v_pk_mul_f32 v[64:65], v[64:65], v[72:73] op_sel_hi:[1,0]
	v_pk_mul_f32 v[62:63], v[62:63], v[66:67]
	v_pk_mul_f32 v[60:61], v[60:61], v[64:65]
	v_pk_add_f32 v[64:65], v[68:69], 1.0 op_sel_hi:[1,0]
	v_pk_add_f32 v[68:69], v[74:75], 1.0 op_sel_hi:[1,0]
	v_mov_b32_e32 v72, v65
	v_mov_b32_e32 v73, v69
	v_mov_b32_e32 v74, v64
	v_mov_b32_e32 v75, v68
	v_pk_mul_f32 v[72:73], v[72:73], v[74:75]
	v_pk_mul_f32 v[54:55], v[62:63], v[54:55]
	v_mul_f32_e32 v74, v72, v73
	v_rcp_f32_e32 v74, v74
	v_pk_mul_f32 v[52:53], v[60:61], v[52:53]
	v_mul_f32_e32 v60, v73, v74
	v_mul_f32_e32 v62, v72, v74
	v_pk_mul_f32 v[62:63], v[68:69], v[62:63] op_sel_hi:[1,0]
	v_pk_mul_f32 v[60:61], v[64:65], v[60:61] op_sel_hi:[1,0]
	v_pk_mul_f32 v[58:59], v[58:59], v[62:63]
	v_pk_mul_f32 v[56:57], v[56:57], v[60:61]
	v_pk_mul_f32 v[58:59], v[58:59], v[50:51]
	v_pk_mul_f32 v[50:51], v[56:57], v[48:49]
	v_cvt_pk_bf16_f32 v48, v52, v53
	v_cvt_pk_bf16_f32 v49, v54, v55
	v_max_f32_e32 v52, 0xc1a00000, v44
	v_max_f32_e32 v54, 0xc1a00000, v46
	v_mul_f32_e32 v52, 0xbfb8aa3b, v52
	v_mul_f32_e32 v54, 0xbfb8aa3b, v54
	v_exp_f32_e32 v53, v52
	v_exp_f32_e32 v55, v54
	v_max_f32_e32 v52, 0xc1a00000, v45
	v_max_f32_e32 v54, 0xc1a00000, v47
	v_mul_f32_e32 v52, 0xbfb8aa3b, v52
	v_mul_f32_e32 v54, 0xbfb8aa3b, v54
	v_exp_f32_e32 v52, v52
	v_exp_f32_e32 v54, v54
	v_cvt_pk_bf16_f32 v50, v50, v51
	v_cvt_pk_bf16_f32 v51, v58, v59
	global_store_dwordx4 v[70:71], v[48:51], off
	v_add_u32_e32 v56, 0x90, v154
	s_nop 0
	v_pk_add_f32 v[48:49], v[52:53], 1.0 op_sel_hi:[1,0]
	v_pk_add_f32 v[50:51], v[54:55], 1.0 op_sel_hi:[1,0]
	v_mul_f32_e32 v52, v49, v48
	v_mul_f32_e32 v53, v51, v50
	s_nop 0
	v_mul_f32_e32 v54, v52, v53
	v_rcp_f32_e32 v57, v54
	v_mad_i64_i32 v[54:55], s[16:17], v56, s40, v[144:145]
	v_lshl_add_u64 v[54:55], v[54:55], 0, v[146:147]
	v_mul_f32_e32 v52, v52, v57
	v_mul_f32_e32 v56, v53, v57
	v_pk_mul_f32 v[50:51], v[50:51], v[52:53] op_sel_hi:[1,0]
	v_max_f32_e32 v52, 0xc1a00000, v40
	v_max_f32_e32 v57, 0xc1a00000, v42
	v_mul_f32_e32 v52, 0xbfb8aa3b, v52
	v_mul_f32_e32 v57, 0xbfb8aa3b, v57
	v_exp_f32_e32 v53, v52
	v_exp_f32_e32 v59, v57
	v_max_f32_e32 v52, 0xc1a00000, v41
	v_max_f32_e32 v57, 0xc1a00000, v43
	v_mul_f32_e32 v52, 0xbfb8aa3b, v52
	v_mul_f32_e32 v57, 0xbfb8aa3b, v57
	v_exp_f32_e32 v52, v52
	v_exp_f32_e32 v58, v57
	v_pk_mul_f32 v[48:49], v[48:49], v[56:57] op_sel_hi:[1,0]
	v_pk_mul_f32 v[46:47], v[46:47], v[50:51]
	v_pk_mul_f32 v[44:45], v[44:45], v[48:49]
	v_pk_add_f32 v[48:49], v[52:53], 1.0 op_sel_hi:[1,0]
	v_pk_add_f32 v[52:53], v[58:59], 1.0 op_sel_hi:[1,0]
	v_mov_b32_e32 v56, v49
	v_mov_b32_e32 v57, v53
	v_mov_b32_e32 v58, v48
	v_mov_b32_e32 v59, v52
	v_pk_mul_f32 v[56:57], v[56:57], v[58:59]
	v_pk_mul_f32 v[38:39], v[46:47], v[38:39]
	v_mul_f32_e32 v58, v56, v57
	v_rcp_f32_e32 v58, v58
	v_pk_mul_f32 v[36:37], v[44:45], v[36:37]
	v_mul_f32_e32 v44, v57, v58
	v_mul_f32_e32 v46, v56, v58
	v_pk_mul_f32 v[46:47], v[52:53], v[46:47] op_sel_hi:[1,0]
	v_pk_mul_f32 v[44:45], v[48:49], v[44:45] op_sel_hi:[1,0]
	v_pk_mul_f32 v[42:43], v[42:43], v[46:47]
	v_pk_mul_f32 v[40:41], v[40:41], v[44:45]
	v_pk_mul_f32 v[42:43], v[42:43], v[34:35]
	v_pk_mul_f32 v[34:35], v[40:41], v[32:33]
	v_cvt_pk_bf16_f32 v32, v36, v37
	v_cvt_pk_bf16_f32 v33, v38, v39
	v_max_f32_e32 v36, 0xc1a00000, v28
	v_max_f32_e32 v38, 0xc1a00000, v30
	v_mul_f32_e32 v36, 0xbfb8aa3b, v36
	v_mul_f32_e32 v38, 0xbfb8aa3b, v38
	v_exp_f32_e32 v37, v36
	v_exp_f32_e32 v39, v38
	v_max_f32_e32 v36, 0xc1a00000, v29
	v_max_f32_e32 v38, 0xc1a00000, v31
	v_mul_f32_e32 v36, 0xbfb8aa3b, v36
	v_mul_f32_e32 v38, 0xbfb8aa3b, v38
	v_exp_f32_e32 v36, v36
	v_exp_f32_e32 v38, v38
	v_cvt_pk_bf16_f32 v34, v34, v35
	v_cvt_pk_bf16_f32 v35, v42, v43
	global_store_dwordx4 v[54:55], v[32:35], off
	v_add_u32_e32 v40, 0xa0, v154
	s_nop 0
	v_pk_add_f32 v[32:33], v[36:37], 1.0 op_sel_hi:[1,0]
	v_pk_add_f32 v[34:35], v[38:39], 1.0 op_sel_hi:[1,0]
	v_mul_f32_e32 v36, v33, v32
	v_mul_f32_e32 v37, v35, v34
	s_nop 0
	v_mul_f32_e32 v38, v36, v37
; __device__ __forceinline__ unsigned cvt_pk_bf16(float lo, float hi) { unsigned r; asm volatile("v_cvt_pk_bf16_f32 %0, %1, %2" : "=v"(r) : "v"(lo), "v"(hi)); return r; }
; __device__ __forceinline__ f32x4 sigmoid4(f32x4 x) {
;     f32x4 d;
; #pragma unroll
;     for (int j = 0; j < 4; ++j) d[j] = 1.0f + __expf(-fmaxf(x[j], -20.0f));
;     const float p01 = d[0] * d[1], p23 = d[2] * d[3], r = __builtin_amdgcn_rcpf(p01 * p23), r01 = r * p23, r23 = r * p01;
;     return (f32x4){r01 * d[1], r01 * d[0], r23 * d[3], r23 * d[2]};
; }
;     __device__ __forceinline__ void operator()(const f32x4 (&acc)[2][2][4][2], const Unit& u, int wr, int wc, int fr, int fq) const {
;         const int row0 = u.pm * BM + wr * 64 + fr, col0 = u.pn * HALF + wc * 32 + 8 * fq;
; #pragma unroll
;         for (int ai = 0; ai < 2; ++ai)
; #pragma unroll
;             for (int m = 0; m < 4; ++m) { bf16_t* rowp = O + (size_t)(row0 + ai * HALF + m * 16) * ldc + col0;
;                 f32x4 v0, v1;
; #pragma unroll
;                 for (int j = 0; j < 1; ++j) { v0 = acc[ai][0][m][0] * sigmoid4(acc[ai][0][m][0]) * acc[ai][1][m][0]; v1 = acc[ai][0][m][1] * sigmoid4(acc[ai][0][m][1]) * acc[ai][1][m][1]; }
;                 u32x4 w; w.x = cvt_pk_bf16(v0[0], v0[1]); w.y = cvt_pk_bf16(v0[2], v0[3]); w.z = cvt_pk_bf16(v1[0], v1[1]); w.w = cvt_pk_bf16(v1[2], v1[3]);
;                 *(u32x4*)rowp = w; }
	v_rcp_f32_e32 v41, v38
	v_mad_i64_i32 v[38:39], s[16:17], v40, s40, v[144:145]
	v_lshl_add_u64 v[38:39], v[38:39], 0, v[146:147]
	v_mul_f32_e32 v36, v36, v41
	v_mul_f32_e32 v40, v37, v41
	v_pk_mul_f32 v[34:35], v[34:35], v[36:37] op_sel_hi:[1,0]
	v_max_f32_e32 v36, 0xc1a00000, v24
	v_max_f32_e32 v41, 0xc1a00000, v26
	v_mul_f32_e32 v36, 0xbfb8aa3b, v36
	v_mul_f32_e32 v41, 0xbfb8aa3b, v41
	v_exp_f32_e32 v37, v36
	v_exp_f32_e32 v43, v41
	v_max_f32_e32 v36, 0xc1a00000, v25
	v_max_f32_e32 v41, 0xc1a00000, v27
	v_mul_f32_e32 v36, 0xbfb8aa3b, v36
	v_mul_f32_e32 v41, 0xbfb8aa3b, v41
	v_exp_f32_e32 v36, v36
	v_exp_f32_e32 v42, v41
	v_pk_mul_f32 v[32:33], v[32:33], v[40:41] op_sel_hi:[1,0]
	v_pk_mul_f32 v[30:31], v[30:31], v[34:35]
	v_pk_mul_f32 v[28:29], v[28:29], v[32:33]
	v_pk_add_f32 v[32:33], v[36:37], 1.0 op_sel_hi:[1,0]
	v_pk_add_f32 v[36:37], v[42:43], 1.0 op_sel_hi:[1,0]
	v_mov_b32_e32 v40, v33
	v_mov_b32_e32 v41, v37
	v_mov_b32_e32 v42, v32
	v_mov_b32_e32 v43, v36
	v_pk_mul_f32 v[40:41], v[40:41], v[42:43]
	v_pk_mul_f32 v[22:23], v[30:31], v[22:23]
	v_mul_f32_e32 v42, v40, v41
	v_rcp_f32_e32 v42, v42
	v_pk_mul_f32 v[20:21], v[28:29], v[20:21]
	v_mul_f32_e32 v28, v41, v42
	v_mul_f32_e32 v30, v40, v42
	v_pk_mul_f32 v[30:31], v[36:37], v[30:31] op_sel_hi:[1,0]
	v_pk_mul_f32 v[28:29], v[32:33], v[28:29] op_sel_hi:[1,0]
	v_pk_mul_f32 v[26:27], v[26:27], v[30:31]
	v_pk_mul_f32 v[24:25], v[24:25], v[28:29]
	v_pk_mul_f32 v[26:27], v[26:27], v[18:19]
	v_pk_mul_f32 v[18:19], v[24:25], v[16:17]
	v_cvt_pk_bf16_f32 v16, v20, v21
	v_cvt_pk_bf16_f32 v17, v22, v23
	v_max_f32_e32 v20, 0xc1a00000, v12
	v_max_f32_e32 v22, 0xc1a00000, v14
	v_mul_f32_e32 v20, 0xbfb8aa3b, v20
	v_mul_f32_e32 v22, 0xbfb8aa3b, v22
	v_exp_f32_e32 v21, v20
	v_exp_f32_e32 v23, v22
	v_max_f32_e32 v20, 0xc1a00000, v13
	v_max_f32_e32 v22, 0xc1a00000, v15
	v_mul_f32_e32 v20, 0xbfb8aa3b, v20
	v_mul_f32_e32 v22, 0xbfb8aa3b, v22
	v_exp_f32_e32 v20, v20
	v_exp_f32_e32 v22, v22
	v_cvt_pk_bf16_f32 v18, v18, v19
	v_cvt_pk_bf16_f32 v19, v26, v27
	global_store_dwordx4 v[38:39], v[16:19], off
	v_add_u32_e32 v24, 0xb0, v154
	s_nop 0
	v_pk_add_f32 v[16:17], v[20:21], 1.0 op_sel_hi:[1,0]
	v_pk_add_f32 v[18:19], v[22:23], 1.0 op_sel_hi:[1,0]
	v_mul_f32_e32 v20, v17, v16
	v_mul_f32_e32 v21, v19, v18
	s_nop 0
	v_mul_f32_e32 v22, v20, v21
	v_rcp_f32_e32 v25, v22
	v_mad_i64_i32 v[22:23], s[16:17], v24, s40, v[144:145]
	v_lshl_add_u64 v[22:23], v[22:23], 0, v[146:147]
	v_mul_f32_e32 v20, v20, v25
	v_mul_f32_e32 v24, v21, v25
	v_pk_mul_f32 v[18:19], v[18:19], v[20:21] op_sel_hi:[1,0]
	v_max_f32_e32 v20, 0xc1a00000, v8
	v_max_f32_e32 v25, 0xc1a00000, v10
	v_mul_f32_e32 v20, 0xbfb8aa3b, v20
	v_mul_f32_e32 v25, 0xbfb8aa3b, v25
	v_exp_f32_e32 v21, v20
	v_exp_f32_e32 v27, v25
	v_max_f32_e32 v20, 0xc1a00000, v9
	v_max_f32_e32 v25, 0xc1a00000, v11
	v_mul_f32_e32 v20, 0xbfb8aa3b, v20
	v_mul_f32_e32 v25, 0xbfb8aa3b, v25
	v_exp_f32_e32 v20, v20
	v_exp_f32_e32 v26, v25
	v_pk_mul_f32 v[16:17], v[16:17], v[24:25] op_sel_hi:[1,0]
	v_pk_mul_f32 v[14:15], v[14:15], v[18:19]
	v_pk_mul_f32 v[12:13], v[12:13], v[16:17]
	v_pk_add_f32 v[16:17], v[20:21], 1.0 op_sel_hi:[1,0]
	v_pk_add_f32 v[20:21], v[26:27], 1.0 op_sel_hi:[1,0]
	v_mov_b32_e32 v24, v17
	v_mov_b32_e32 v25, v21
	v_mov_b32_e32 v26, v16
	v_mov_b32_e32 v27, v20
	v_pk_mul_f32 v[24:25], v[24:25], v[26:27]
	v_pk_mul_f32 v[6:7], v[14:15], v[6:7]
	v_mul_f32_e32 v26, v24, v25
	v_rcp_f32_e32 v26, v26
	v_pk_mul_f32 v[4:5], v[12:13], v[4:5]
	s_mov_b64 s[16:17], s[10:11]
	v_mul_f32_e32 v12, v25, v26
	v_mul_f32_e32 v14, v24, v26
	v_pk_mul_f32 v[14:15], v[20:21], v[14:15] op_sel_hi:[1,0]
	v_pk_mul_f32 v[12:13], v[16:17], v[12:13] op_sel_hi:[1,0]
	v_pk_mul_f32 v[10:11], v[10:11], v[14:15]
	v_pk_mul_f32 v[8:9], v[8:9], v[12:13]
	v_pk_mul_f32 v[10:11], v[10:11], v[2:3]
	v_pk_mul_f32 v[2:3], v[8:9], v[0:1]
	v_cvt_pk_bf16_f32 v0, v4, v5
	v_cvt_pk_bf16_f32 v1, v6, v7
	s_nop 0
	v_cvt_pk_bf16_f32 v2, v2, v3
	v_cvt_pk_bf16_f32 v3, v10, v11
	global_store_dwordx4 v[22:23], v[0:3], off
	s_cbranch_vccz .LBB0_1199
	s_waitcnt vmcnt(0)
	s_cmpk_gt_u32 s23, 0xff
	s_cbranch_scc1 .LBB0_1206
	s_barrier
